# baseline (speedup 1.0000x reference)
.LBB0_122:
	s_or_b64 exec, exec, s[90:91]
	v_lshrrev_b32_e32 v8, 6, v8
	v_and_b32_e32 v13, 63, v18
	v_cmp_eq_u32_e32 vcc, 0, v9
	v_lshl_add_u64 v[10:11], v[0:1], 1, v[10:11]
	v_and_b32_e32 v0, v20, v7
	v_cndmask_b32_e32 v8, v13, v8, vcc
	v_lshlrev_b32_e32 v0, 1, v0
	v_lshlrev_b32_e32 v8, v19, v8
	v_lshl_add_u64 v[36:37], v[10:11], 0, v[0:1]
	v_lshl_add_u64 v[10:11], s[22:23], 0, v[14:15]
	v_add_lshl_u32 v0, v8, v0, 2
	v_lshl_add_u64 v[18:19], v[10:11], 0, v[0:1]
	v_lshlrev_b32_e32 v0, 1, v12
	global_load_dwordx4 v[20:23], v[36:37], off
	global_load_dwordx4 v[8:11], v[18:19], off
	global_load_dwordx4 v[14:17], v[18:19], off offset:16
	global_load_dwordx4 v[24:27], v[18:19], off offset:32
	global_load_dwordx4 v[28:31], v[18:19], off offset:48
	v_lshl_add_u64 v[18:19], v[36:37], 0, v[0:1]
	global_load_dwordx4 v[32:35], v[18:19], off
	v_add_u32_e32 v6, s86, v6
	s_mov_b32 s2, 0xcffff
	v_cmp_lt_i32_e32 vcc, s2, v6
	s_or_b64 s[74:75], vcc, s[74:75]
	v_add_u32_e32 v7, s54, v7
	s_waitcnt vmcnt(4)
	v_mov_b32_e32 v64, v9
	v_mov_b32_e32 v65, v10
	v_and_b32_e32 v13, 0xffff0000, v20
	v_lshlrev_b32_e32 v41, 16, v20
	v_and_b32_e32 v43, 16, v20
	s_waitcnt vmcnt(0)
	v_and_b32_e32 v42, 0xffff0000, v32
	v_lshlrev_b32_e32 v44, 16, v33
	v_and_b32_e32 v20, 0xffff0000, v33
	v_and_b32_e32 v45, 0xffff0000, v21
	v_lshlrev_b32_e32 v47, 16, v21
	v_and_b32_e32 v21, 16, v21
	v_mov_b32_e32 v58, v41
	v_mov_b32_e32 v66, v15
	v_mov_b32_e32 v67, v16
	v_mov_b32_e32 v73, v10
	v_mov_b32_e32 v10, v9
	v_mov_b32_e32 v9, v11
	v_mov_b32_e32 v75, v16
	v_mov_b32_e32 v16, v15
	v_mov_b32_e32 v15, v17
	v_lshlrev_b32_e32 v12, 16, v32
	v_pk_mov_b32 v[32:33], v[40:41], v[42:43] op_sel:[1,0]
	v_mov_b32_e32 v41, v42
	v_mov_b32_e32 v42, v44
	v_mov_b32_e32 v43, v20
	v_mov_b32_e32 v59, v13
	v_mov_b32_e32 v60, v47
	v_mov_b32_e32 v61, v45
	v_mov_b32_e32 v72, v8
	v_mov_b32_e32 v74, v14
	v_mov_b32_e32 v40, v12
	v_pk_mul_f32 v[8:9], v[8:9], v[12:13]
	v_pk_mov_b32 v[12:13], v[46:47], v[20:21] op_sel:[1,0]
	v_pk_mul_f32 v[14:15], v[14:15], v[44:45]
	v_pk_mul_f32 v[16:17], v[16:17], v[42:43]
	v_and_b32_e32 v49, 0xffff0000, v22
	v_lshlrev_b32_e32 v51, 16, v22
	v_and_b32_e32 v53, 16, v22
	v_mov_b32_e32 v68, v25
	v_mov_b32_e32 v69, v26
	v_mov_b32_e32 v77, v26
	v_mov_b32_e32 v26, v25
	v_mov_b32_e32 v25, v27
	v_lshlrev_b32_e32 v48, 16, v34
	v_and_b32_e32 v52, 0xffff0000, v34
	v_pk_fma_f32 v[8:9], v[64:65], v[32:33], v[8:9]
	v_pk_fma_f32 v[12:13], v[66:67], v[12:13], v[14:15]
	v_pk_fma_f32 v[16:17], v[74:75], v[60:61], v[16:17] neg_lo:[0,0,1] neg_hi:[0,0,1]
	v_mov_b32_e32 v76, v24
	v_lshlrev_b32_e32 v54, 16, v35
	v_pk_mov_b32 v[20:21], v[50:51], v[52:53] op_sel:[1,0]
	v_mov_b32_e32 v44, v48
	v_mov_b32_e32 v45, v52
	v_pk_mul_f32 v[24:25], v[24:25], v[48:49]
	v_pk_mul_f32 v[10:11], v[10:11], v[40:41]
	v_cvt_pk_bf16_f32 v8, v8, v9
	v_cvt_pk_bf16_f32 v9, v12, v13
	v_cvt_pk_bf16_f32 v13, v16, v17
	v_and_b32_e32 v16, 0xffff0000, v35
	v_and_b32_e32 v55, 0xffff0000, v23
	v_lshlrev_b32_e32 v57, 16, v23
	v_mov_b32_e32 v71, v30
	v_pk_mul_f32 v[14:15], v[26:27], v[44:45]
	v_pk_fma_f32 v[20:21], v[68:69], v[20:21], v[24:25]
	v_pk_fma_f32 v[24:25], v[72:73], v[58:59], v[10:11] neg_lo:[0,0,1] neg_hi:[0,0,1]
	v_and_b32_e32 v17, 16, v23
	v_mov_b32_e32 v23, v30
	v_mov_b32_e32 v30, v29
	v_mov_b32_e32 v26, v54
	v_mov_b32_e32 v27, v16
	v_mov_b32_e32 v62, v51
	v_mov_b32_e32 v63, v49
	v_cvt_pk_bf16_f32 v10, v20, v21
	v_cvt_pk_bf16_f32 v12, v24, v25
	v_pk_mov_b32 v[20:21], v[56:57], v[16:17] op_sel:[1,0]
	v_mov_b32_e32 v22, v28
	v_mov_b32_e32 v24, v57
	v_mov_b32_e32 v25, v55
	v_pk_mul_f32 v[16:17], v[30:31], v[26:27]
	v_mov_b32_e32 v70, v29
	v_pk_fma_f32 v[14:15], v[76:77], v[62:63], v[14:15] neg_lo:[0,0,1] neg_hi:[0,0,1]
	v_pk_fma_f32 v[16:17], v[22:23], v[24:25], v[16:17] neg_lo:[0,0,1] neg_hi:[0,0,1]
	v_mov_b32_e32 v29, v31
	v_cvt_pk_bf16_f32 v14, v14, v15
	v_cvt_pk_bf16_f32 v15, v16, v17
	v_pk_mul_f32 v[16:17], v[28:29], v[54:55]
	s_nop 0
	v_pk_fma_f32 v[16:17], v[70:71], v[20:21], v[16:17]
	s_nop 0
	v_cvt_pk_bf16_f32 v11, v16, v17
	global_store_dwordx4 v[36:37], v[12:15], off sc1
	global_store_dwordx4 v[18:19], v[8:11], off sc1
	s_andn2_b64 exec, exec, s[74:75]
	s_cbranch_execz .LBB0_215

.LBB0_134:
	v_add_f32_e32 v47, 0, v124
	v_add_f32_e32 v47, v125, v47
	v_add_f32_e32 v47, v126, v47
	v_add_f32_e32 v47, v127, v47
	v_add_f32_e32 v47, v128, v47
	v_add_f32_e32 v47, v129, v47
	v_cmp_gt_u32_e32 vcc, 16, v121
	v_add_f32_e32 v47, v130, v47
	v_add_f32_e32 v47, v132, v47
	v_cndmask_b32_e64 v46, 0, 1.0, vcc
	v_fmac_f32_e32 v47, v46, v131
	v_add_f32_e32 v46, 0, v138
	v_add_f32_e32 v46, v139, v46
	v_add_f32_e32 v46, v154, v46
	v_add_f32_e32 v46, v155, v46
	v_add_f32_e32 v46, v156, v46
	v_add_f32_e32 v46, v157, v46
	v_add_f32_e32 v46, v158, v46
	v_add_f32_e32 v46, v159, v46
	v_fmac_f32_e32 v46, v47, v0
	v_add_f32_e32 v0, 0, v169
	v_add_f32_e32 v0, v170, v0
	v_add_f32_e32 v0, v171, v0
	v_add_f32_e32 v0, v172, v0
	v_add_f32_e32 v0, v173, v0
	v_add_f32_e32 v0, v178, v0
	v_add_f32_e32 v0, v179, v0
	v_add_f32_e32 v0, v180, v0
	v_fmac_f32_e32 v0, v46, v110
	v_add_f32_e32 v46, 0, v189
	v_add_f32_e32 v46, v192, v46
	v_add_f32_e32 v46, v193, v46
	v_add_f32_e32 v46, v194, v46
	v_add_f32_e32 v46, v195, v46
	v_add_f32_e32 v46, v196, v46
	v_add_f32_e32 v46, v198, v46
	v_add_f32_e32 v46, v199, v46
	v_fmac_f32_e32 v46, v0, v116
	v_add_f32_e32 v0, 0, v113
	v_add_f32_e32 v0, v115, v0
	v_add_f32_e32 v0, v200, v0
	v_add_f32_e32 v0, v201, v0
	v_add_f32_e32 v0, v202, v0
	v_add_f32_e32 v0, v203, v0
	v_add_f32_e32 v0, v204, v0
	v_add_f32_e32 v0, v205, v0
	v_fmac_f32_e32 v0, v46, v112
	v_add_f32_e32 v46, 0, v181
	v_add_f32_e32 v46, v182, v46
	v_add_f32_e32 v46, v183, v46
	v_add_f32_e32 v46, v184, v46
	v_add_f32_e32 v46, v185, v46
	v_add_f32_e32 v46, v186, v46
	v_add_f32_e32 v46, v187, v46
	v_add_f32_e32 v50, v188, v46
	v_fmac_f32_e32 v50, v0, v114
	v_add_f32_e32 v0, 0, v96
	v_add_f32_e32 v0, v97, v0
	v_add_f32_e32 v0, v98, v0
	v_sub_f32_e32 v46, v86, v78
	v_add_f32_e32 v0, v91, v0
	v_exp_f32_e32 v51, v46
	v_sub_f32_e32 v46, v85, v78
	v_add_f32_e32 v0, v92, v0
	v_exp_f32_e32 v52, v46
	v_sub_f32_e32 v46, v84, v78
	v_add_f32_e32 v0, v93, v0
	v_exp_f32_e32 v53, v46
	v_sub_f32_e32 v46, v83, v78
	v_add_f32_e32 v0, v94, v0
	v_exp_f32_e32 v79, v46
	v_sub_f32_e32 v46, v82, v78
	v_add_f32_e32 v0, v95, v0
	v_exp_f32_e32 v80, v46
	v_sub_f32_e32 v46, v77, v78
	v_fmac_f32_e32 v0, v50, v90
	v_add_f32_e32 v50, 0, v51
	v_exp_f32_e32 v77, v46
	v_sub_f32_e32 v46, v76, v78
	v_add_f32_e32 v50, v52, v50
	v_exp_f32_e32 v76, v46
	v_sub_f32_e32 v46, v75, v78
	v_add_f32_e32 v50, v53, v50
	v_exp_f32_e32 v75, v46
	v_add_f32_e32 v50, v79, v50
	v_add_f32_e32 v50, v80, v50
	v_add_f32_e32 v50, v77, v50
	v_add_f32_e32 v50, v76, v50
	v_add_f32_e32 v50, v75, v50
	v_fmac_f32_e32 v50, v0, v74
	ds_bpermute_b32 v0, v119, v50
	v_cvt_pk_bf16_f32 v46, v51, v52
	v_cvt_pk_bf16_f32 v47, v53, v79
	v_cvt_pk_bf16_f32 v48, v80, v77
	v_cvt_pk_bf16_f32 v49, v76, v75
	s_waitcnt lgkmcnt(0)
	v_add_f32_e32 v0, v50, v0
	s_lshl_b32 s2, s2, 7
	v_mfma_f32_16x16x32_bf16 v[42:45], v[42:45], v[46:49], v[6:9]
	s_lshl_b32 s60, s2, 1
	s_barrier
	s_nop 0
	ds_bpermute_b32 v8, v120, v0
	v_mfma_f32_16x16x32_bf16 v[30:33], v[30:33], v[46:49], v[34:37]
	v_mov_b64_e32 v[6:7], s[48:49]
	v_mad_i64_i32 v[6:7], s[8:9], v152, s1, v[6:7]
	s_waitcnt lgkmcnt(0)
	v_add_f32_e32 v0, v0, v8
	v_div_scale_f32 v8, s[8:9], v0, v0, 1.0
	v_rcp_f32_e32 v34, v8
	v_lshl_add_u64 v[6:7], v[6:7], 0, s[60:61]
	v_mfma_f32_16x16x32_bf16 v[22:25], v[70:73], v[46:49], v[22:25]
	v_lshlrev_b32_e32 v9, 2, v118
	v_fma_f32 v35, -v8, v34, 1.0
	v_fmac_f32_e32 v34, v35, v34
	v_div_scale_f32 v35, vcc, 1.0, v0, 1.0
	v_mul_f32_e32 v36, v35, v34
	v_fma_f32 v37, -v8, v36, v35
	v_fmac_f32_e32 v36, v37, v34
	v_fma_f32 v8, -v8, v36, v35
	v_div_fmas_f32 v8, v8, v34, v36
	v_div_fixup_f32 v36, v8, v0, 1.0
	v_mul_u32_u24_e32 v0, 0xc00, v117
	v_lshlrev_b32_e32 v0, 1, v0
	v_lshl_add_u64 v[6:7], v[6:7], 0, v[0:1]
	v_and_b32_e32 v0, 16, v111
	v_add_u32_e32 v8, 12, v9
	v_cmp_eq_u32_e32 vcc, 0, v0
	v_mfma_f32_16x16x32_bf16 v[18:21], v[62:65], v[46:49], v[18:21]
	s_mov_b64 s[8:9], 0x800
	v_cndmask_b32_e32 v0, v8, v9, vcc
	v_lshlrev_b32_e32 v0, 1, v0
	v_mfma_f32_16x16x32_bf16 v[26:29], v[66:69], v[46:49], v[26:29]
	v_lshl_add_u64 v[34:35], v[6:7], 0, v[0:1]
	v_mul_f32_e32 v0, v22, v36
	v_mul_f32_e32 v8, v23, v36
	v_cvt_pk_bf16_f32 v22, v0, v8
	v_mul_f32_e32 v0, v24, v36
	v_mul_f32_e32 v8, v25, v36
	v_mfma_f32_16x16x32_bf16 v[14:17], v[58:61], v[46:49], v[14:17]
	v_cvt_pk_bf16_f32 v23, v0, v8
	v_mul_f32_e32 v0, v18, v36
	v_mul_f32_e32 v8, v19, v36
	v_cvt_pk_bf16_f32 v24, v0, v8
	v_mul_f32_e32 v0, v20, v36
	v_mul_f32_e32 v8, v21, v36
	v_mfma_f32_16x16x32_bf16 v[10:13], v[54:57], v[46:49], v[10:13]
	v_cvt_pk_bf16_f32 v25, v0, v8
	v_mul_f32_e32 v0, v26, v36
	v_mul_f32_e32 v8, v27, v36
	v_cvt_pk_bf16_f32 v18, v0, v8
	v_mul_f32_e32 v0, v28, v36
	v_mul_f32_e32 v8, v29, v36
	v_cvt_pk_bf16_f32 v19, v0, v8
	v_mul_f32_e32 v0, v14, v36
	v_mul_f32_e32 v8, v15, v36
	v_cvt_pk_bf16_f32 v20, v0, v8
	v_mul_f32_e32 v0, v16, v36
	v_mul_f32_e32 v8, v17, v36
	v_mfma_f32_16x16x32_bf16 v[2:5], v[38:41], v[46:49], v[2:5]
	v_cvt_pk_bf16_f32 v21, v0, v8
	v_mul_f32_e32 v0, v10, v36
	v_mul_f32_e32 v8, v11, v36
	v_cvt_pk_bf16_f32 v8, v0, v8
	v_mul_f32_e32 v0, v12, v36
	v_mul_f32_e32 v9, v13, v36
	v_cvt_pk_bf16_f32 v9, v0, v9
	v_mul_f32_e32 v0, v42, v36
	v_mul_f32_e32 v10, v43, v36
	v_cvt_pk_bf16_f32 v10, v0, v10
	v_mul_f32_e32 v0, v44, v36
	v_mul_f32_e32 v11, v45, v36
	v_cvt_pk_bf16_f32 v11, v0, v11
	v_mul_f32_e32 v0, v2, v36
	v_mul_f32_e32 v2, v3, v36
	v_cvt_pk_bf16_f32 v2, v0, v2
	v_mul_f32_e32 v0, v4, v36
	v_mul_f32_e32 v3, v5, v36
	v_cvt_pk_bf16_f32 v3, v0, v3
	v_mul_f32_e32 v0, v30, v36
	v_mul_f32_e32 v4, v31, v36
	v_cvt_pk_bf16_f32 v4, v0, v4
	v_mul_f32_e32 v0, v32, v36
	v_mul_f32_e32 v5, v33, v36
	v_cvt_pk_bf16_f32 v5, v0, v5
	v_lshl_add_u64 v[6:7], v[34:35], 0, s[8:9]
	v_permlane16_swap_b32_e32 v22, v24
	v_permlane16_swap_b32_e32 v23, v25
	v_permlane16_swap_b32_e32 v18, v20
	v_permlane16_swap_b32_e32 v19, v21
	v_permlane16_swap_b32_e32 v8, v10
	v_permlane16_swap_b32_e32 v9, v11
	v_permlane16_swap_b32_e32 v2, v4
	v_permlane16_swap_b32_e32 v3, v5
	global_store_dwordx4 v[34:35], v[22:25], off offset:2048 sc1
	global_store_dwordx4 v[34:35], v[18:21], off offset:2112 sc1
	global_store_dwordx4 v[34:35], v[8:11], off offset:2176 sc1
.LBB0_135:
	v_readlane_b32 s2, v255, 34
	s_add_i32 s95, s95, s3
	s_add_i32 s94, s94, s2
	s_add_i32 s19, s19, s3
	s_cmpk_gt_i32 s95, 0x3ff
	global_store_dwordx4 v[6:7], v[2:5], off offset:192 sc1
	s_cbranch_scc1 .LBB0_211

.LBB0_156:
	v_sub_f32_e32 v63, v63, v64
	v_sub_f32_e32 v62, v62, v64
	v_sub_f32_e32 v61, v61, v64
	v_sub_f32_e32 v60, v60, v64
	v_sub_f32_e32 v59, v59, v64
	v_sub_f32_e32 v58, v58, v64
	v_sub_f32_e32 v57, v57, v64
	v_sub_f32_e32 v0, v0, v64
	v_exp_f32_e32 v173, v63
	v_exp_f32_e32 v165, v62
	v_exp_f32_e32 v169, v61
	v_exp_f32_e32 v163, v60
	v_exp_f32_e32 v167, v59
	v_exp_f32_e32 v171, v58
	v_exp_f32_e32 v67, v57
	v_exp_f32_e32 v57, v0
	v_cvt_pk_bf16_f32 v58, v173, v165
	v_cvt_pk_bf16_f32 v59, v169, v163
	v_cvt_pk_bf16_f32 v60, v167, v171
	v_cvt_pk_bf16_f32 v61, v67, v57
	v_add_f32_e32 v0, 0, v187
	s_lshl_b32 s60, s30, 1
	v_mfma_f32_16x16x32_bf16 v[62:65], v[96:99], v[58:61], v[20:23]
	v_add_f32_e32 v0, v188, v0
	v_mul_f32_e32 v132, v183, v132
	v_mul_f32_e32 v66, v184, v160
	v_mov_b64_e32 v[20:21], s[48:49]
	v_mad_i64_i32 v[20:21], s[58:59], v152, s1, v[20:21]
	v_lshl_add_u64 v[72:73], v[20:21], 0, s[60:61]
	v_mfma_f32_16x16x32_bf16 v[20:23], v[116:119], v[58:61], v[36:39]
	s_barrier
	s_nop 1
	v_pk_add_f32 v[36:37], v[172:173], v[0:1]
	v_add_f32_e32 v0, 0, v185
	v_add_f32_e32 v0, v186, v0
	v_pk_add_f32 v[38:39], v[158:159], v[0:1]
	v_mfma_f32_16x16x32_bf16 v[40:43], v[88:91], v[58:61], v[40:43]
	v_add_f32_e64 v38, v156, v38
	v_add_f32_e64 v39, v157, v39
	v_pk_add_f32 v[38:39], v[154:155], v[38:39]
	v_mfma_f32_16x16x32_bf16 v[44:47], v[92:95], v[58:61], v[44:47]
	v_add_f32_e64 v38, v138, v38
	v_add_f32_e64 v39, v139, v39
	v_pk_add_f32 v[38:39], v[136:137], v[38:39]
	v_mfma_f32_16x16x32_bf16 v[32:35], v[84:87], v[58:61], v[32:35]
	v_add_f32_e64 v38, v134, v38
	v_add_f32_e64 v39, v135, v39
	v_pk_add_f32 v[38:39], v[132:133], v[38:39]
	v_mfma_f32_16x16x32_bf16 v[28:31], v[112:115], v[58:61], v[28:31]
	v_add_f32_e32 v0, v39, v19
	v_fmac_f32_e32 v0, v38, v18
	ds_bpermute_b32 v38, v179, v0
	v_pk_add_f32 v[18:19], v[164:165], v[36:37]
	v_mfma_f32_16x16x32_bf16 v[24:27], v[108:111], v[58:61], v[24:27]
	v_add_f32_e64 v18, v168, v18
	v_add_f32_e64 v19, v169, v19
	s_waitcnt lgkmcnt(0)
	v_add_f32_e32 v0, v0, v38
	v_pk_add_f32 v[18:19], v[162:163], v[18:19]
	ds_bpermute_b32 v36, v178, v0
	v_pk_add_f32 v[18:19], v[166:167], v[18:19]
	v_mfma_f32_16x16x32_bf16 v[48:51], v[120:123], v[58:61], v[48:51]
	v_add_f32_e64 v18, v170, v18
	v_add_f32_e64 v19, v171, v19
	s_waitcnt lgkmcnt(0)
	v_add_f32_e32 v0, v0, v36
	v_pk_add_f32 v[18:19], v[66:67], v[18:19]
	v_div_scale_f32 v36, s[30:31], v0, v0, 1.0
	v_add_f32_e32 v19, v19, v57
	v_fmac_f32_e32 v19, v18, v56
	ds_bpermute_b32 v18, v179, v19
	v_rcp_f32_e32 v37, v36
	s_waitcnt lgkmcnt(0)
	v_add_f32_e32 v18, v19, v18
	ds_bpermute_b32 v19, v178, v18
	v_fma_f32 v38, -v36, v37, 1.0
	v_fmac_f32_e32 v37, v38, v37
	v_div_scale_f32 v38, vcc, 1.0, v0, 1.0
	v_mul_f32_e32 v39, v38, v37
	v_fma_f32 v56, -v36, v39, v38
	s_waitcnt lgkmcnt(0)
	v_add_f32_e32 v18, v18, v19
	v_fmac_f32_e32 v39, v56, v37
	v_div_scale_f32 v19, s[30:31], v18, v18, 1.0
	v_fma_f32 v36, -v36, v39, v38
	v_rcp_f32_e32 v38, v19
	v_div_fmas_f32 v36, v36, v37, v39
	v_div_fixup_f32 v56, v36, v0, 1.0
	s_mov_b64 s[30:31], 0x1000
	v_fma_f32 v0, -v19, v38, 1.0
	v_fmac_f32_e32 v38, v0, v38
	v_div_scale_f32 v0, vcc, 1.0, v18, 1.0
	v_mul_f32_e32 v36, v0, v38
	v_fma_f32 v37, -v19, v36, v0
	v_fmac_f32_e32 v36, v37, v38
	v_fma_f32 v0, -v19, v36, v0
	v_div_fmas_f32 v0, v0, v38, v36
	v_div_fixup_f32 v0, v0, v18, 1.0
	v_and_b32_e32 v18, 16, v180
	v_lshlrev_b32_e32 v19, 2, v182
	v_mul_u32_u24_e32 v36, 0xc00, v181
	v_add_u32_e32 v37, 12, v19
	v_cmp_eq_u32_e32 vcc, 0, v18
	v_mul_f32_e32 v58, v153, v0
	v_lshlrev_b32_e32 v0, 1, v36
	v_cndmask_b32_e32 v37, v37, v19, vcc
	v_pk_mul_f32 v[18:19], v[20:21], v[58:59] op_sel_hi:[1,0]
	v_pk_mul_f32 v[20:21], v[22:23], v[58:59] op_sel_hi:[1,0]
	v_lshl_add_u64 v[22:23], v[72:73], 0, v[0:1]
	v_lshlrev_b32_e32 v0, 1, v37
	v_lshl_add_u64 v[60:61], v[22:23], 0, v[0:1]
	v_lshlrev_b32_e32 v0, 4, v182
	v_lshl_add_u64 v[66:67], v[140:141], 0, v[0:1]
	v_pk_mul_f32 v[22:23], v[42:43], v[58:59] op_sel_hi:[1,0]
	v_pk_mul_f32 v[48:49], v[48:49], v[58:59] op_sel_hi:[1,0]
	v_pk_fma_f32 v[72:73], v[102:103], v[56:57], v[22:23] op_sel_hi:[1,0,1] neg_lo:[0,0,1] neg_hi:[0,0,1]
	v_pk_mul_f32 v[22:23], v[40:41], v[58:59] op_sel_hi:[1,0]
	global_load_dwordx4 v[36:39], v[66:67], off offset:64
	global_load_dwordx4 v[40:43], v[66:67], off
	v_pk_fma_f32 v[76:77], v[100:101], v[56:57], v[22:23] op_sel_hi:[1,0,1] neg_lo:[0,0,1] neg_hi:[0,0,1]
	v_pk_mul_f32 v[22:23], v[46:47], v[58:59] op_sel_hi:[1,0]
	v_pk_mul_f32 v[78:79], v[76:77], v[76:77]
	v_pk_fma_f32 v[82:83], v[82:83], v[56:57], v[22:23] op_sel_hi:[1,0,1] neg_lo:[0,0,1] neg_hi:[0,0,1]
	v_pk_mul_f32 v[22:23], v[44:45], v[58:59] op_sel_hi:[1,0]
	v_pk_mul_f32 v[84:85], v[82:83], v[82:83]
	v_pk_fma_f32 v[80:81], v[80:81], v[56:57], v[22:23] op_sel_hi:[1,0,1] neg_lo:[0,0,1] neg_hi:[0,0,1]
	v_pk_mul_f32 v[22:23], v[30:31], v[58:59] op_sel_hi:[1,0]
	v_pk_mul_f32 v[86:87], v[80:81], v[80:81]
	v_pk_fma_f32 v[70:71], v[70:71], v[56:57], v[22:23] op_sel_hi:[1,0,1] neg_lo:[0,0,1] neg_hi:[0,0,1]
	v_pk_mul_f32 v[22:23], v[28:29], v[58:59] op_sel_hi:[1,0]
	global_load_dwordx4 v[28:31], v[66:67], off offset:192
	global_load_dwordx4 v[44:47], v[66:67], off offset:128
	v_pk_fma_f32 v[68:69], v[68:69], v[56:57], v[22:23] op_sel_hi:[1,0,1] neg_lo:[0,0,1] neg_hi:[0,0,1]
	v_pk_mul_f32 v[22:23], v[34:35], v[58:59] op_sel_hi:[1,0]
	v_add_f32_e32 v0, v86, v87
	v_pk_fma_f32 v[16:17], v[16:17], v[56:57], v[22:23] op_sel_hi:[1,0,1] neg_lo:[0,0,1] neg_hi:[0,0,1]
	v_pk_mul_f32 v[22:23], v[32:33], v[58:59] op_sel_hi:[1,0]
	v_add_f32_e32 v0, v84, v0
	v_pk_fma_f32 v[92:93], v[14:15], v[56:57], v[22:23] op_sel_hi:[1,0,1] neg_lo:[0,0,1] neg_hi:[0,0,1]
	v_pk_mul_f32 v[14:15], v[64:65], v[58:59] op_sel_hi:[1,0]
	v_add_f32_e32 v0, v85, v0
	v_pk_fma_f32 v[64:65], v[12:13], v[56:57], v[14:15] op_sel_hi:[1,0,1] neg_lo:[0,0,1] neg_hi:[0,0,1]
	v_pk_mul_f32 v[12:13], v[62:63], v[58:59] op_sel_hi:[1,0]
	v_add_f32_e32 v0, v78, v0
	v_pk_fma_f32 v[62:63], v[10:11], v[56:57], v[12:13] op_sel_hi:[1,0,1] neg_lo:[0,0,1] neg_hi:[0,0,1]
	v_pk_mul_f32 v[10:11], v[26:27], v[58:59] op_sel_hi:[1,0]
	v_pk_mul_f32 v[74:75], v[72:73], v[72:73]
	v_pk_fma_f32 v[26:27], v[8:9], v[56:57], v[10:11] op_sel_hi:[1,0,1] neg_lo:[0,0,1] neg_hi:[0,0,1]
	global_load_dwordx4 v[8:11], v[66:67], off offset:320
	global_load_dwordx4 v[12:15], v[66:67], off offset:256
	v_add_f32_e32 v0, v79, v0
	v_add_f32_e32 v0, v74, v0
	v_pk_mul_f32 v[32:33], v[92:93], v[92:93]
	v_pk_mul_f32 v[22:23], v[24:25], v[58:59] op_sel_hi:[1,0]
	v_add_f32_e32 v0, v75, v0
	v_pk_fma_f32 v[100:101], v[6:7], v[56:57], v[22:23] op_sel_hi:[1,0,1] neg_lo:[0,0,1] neg_hi:[0,0,1]
	v_pk_mul_f32 v[22:23], v[50:51], v[58:59] op_sel_hi:[1,0]
	v_add_f32_e32 v0, v32, v0
	v_pk_mul_f32 v[34:35], v[16:17], v[16:17]
	v_pk_fma_f32 v[50:51], v[4:5], v[56:57], v[22:23] op_sel_hi:[1,0,1] neg_lo:[0,0,1] neg_hi:[0,0,1]
	global_load_dwordx4 v[22:25], v[66:67], off offset:384
	v_add_f32_e32 v0, v33, v0
	v_add_f32_e32 v0, v34, v0
	v_add_f32_e32 v0, v35, v0
	global_load_dwordx4 v[32:35], v[66:67], off offset:448
	v_pk_mul_f32 v[90:91], v[68:69], v[68:69]
	v_pk_mul_f32 v[88:89], v[70:71], v[70:71]
	v_add_f32_e32 v0, v90, v0
	v_add_f32_e32 v0, v91, v0
	v_add_f32_e32 v0, v88, v0
	v_pk_mul_f32 v[6:7], v[100:101], v[100:101]
	v_add_f32_e32 v0, v89, v0
	v_add_f32_e32 v0, v6, v0
	v_pk_mul_f32 v[98:99], v[26:27], v[26:27]
	v_add_f32_e32 v0, v7, v0
	v_add_f32_e32 v0, v98, v0
	v_pk_mul_f32 v[96:97], v[62:63], v[62:63]
	v_add_f32_e32 v0, v99, v0
	v_add_f32_e32 v0, v96, v0
	v_pk_mul_f32 v[94:95], v[64:65], v[64:65]
	v_add_f32_e32 v0, v97, v0
	v_pk_fma_f32 v[48:49], v[2:3], v[56:57], v[48:49] op_sel_hi:[1,0,1] neg_lo:[0,0,1] neg_hi:[0,0,1]
	v_add_f32_e32 v0, v94, v0
	v_pk_mul_f32 v[2:3], v[48:49], v[48:49]
	v_add_f32_e32 v0, v95, v0
	v_add_f32_e32 v0, v2, v0
	v_pk_mul_f32 v[4:5], v[50:51], v[50:51]
	v_add_f32_e32 v0, v3, v0
	v_pk_fma_f32 v[18:19], v[52:53], v[56:57], v[18:19] op_sel_hi:[1,0,1] neg_lo:[0,0,1] neg_hi:[0,0,1]
	v_add_f32_e32 v0, v4, v0
	v_pk_mul_f32 v[52:53], v[18:19], v[18:19]
	v_add_f32_e32 v0, v5, v0
	v_pk_fma_f32 v[20:21], v[54:55], v[56:57], v[20:21] op_sel_hi:[1,0,1] neg_lo:[0,0,1] neg_hi:[0,0,1]
	v_add_f32_e32 v0, v52, v0
	v_pk_mul_f32 v[54:55], v[20:21], v[20:21]
	v_add_f32_e32 v0, v53, v0
	v_add_f32_e32 v0, v54, v0
	v_add_f32_e32 v0, v55, v0
	ds_bpermute_b32 v2, v179, v0
	v_lshl_add_u64 v[6:7], v[60:61], 0, s[30:31]
	s_mov_b64 s[30:31], 0
	s_waitcnt lgkmcnt(0)
	v_add_f32_e32 v0, v0, v2
	ds_bpermute_b32 v2, v178, v0
	s_waitcnt lgkmcnt(0)
	v_add_f32_e32 v0, v0, v2
	v_fmamk_f32 v0, v0, 0x3c000000, v191
	v_mul_f32_e32 v2, 0x4b800000, v0
	v_cmp_gt_f32_e32 vcc, s0, v0
	s_nop 1
	v_cndmask_b32_e32 v0, v0, v2, vcc
	v_rsq_f32_e32 v0, v0
	s_nop 0
	v_mul_f32_e32 v2, 0x45800000, v0
	v_cndmask_b32_e32 v0, v0, v2, vcc
	v_mul_f32_e32 v0, v161, v0
	v_pk_mul_f32 v[2:3], v[80:81], v[0:1] op_sel_hi:[1,0]
	v_pk_mul_f32 v[4:5], v[82:83], v[0:1] op_sel_hi:[1,0]
	s_waitcnt vmcnt(6)
	v_pk_mul_f32 v[2:3], v[40:41], v[2:3]
	v_pk_mul_f32 v[4:5], v[42:43], v[4:5]
	v_cvt_pk_bf16_f32 v2, v2, v3
	v_cvt_pk_bf16_f32 v3, v4, v5
	v_pk_mul_f32 v[4:5], v[76:77], v[0:1] op_sel_hi:[1,0]
	s_nop 0
	v_pk_mul_f32 v[4:5], v[36:37], v[4:5]
	v_pk_mul_f32 v[36:37], v[72:73], v[0:1] op_sel_hi:[1,0]
	v_cvt_pk_bf16_f32 v4, v4, v5
	v_pk_mul_f32 v[36:37], v[38:39], v[36:37]
	s_nop 0
	v_permlane16_swap_b32_e32 v2, v4
	v_cvt_pk_bf16_f32 v5, v36, v37
	v_add_co_u32_e32 v36, vcc, s51, v60
	s_nop 0
	v_permlane16_swap_b32_e32 v3, v5
	v_addc_co_u32_e32 v37, vcc, 0, v61, vcc
	global_store_dwordx4 v[36:37], v[2:5], off sc1
	s_nop 1
	v_pk_mul_f32 v[2:3], v[92:93], v[0:1] op_sel_hi:[1,0]
	v_pk_mul_f32 v[4:5], v[16:17], v[0:1] op_sel_hi:[1,0]
	s_waitcnt vmcnt(5)
	v_pk_mul_f32 v[2:3], v[44:45], v[2:3]
	v_pk_mul_f32 v[4:5], v[46:47], v[4:5]
	v_cvt_pk_bf16_f32 v2, v2, v3
	v_cvt_pk_bf16_f32 v3, v4, v5
	v_pk_mul_f32 v[4:5], v[68:69], v[0:1] op_sel_hi:[1,0]
	v_pk_mul_f32 v[16:17], v[70:71], v[0:1] op_sel_hi:[1,0]
	v_pk_mul_f32 v[4:5], v[28:29], v[4:5]
	v_pk_mul_f32 v[16:17], v[30:31], v[16:17]
	v_cvt_pk_bf16_f32 v4, v4, v5
	v_cvt_pk_bf16_f32 v5, v16, v17
	s_nop 0
	v_permlane16_swap_b32_e32 v2, v4
	v_permlane16_swap_b32_e32 v3, v5
	global_store_dwordx4 v[6:7], v[2:5], off offset:64 sc1
	s_nop 1
	v_pk_mul_f32 v[2:3], v[100:101], v[0:1] op_sel_hi:[1,0]
	v_pk_mul_f32 v[4:5], v[26:27], v[0:1] op_sel_hi:[1,0]
	s_waitcnt vmcnt(4)
	v_pk_mul_f32 v[2:3], v[12:13], v[2:3]
	v_pk_mul_f32 v[4:5], v[14:15], v[4:5]
	v_cvt_pk_bf16_f32 v2, v2, v3
	v_cvt_pk_bf16_f32 v3, v4, v5
	v_pk_mul_f32 v[4:5], v[62:63], v[0:1] op_sel_hi:[1,0]
	s_nop 0
	v_pk_mul_f32 v[4:5], v[8:9], v[4:5]
	v_pk_mul_f32 v[8:9], v[64:65], v[0:1] op_sel_hi:[1,0]
	v_cvt_pk_bf16_f32 v4, v4, v5
	v_pk_mul_f32 v[8:9], v[10:11], v[8:9]
	s_nop 0
	v_permlane16_swap_b32_e32 v2, v4
	v_cvt_pk_bf16_f32 v5, v8, v9
	s_nop 1
	v_permlane16_swap_b32_e32 v3, v5
	global_store_dwordx4 v[6:7], v[2:5], off offset:128 sc1
	v_pk_mul_f32 v[8:9], v[20:21], v[0:1] op_sel_hi:[1,0]
	s_nop 0
	v_pk_mul_f32 v[2:3], v[48:49], v[0:1] op_sel_hi:[1,0]
	v_pk_mul_f32 v[4:5], v[50:51], v[0:1] op_sel_hi:[1,0]
	s_waitcnt vmcnt(4)
	v_pk_mul_f32 v[2:3], v[22:23], v[2:3]
	v_pk_mul_f32 v[4:5], v[24:25], v[4:5]
	v_cvt_pk_bf16_f32 v2, v2, v3
	v_cvt_pk_bf16_f32 v3, v4, v5
	v_pk_mul_f32 v[4:5], v[18:19], v[0:1] op_sel_hi:[1,0]
	s_waitcnt vmcnt(3)
	v_pk_mul_f32 v[8:9], v[8:9], v[34:35]
	v_pk_mul_f32 v[4:5], v[32:33], v[4:5]
	s_nop 0
	v_cvt_pk_bf16_f32 v4, v4, v5
	v_cvt_pk_bf16_f32 v5, v8, v9
	s_nop 0
	v_permlane16_swap_b32_e32 v2, v4
	v_permlane16_swap_b32_e32 v3, v5

.LBB0_193:
	v_sub_f32_e32 v63, v63, v64
	v_sub_f32_e32 v62, v62, v64
	v_sub_f32_e32 v61, v61, v64
	v_sub_f32_e32 v60, v60, v64
	v_sub_f32_e32 v59, v59, v64
	v_sub_f32_e32 v58, v58, v64
	v_sub_f32_e32 v57, v57, v64
	v_sub_f32_e32 v0, v0, v64
	v_exp_f32_e32 v173, v63
	v_exp_f32_e32 v165, v62
	v_exp_f32_e32 v169, v61
	v_exp_f32_e32 v163, v60
	v_exp_f32_e32 v167, v59
	v_exp_f32_e32 v171, v58
	v_exp_f32_e32 v67, v57
	v_exp_f32_e32 v57, v0
	v_cvt_pk_bf16_f32 v58, v173, v165
	v_cvt_pk_bf16_f32 v59, v169, v163
	v_cvt_pk_bf16_f32 v60, v167, v171
	v_cvt_pk_bf16_f32 v61, v67, v57
	v_add_f32_e32 v0, 0, v187
	s_lshl_b32 s60, s8, 1
	v_mfma_f32_16x16x32_bf16 v[62:65], v[96:99], v[58:61], v[20:23]
	v_add_f32_e32 v0, v188, v0
	v_mul_f32_e32 v132, v183, v132
	v_mul_f32_e32 v66, v184, v160
	v_mov_b64_e32 v[20:21], s[48:49]
	v_mad_i64_i32 v[20:21], s[28:29], v152, s1, v[20:21]
	v_lshl_add_u64 v[72:73], v[20:21], 0, s[60:61]
	v_mfma_f32_16x16x32_bf16 v[20:23], v[116:119], v[58:61], v[36:39]
	s_barrier
	s_nop 1
	v_pk_add_f32 v[36:37], v[172:173], v[0:1]
	v_add_f32_e32 v0, 0, v185
	v_add_f32_e32 v0, v186, v0
	v_pk_add_f32 v[38:39], v[158:159], v[0:1]
	v_mfma_f32_16x16x32_bf16 v[40:43], v[88:91], v[58:61], v[40:43]
	v_add_f32_e64 v38, v156, v38
	v_add_f32_e64 v39, v157, v39
	s_mov_b64 s[30:31], 0
	v_pk_add_f32 v[38:39], v[154:155], v[38:39]
	v_mfma_f32_16x16x32_bf16 v[44:47], v[92:95], v[58:61], v[44:47]
	v_add_f32_e64 v38, v138, v38
	v_add_f32_e64 v39, v139, v39
	v_pk_add_f32 v[38:39], v[136:137], v[38:39]
	v_mfma_f32_16x16x32_bf16 v[32:35], v[84:87], v[58:61], v[32:35]
	v_add_f32_e64 v38, v134, v38
	v_add_f32_e64 v39, v135, v39
	v_pk_add_f32 v[38:39], v[132:133], v[38:39]
	v_mfma_f32_16x16x32_bf16 v[28:31], v[112:115], v[58:61], v[28:31]
	v_add_f32_e32 v0, v39, v19
	v_fmac_f32_e32 v0, v38, v18
	ds_bpermute_b32 v38, v179, v0
	v_pk_add_f32 v[18:19], v[164:165], v[36:37]
	v_mfma_f32_16x16x32_bf16 v[24:27], v[108:111], v[58:61], v[24:27]
	v_add_f32_e64 v18, v168, v18
	v_add_f32_e64 v19, v169, v19
	s_waitcnt lgkmcnt(0)
	v_add_f32_e32 v0, v0, v38
	v_pk_add_f32 v[18:19], v[162:163], v[18:19]
	ds_bpermute_b32 v36, v178, v0
	v_pk_add_f32 v[18:19], v[166:167], v[18:19]
	v_mfma_f32_16x16x32_bf16 v[48:51], v[120:123], v[58:61], v[48:51]
	v_add_f32_e64 v18, v170, v18
	v_add_f32_e64 v19, v171, v19
	s_waitcnt lgkmcnt(0)
	v_add_f32_e32 v0, v0, v36
	v_pk_add_f32 v[18:19], v[66:67], v[18:19]
	v_div_scale_f32 v36, s[28:29], v0, v0, 1.0
	v_add_f32_e32 v19, v19, v57
	v_fmac_f32_e32 v19, v18, v56
	ds_bpermute_b32 v18, v179, v19
	v_rcp_f32_e32 v37, v36
	s_waitcnt lgkmcnt(0)
	v_add_f32_e32 v18, v19, v18
	ds_bpermute_b32 v19, v178, v18
	v_fma_f32 v38, -v36, v37, 1.0
	v_fmac_f32_e32 v37, v38, v37
	v_div_scale_f32 v38, vcc, 1.0, v0, 1.0
	v_mul_f32_e32 v39, v38, v37
	v_fma_f32 v56, -v36, v39, v38
	s_waitcnt lgkmcnt(0)
	v_add_f32_e32 v18, v18, v19
	v_fmac_f32_e32 v39, v56, v37
	v_div_scale_f32 v19, s[28:29], v18, v18, 1.0
	v_fma_f32 v36, -v36, v39, v38
	v_rcp_f32_e32 v38, v19
	v_div_fmas_f32 v36, v36, v37, v39
	v_div_fixup_f32 v56, v36, v0, 1.0
	s_mov_b64 s[28:29], 0x1000
	v_fma_f32 v0, -v19, v38, 1.0
	v_fmac_f32_e32 v38, v0, v38
	v_div_scale_f32 v0, vcc, 1.0, v18, 1.0
	v_mul_f32_e32 v36, v0, v38
	v_fma_f32 v37, -v19, v36, v0
	v_fmac_f32_e32 v36, v37, v38
	v_fma_f32 v0, -v19, v36, v0
	v_div_fmas_f32 v0, v0, v38, v36
	v_div_fixup_f32 v0, v0, v18, 1.0
	v_and_b32_e32 v18, 16, v180
	v_lshlrev_b32_e32 v19, 2, v181
	v_mul_u32_u24_e32 v36, 0xc00, v182
	v_add_u32_e32 v37, 12, v19
	v_cmp_eq_u32_e32 vcc, 0, v18
	v_mul_f32_e32 v58, v153, v0
	v_lshlrev_b32_e32 v0, 1, v36
	v_cndmask_b32_e32 v37, v37, v19, vcc
	v_pk_mul_f32 v[18:19], v[20:21], v[58:59] op_sel_hi:[1,0]
	v_pk_mul_f32 v[20:21], v[22:23], v[58:59] op_sel_hi:[1,0]
	v_lshl_add_u64 v[22:23], v[72:73], 0, v[0:1]
	v_lshlrev_b32_e32 v0, 1, v37
	v_lshl_add_u64 v[60:61], v[22:23], 0, v[0:1]
	v_lshlrev_b32_e32 v0, 4, v181
	v_lshl_add_u64 v[66:67], v[140:141], 0, v[0:1]
	v_pk_mul_f32 v[22:23], v[42:43], v[58:59] op_sel_hi:[1,0]
	v_pk_mul_f32 v[48:49], v[48:49], v[58:59] op_sel_hi:[1,0]
	v_pk_fma_f32 v[72:73], v[102:103], v[56:57], v[22:23] op_sel_hi:[1,0,1] neg_lo:[0,0,1] neg_hi:[0,0,1]
	v_pk_mul_f32 v[22:23], v[40:41], v[58:59] op_sel_hi:[1,0]
	global_load_dwordx4 v[36:39], v[66:67], off offset:64
	global_load_dwordx4 v[40:43], v[66:67], off
	v_pk_fma_f32 v[76:77], v[100:101], v[56:57], v[22:23] op_sel_hi:[1,0,1] neg_lo:[0,0,1] neg_hi:[0,0,1]
	v_pk_mul_f32 v[22:23], v[46:47], v[58:59] op_sel_hi:[1,0]
	v_pk_mul_f32 v[78:79], v[76:77], v[76:77]
	v_pk_fma_f32 v[82:83], v[82:83], v[56:57], v[22:23] op_sel_hi:[1,0,1] neg_lo:[0,0,1] neg_hi:[0,0,1]
	v_pk_mul_f32 v[22:23], v[44:45], v[58:59] op_sel_hi:[1,0]
	v_pk_mul_f32 v[84:85], v[82:83], v[82:83]
	v_pk_fma_f32 v[80:81], v[80:81], v[56:57], v[22:23] op_sel_hi:[1,0,1] neg_lo:[0,0,1] neg_hi:[0,0,1]
	v_pk_mul_f32 v[22:23], v[30:31], v[58:59] op_sel_hi:[1,0]
	v_pk_mul_f32 v[86:87], v[80:81], v[80:81]
	v_pk_fma_f32 v[70:71], v[70:71], v[56:57], v[22:23] op_sel_hi:[1,0,1] neg_lo:[0,0,1] neg_hi:[0,0,1]
	v_pk_mul_f32 v[22:23], v[28:29], v[58:59] op_sel_hi:[1,0]
	global_load_dwordx4 v[28:31], v[66:67], off offset:192
	global_load_dwordx4 v[44:47], v[66:67], off offset:128
	v_pk_fma_f32 v[68:69], v[68:69], v[56:57], v[22:23] op_sel_hi:[1,0,1] neg_lo:[0,0,1] neg_hi:[0,0,1]
	v_pk_mul_f32 v[22:23], v[34:35], v[58:59] op_sel_hi:[1,0]
	v_add_f32_e32 v0, v86, v87
	v_pk_fma_f32 v[16:17], v[16:17], v[56:57], v[22:23] op_sel_hi:[1,0,1] neg_lo:[0,0,1] neg_hi:[0,0,1]
	v_pk_mul_f32 v[22:23], v[32:33], v[58:59] op_sel_hi:[1,0]
	v_add_f32_e32 v0, v84, v0
	v_pk_fma_f32 v[92:93], v[14:15], v[56:57], v[22:23] op_sel_hi:[1,0,1] neg_lo:[0,0,1] neg_hi:[0,0,1]
	v_pk_mul_f32 v[14:15], v[64:65], v[58:59] op_sel_hi:[1,0]
	v_add_f32_e32 v0, v85, v0
	v_pk_fma_f32 v[64:65], v[12:13], v[56:57], v[14:15] op_sel_hi:[1,0,1] neg_lo:[0,0,1] neg_hi:[0,0,1]
	v_pk_mul_f32 v[12:13], v[62:63], v[58:59] op_sel_hi:[1,0]
	v_add_f32_e32 v0, v78, v0
	v_pk_fma_f32 v[62:63], v[10:11], v[56:57], v[12:13] op_sel_hi:[1,0,1] neg_lo:[0,0,1] neg_hi:[0,0,1]
	v_pk_mul_f32 v[10:11], v[26:27], v[58:59] op_sel_hi:[1,0]
	v_pk_mul_f32 v[74:75], v[72:73], v[72:73]
	v_pk_fma_f32 v[26:27], v[8:9], v[56:57], v[10:11] op_sel_hi:[1,0,1] neg_lo:[0,0,1] neg_hi:[0,0,1]
	global_load_dwordx4 v[8:11], v[66:67], off offset:320
	global_load_dwordx4 v[12:15], v[66:67], off offset:256
	v_add_f32_e32 v0, v79, v0
	v_add_f32_e32 v0, v74, v0
	v_pk_mul_f32 v[32:33], v[92:93], v[92:93]
	v_pk_mul_f32 v[22:23], v[24:25], v[58:59] op_sel_hi:[1,0]
	v_add_f32_e32 v0, v75, v0
	v_pk_fma_f32 v[100:101], v[6:7], v[56:57], v[22:23] op_sel_hi:[1,0,1] neg_lo:[0,0,1] neg_hi:[0,0,1]
	v_pk_mul_f32 v[22:23], v[50:51], v[58:59] op_sel_hi:[1,0]
	v_add_f32_e32 v0, v32, v0
	v_pk_mul_f32 v[34:35], v[16:17], v[16:17]
	v_pk_fma_f32 v[50:51], v[4:5], v[56:57], v[22:23] op_sel_hi:[1,0,1] neg_lo:[0,0,1] neg_hi:[0,0,1]
	global_load_dwordx4 v[22:25], v[66:67], off offset:384
	v_add_f32_e32 v0, v33, v0
	v_add_f32_e32 v0, v34, v0
	v_add_f32_e32 v0, v35, v0
	global_load_dwordx4 v[32:35], v[66:67], off offset:448
	v_pk_mul_f32 v[90:91], v[68:69], v[68:69]
	v_pk_mul_f32 v[88:89], v[70:71], v[70:71]
	v_add_f32_e32 v0, v90, v0
	v_add_f32_e32 v0, v91, v0
	v_add_f32_e32 v0, v88, v0
	v_pk_mul_f32 v[6:7], v[100:101], v[100:101]
	v_add_f32_e32 v0, v89, v0
	v_add_f32_e32 v0, v6, v0
	v_pk_mul_f32 v[98:99], v[26:27], v[26:27]
	v_add_f32_e32 v0, v7, v0
	v_add_f32_e32 v0, v98, v0
	v_pk_mul_f32 v[96:97], v[62:63], v[62:63]
	v_add_f32_e32 v0, v99, v0
	v_add_f32_e32 v0, v96, v0
	v_pk_mul_f32 v[94:95], v[64:65], v[64:65]
	v_add_f32_e32 v0, v97, v0
	v_pk_fma_f32 v[48:49], v[2:3], v[56:57], v[48:49] op_sel_hi:[1,0,1] neg_lo:[0,0,1] neg_hi:[0,0,1]
	v_add_f32_e32 v0, v94, v0
	v_pk_mul_f32 v[2:3], v[48:49], v[48:49]
	v_add_f32_e32 v0, v95, v0
	v_add_f32_e32 v0, v2, v0
	v_pk_mul_f32 v[4:5], v[50:51], v[50:51]
	v_add_f32_e32 v0, v3, v0
	v_pk_fma_f32 v[18:19], v[52:53], v[56:57], v[18:19] op_sel_hi:[1,0,1] neg_lo:[0,0,1] neg_hi:[0,0,1]
	v_add_f32_e32 v0, v4, v0
	v_pk_mul_f32 v[52:53], v[18:19], v[18:19]
	v_add_f32_e32 v0, v5, v0
	v_pk_fma_f32 v[20:21], v[54:55], v[56:57], v[20:21] op_sel_hi:[1,0,1] neg_lo:[0,0,1] neg_hi:[0,0,1]
	v_add_f32_e32 v0, v52, v0
	v_pk_mul_f32 v[54:55], v[20:21], v[20:21]
	v_add_f32_e32 v0, v53, v0
	v_add_f32_e32 v0, v54, v0
	v_add_f32_e32 v0, v55, v0
	ds_bpermute_b32 v2, v179, v0
	v_lshl_add_u64 v[6:7], v[60:61], 0, s[28:29]
	s_waitcnt lgkmcnt(0)
	v_add_f32_e32 v0, v0, v2
	ds_bpermute_b32 v2, v178, v0
	s_waitcnt lgkmcnt(0)
	v_add_f32_e32 v0, v0, v2
	v_fmamk_f32 v0, v0, 0x3c000000, v191
	v_mul_f32_e32 v2, 0x4b800000, v0
	v_cmp_gt_f32_e32 vcc, s0, v0
	s_nop 1
	v_cndmask_b32_e32 v0, v0, v2, vcc
	v_rsq_f32_e32 v0, v0
	s_nop 0
	v_mul_f32_e32 v2, 0x45800000, v0
	v_cndmask_b32_e32 v0, v0, v2, vcc
	v_mul_f32_e32 v0, v161, v0
	v_pk_mul_f32 v[2:3], v[80:81], v[0:1] op_sel_hi:[1,0]
	v_pk_mul_f32 v[4:5], v[82:83], v[0:1] op_sel_hi:[1,0]
	s_waitcnt vmcnt(6)
	v_pk_mul_f32 v[2:3], v[40:41], v[2:3]
	v_pk_mul_f32 v[4:5], v[42:43], v[4:5]
	v_cvt_pk_bf16_f32 v2, v2, v3
	v_cvt_pk_bf16_f32 v3, v4, v5
	v_pk_mul_f32 v[4:5], v[76:77], v[0:1] op_sel_hi:[1,0]
	s_nop 0
	v_pk_mul_f32 v[4:5], v[36:37], v[4:5]
	v_pk_mul_f32 v[36:37], v[72:73], v[0:1] op_sel_hi:[1,0]
	v_cvt_pk_bf16_f32 v4, v4, v5
	v_pk_mul_f32 v[36:37], v[38:39], v[36:37]
	s_nop 0
	v_permlane16_swap_b32_e32 v2, v4
	v_cvt_pk_bf16_f32 v5, v36, v37
	v_add_co_u32_e32 v36, vcc, s51, v60
	s_nop 0
	v_permlane16_swap_b32_e32 v3, v5
	v_addc_co_u32_e32 v37, vcc, 0, v61, vcc
	global_store_dwordx4 v[36:37], v[2:5], off sc1
	s_nop 1
	v_pk_mul_f32 v[2:3], v[92:93], v[0:1] op_sel_hi:[1,0]
	v_pk_mul_f32 v[4:5], v[16:17], v[0:1] op_sel_hi:[1,0]
	s_waitcnt vmcnt(5)
	v_pk_mul_f32 v[2:3], v[44:45], v[2:3]
	v_pk_mul_f32 v[4:5], v[46:47], v[4:5]
	v_cvt_pk_bf16_f32 v2, v2, v3
	v_cvt_pk_bf16_f32 v3, v4, v5
	v_pk_mul_f32 v[4:5], v[68:69], v[0:1] op_sel_hi:[1,0]
	v_pk_mul_f32 v[16:17], v[70:71], v[0:1] op_sel_hi:[1,0]
	v_pk_mul_f32 v[4:5], v[28:29], v[4:5]
	v_pk_mul_f32 v[16:17], v[30:31], v[16:17]
	v_cvt_pk_bf16_f32 v4, v4, v5
	v_cvt_pk_bf16_f32 v5, v16, v17
	s_nop 0
	v_permlane16_swap_b32_e32 v2, v4
	v_permlane16_swap_b32_e32 v3, v5
	global_store_dwordx4 v[6:7], v[2:5], off offset:64 sc1
	s_nop 1
	v_pk_mul_f32 v[2:3], v[100:101], v[0:1] op_sel_hi:[1,0]
	v_pk_mul_f32 v[4:5], v[26:27], v[0:1] op_sel_hi:[1,0]
	s_waitcnt vmcnt(4)
	v_pk_mul_f32 v[2:3], v[12:13], v[2:3]
	v_pk_mul_f32 v[4:5], v[14:15], v[4:5]
	v_cvt_pk_bf16_f32 v2, v2, v3
	v_cvt_pk_bf16_f32 v3, v4, v5
	v_pk_mul_f32 v[4:5], v[62:63], v[0:1] op_sel_hi:[1,0]
	s_nop 0
	v_pk_mul_f32 v[4:5], v[8:9], v[4:5]
	v_pk_mul_f32 v[8:9], v[64:65], v[0:1] op_sel_hi:[1,0]
	v_cvt_pk_bf16_f32 v4, v4, v5
	v_pk_mul_f32 v[8:9], v[10:11], v[8:9]
	s_nop 0
	v_permlane16_swap_b32_e32 v2, v4
	v_cvt_pk_bf16_f32 v5, v8, v9
	s_nop 1
	v_permlane16_swap_b32_e32 v3, v5
	global_store_dwordx4 v[6:7], v[2:5], off offset:128 sc1
	v_pk_mul_f32 v[8:9], v[20:21], v[0:1] op_sel_hi:[1,0]
	s_nop 0
	v_pk_mul_f32 v[2:3], v[48:49], v[0:1] op_sel_hi:[1,0]
	v_pk_mul_f32 v[4:5], v[50:51], v[0:1] op_sel_hi:[1,0]
	s_waitcnt vmcnt(4)
	v_pk_mul_f32 v[2:3], v[22:23], v[2:3]
	v_pk_mul_f32 v[4:5], v[24:25], v[4:5]
	v_cvt_pk_bf16_f32 v2, v2, v3
	v_cvt_pk_bf16_f32 v3, v4, v5
	v_pk_mul_f32 v[4:5], v[18:19], v[0:1] op_sel_hi:[1,0]
	s_waitcnt vmcnt(3)
	v_pk_mul_f32 v[8:9], v[8:9], v[34:35]
	v_pk_mul_f32 v[4:5], v[32:33], v[4:5]
	s_nop 0
	v_cvt_pk_bf16_f32 v4, v4, v5
	v_cvt_pk_bf16_f32 v5, v8, v9
	s_nop 0
	v_permlane16_swap_b32_e32 v2, v4
	v_permlane16_swap_b32_e32 v3, v5

.LBB0_210:
	ds_bpermute_b32 v0, v109, v116
	s_lshl_b32 s9, s9, 7
	v_mov_b64_e32 v[2:3], s[48:49]
	s_lshl_b32 s60, s9, 1
	v_mad_i64_i32 v[2:3], s[30:31], v152, s1, v[2:3]
	s_waitcnt lgkmcnt(0)
	v_add_f32_e32 v4, v116, v0
	ds_bpermute_b32 v5, v115, v4
	v_mul_u32_u24_e32 v0, 0xc00, v111
	v_lshlrev_b32_e32 v0, 1, v0
	v_lshl_add_u64 v[2:3], v[2:3], 0, s[60:61]
	v_lshl_add_u64 v[2:3], v[2:3], 0, v[0:1]
	s_waitcnt lgkmcnt(0)
	v_add_f32_e32 v4, v4, v5
	v_div_scale_f32 v5, s[30:31], v4, v4, 1.0
	v_rcp_f32_e32 v6, v5
	v_div_scale_f32 v7, vcc, 1.0, v4, 1.0
	v_and_b32_e32 v0, 16, v110
	v_fma_f32 v8, -v5, v6, 1.0
	v_fmac_f32_e32 v6, v8, v6
	v_mul_f32_e32 v8, v7, v6
	v_fma_f32 v9, -v5, v8, v7
	v_fmac_f32_e32 v8, v9, v6
	v_fma_f32 v5, -v5, v8, v7
	v_div_fmas_f32 v5, v5, v6, v8
	v_div_fixup_f32 v10, v5, v4, 1.0
	v_add_u32_e32 v4, 12, v114
	v_cmp_eq_u32_e32 vcc, 0, v0
	v_mul_f32_e32 v5, v63, v10
	s_mov_b64 s[30:31], 0x800
	v_cndmask_b32_e32 v0, v4, v114, vcc
	v_lshl_add_u64 v[8:9], v[0:1], 1, v[2:3]
	v_mul_f32_e32 v0, v64, v10
	v_mul_f32_e32 v2, v65, v10
	v_cvt_pk_bf16_f32 v2, v0, v2
	v_mul_f32_e32 v0, v66, v10
	v_mul_f32_e32 v3, v67, v10
	v_cvt_pk_bf16_f32 v3, v0, v3
	v_mul_f32_e32 v0, v60, v10
	v_mul_f32_e32 v4, v61, v10
	v_cvt_pk_bf16_f32 v4, v0, v4
	v_mul_f32_e32 v0, v62, v10
	v_cvt_pk_bf16_f32 v5, v0, v5
	v_permlane16_swap_b32_e32 v2, v4
	s_nop 0
	v_permlane16_swap_b32_e32 v3, v5
	global_store_dwordx4 v[8:9], v[2:5], off offset:2048 sc1
	v_mul_f32_e32 v0, v56, v10
	v_lshl_add_u64 v[6:7], v[8:9], 0, s[30:31]
	v_mul_f32_e32 v2, v57, v10
	v_cvt_pk_bf16_f32 v2, v0, v2
	v_mul_f32_e32 v0, v58, v10
	v_mul_f32_e32 v3, v59, v10
	v_cvt_pk_bf16_f32 v3, v0, v3
	v_mul_f32_e32 v0, v52, v10
	v_mul_f32_e32 v4, v53, v10
	v_cvt_pk_bf16_f32 v4, v0, v4
	v_mul_f32_e32 v0, v54, v10
	v_mul_f32_e32 v5, v55, v10
	v_cvt_pk_bf16_f32 v5, v0, v5
	v_permlane16_swap_b32_e32 v2, v4
	s_nop 0
	v_permlane16_swap_b32_e32 v3, v5
	global_store_dwordx4 v[8:9], v[2:5], off offset:2112 sc1
	v_mul_f32_e32 v0, v48, v10
	s_nop 0
	v_mul_f32_e32 v2, v49, v10
	v_cvt_pk_bf16_f32 v2, v0, v2
	v_mul_f32_e32 v0, v50, v10
	v_mul_f32_e32 v3, v51, v10
	v_cvt_pk_bf16_f32 v3, v0, v3
	v_mul_f32_e32 v0, v44, v10
	v_mul_f32_e32 v4, v45, v10
	v_cvt_pk_bf16_f32 v4, v0, v4
	v_mul_f32_e32 v0, v46, v10
	v_mul_f32_e32 v5, v47, v10
	v_cvt_pk_bf16_f32 v5, v0, v5
	v_permlane16_swap_b32_e32 v2, v4
	s_nop 0
	v_permlane16_swap_b32_e32 v3, v5
	global_store_dwordx4 v[8:9], v[2:5], off offset:2176 sc1
	v_mul_f32_e32 v0, v40, v10
	s_nop 0
	v_mul_f32_e32 v2, v41, v10
	v_cvt_pk_bf16_f32 v2, v0, v2
	v_mul_f32_e32 v0, v42, v10
	v_mul_f32_e32 v3, v43, v10
	v_cvt_pk_bf16_f32 v3, v0, v3
	v_mul_f32_e32 v0, v36, v10
	v_mul_f32_e32 v4, v37, v10
	v_cvt_pk_bf16_f32 v4, v0, v4
	v_mul_f32_e32 v0, v38, v10
	v_mul_f32_e32 v5, v39, v10
	v_cvt_pk_bf16_f32 v5, v0, v5
	v_permlane16_swap_b32_e32 v2, v4
	s_nop 0
	v_permlane16_swap_b32_e32 v3, v5
	s_cbranch_execnz .LBB0_135
	s_branch .LBB0_174

.LBB0_217:
	s_or_b64 exec, exec, s[90:91]
	v_lshlrev_b32_e32 v36, 2, v41
	v_mov_b32_e32 v37, v1
	v_lshl_add_u64 v[54:55], v[30:31], 0, v[36:37]
	v_lshl_add_u64 v[58:59], v[32:33], 0, v[36:37]
	v_lshl_add_u64 v[36:37], v[34:35], 0, v[36:37]
	global_load_dwordx4 v[42:45], v[54:55], off
	global_load_dwordx4 v[46:49], v[58:59], off
	global_load_dwordx4 v[50:53], v[36:37], off
	s_nop 0
	global_load_dwordx4 v[54:57], v[54:55], off offset:16
	s_nop 0
	global_load_dwordx4 v[58:61], v[58:59], off offset:16
	s_nop 0
	global_load_dwordx4 v[62:65], v[36:37], off offset:16
	s_waitcnt vmcnt(7)
	v_lshlrev_b32_e32 v70, 16, v6
	v_and_b32_e32 v71, 0xffff0000, v6
	v_lshlrev_b32_e32 v6, 16, v7
	v_and_b32_e32 v7, 0xffff0000, v7
	v_lshlrev_b32_e32 v84, 16, v8
	v_and_b32_e32 v85, 0xffff0000, v8
	v_lshlrev_b32_e32 v66, 16, v22
	s_waitcnt vmcnt(6)
	v_lshlrev_b32_e32 v72, 16, v14
	v_and_b32_e32 v67, 0xffff0000, v22
	v_and_b32_e32 v73, 0xffff0000, v14
	v_lshlrev_b32_e32 v22, 16, v23
	v_lshlrev_b32_e32 v14, 16, v15
	v_and_b32_e32 v23, 0xffff0000, v23
	v_and_b32_e32 v15, 0xffff0000, v15
	v_lshlrev_b32_e32 v80, 16, v24
	v_lshlrev_b32_e32 v86, 16, v16
	v_and_b32_e32 v81, 0xffff0000, v24
	v_and_b32_e32 v87, 0xffff0000, v16
	v_lshlrev_b32_e32 v68, 16, v18
	v_and_b32_e32 v69, 0xffff0000, v18
	v_lshlrev_b32_e32 v74, 16, v26
	v_and_b32_e32 v75, 0xffff0000, v26
	v_lshlrev_b32_e32 v18, 16, v19
	v_and_b32_e32 v19, 0xffff0000, v19
	v_lshlrev_b32_e32 v26, 16, v27
	v_and_b32_e32 v27, 0xffff0000, v27
	v_lshlrev_b32_e32 v82, 16, v20
	v_and_b32_e32 v83, 0xffff0000, v20
	v_lshlrev_b32_e32 v88, 16, v28
	v_and_b32_e32 v89, 0xffff0000, v28
	v_lshlrev_b32_e32 v76, 16, v2
	v_and_b32_e32 v77, 0xffff0000, v2
	v_lshlrev_b32_e32 v2, 16, v3
	v_and_b32_e32 v3, 0xffff0000, v3
	v_lshlrev_b32_e32 v90, 16, v4
	v_and_b32_e32 v91, 0xffff0000, v4
	v_lshlrev_b32_e32 v78, 16, v12
	v_and_b32_e32 v79, 0xffff0000, v12
	v_lshlrev_b32_e32 v8, 16, v9
	v_and_b32_e32 v9, 0xffff0000, v9
	v_lshlrev_b32_e32 v36, 16, v10
	v_and_b32_e32 v37, 0xffff0000, v10
	v_lshlrev_b32_e32 v10, 16, v11
	v_and_b32_e32 v11, 0xffff0000, v11
	v_lshlrev_b32_e32 v24, 16, v25
	v_lshlrev_b32_e32 v16, 16, v17
	v_and_b32_e32 v25, 0xffff0000, v25
	v_and_b32_e32 v17, 0xffff0000, v17
	v_lshlrev_b32_e32 v20, 16, v21
	v_and_b32_e32 v21, 0xffff0000, v21
	v_lshlrev_b32_e32 v12, 16, v13
	v_and_b32_e32 v13, 0xffff0000, v13
	v_add_u32_e32 v38, s86, v38
	s_mov_b32 s2, 0xfffff
	v_cmp_lt_i32_e32 vcc, s2, v38
	s_or_b64 s[74:75], vcc, s[74:75]
	v_add_u32_e32 v39, s54, v39
	s_waitcnt vmcnt(5)
	v_pk_mul_f32 v[22:23], v[44:45], v[22:23]
	s_waitcnt vmcnt(4)
	v_pk_mul_f32 v[6:7], v[48:49], v[6:7]
	s_waitcnt vmcnt(3)
	v_pk_mul_f32 v[26:27], v[52:53], v[26:27]
	s_waitcnt vmcnt(2)
	v_pk_mul_f32 v[44:45], v[54:55], v[80:81]
	s_waitcnt vmcnt(1)
	v_pk_mul_f32 v[48:49], v[58:59], v[84:85]
	v_pk_mul_f32 v[6:7], v[6:7], v[14:15]
	v_pk_mul_f32 v[14:15], v[48:49], v[86:87]
	s_waitcnt vmcnt(0)
	v_pk_mul_f32 v[52:53], v[62:63], v[88:89]
	v_pk_fma_f32 v[6:7], v[22:23], v[18:19], v[6:7]
	v_pk_fma_f32 v[14:15], v[44:45], v[82:83], v[14:15]
	v_pk_fma_f32 v[2:3], v[26:27], v[2:3], v[6:7]
	v_pk_fma_f32 v[6:7], v[52:53], v[90:91], v[14:15]
	v_pk_mul_f32 v[24:25], v[56:57], v[24:25]
	v_pk_mul_f32 v[6:7], v[6:7], v[78:79]
	v_pk_mul_f32 v[10:11], v[2:3], v[10:11]
	v_cvt_pk_bf16_f32 v4, v6, v7
	v_pk_mul_f32 v[6:7], v[60:61], v[8:9]
	v_lshlrev_b32_e32 v8, 16, v29
	v_pk_mul_f32 v[6:7], v[6:7], v[16:17]
	v_and_b32_e32 v9, 0xffff0000, v29
	v_pk_mul_f32 v[46:47], v[46:47], v[70:71]
	v_cvt_pk_bf16_f32 v3, v10, v11
	v_pk_fma_f32 v[6:7], v[24:25], v[20:21], v[6:7]
	v_pk_mul_f32 v[8:9], v[64:65], v[8:9]
	v_lshlrev_b32_e32 v10, 16, v5
	v_and_b32_e32 v11, 0xffff0000, v5
	v_pk_mul_f32 v[42:43], v[42:43], v[66:67]
	v_pk_mul_f32 v[46:47], v[46:47], v[72:73]
	v_pk_fma_f32 v[6:7], v[8:9], v[10:11], v[6:7]
	v_pk_mul_f32 v[50:51], v[50:51], v[74:75]
	v_pk_fma_f32 v[42:43], v[42:43], v[68:69], v[46:47]
	v_pk_mul_f32 v[6:7], v[6:7], v[12:13]
	v_pk_fma_f32 v[18:19], v[50:51], v[76:77], v[42:43]
	v_cvt_pk_bf16_f32 v5, v6, v7
	v_mov_b64_e32 v[6:7], s[48:49]
	v_pk_mul_f32 v[14:15], v[18:19], v[36:37]
	v_mad_i64_i32 v[6:7], s[8:9], v40, s1, v[6:7]
	v_cvt_pk_bf16_f32 v2, v14, v15
	v_lshl_add_u64 v[6:7], v[6:7], 0, v[0:1]
	global_store_dwordx4 v[6:7], v[2:5], off sc1
	s_andn2_b64 exec, exec, s[74:75]
	s_cbranch_execz .LBB0_222

.LBB0_246:
	v_cvt_pk_bf16_f32 v6, v6, v7
	v_cvt_pk_bf16_f32 v7, v8, v9
	v_cvt_pk_bf16_f32 v8, v2, v3
	v_cvt_pk_bf16_f32 v9, v4, v5
	v_add_co_u32_e32 v2, vcc, 0x4a4000, v130
	v_permlane16_swap_b32_e32 v6, v8
	v_permlane16_swap_b32_e32 v7, v9
	v_addc_co_u32_e32 v3, vcc, 0, v131, vcc
	global_store_dwordx4 v[2:3], v[6:9], off offset:256 sc1

.LBB0_266:
	v_mov_b32_e32 v0, v190
	s_mov_b64 s[28:29], -1
	v_ashrrev_i32_e32 v131, 2, v0
	v_and_b32_e32 v130, 15, v0
	v_and_b32_e32 v131, 0xffffffc0, v131
	v_add3_u32 v198, v130, s60, v131
	v_lshrrev_b32_e32 v130, 1, v0
	v_and_b32_e32 v230, 0x60, v130
	v_lshrrev_b32_e32 v130, 2, v0
	v_and_b32_e32 v130, 12, v130
	v_and_b32_e32 v0, 16, v0
	v_add_u32_e32 v131, 12, v130
	v_cmp_eq_u32_e32 vcc, 0, v0
	v_add3_u32 v200, v230, s94, v130
	s_mov_b64 s[6:7], 0
	v_cndmask_b32_e32 v231, v131, v130, vcc
	s_cmp_lt_i32 s97, 1
	s_mov_b64 s[24:25], 0
	s_cbranch_scc1 .LBB0_282
	s_cmp_gt_i32 s97, 2
	s_cbranch_scc0 .LBB0_271
	s_cmp_eq_u32 s97, 3
	s_mov_b64 s[24:25], -1
	s_cbranch_scc0 .LBB0_270
	v_ashrrev_i32_e32 v199, 31, v198
	v_lshlrev_b64 v[130:131], 14, v[198:199]
	v_lshl_add_u64 v[130:131], s[34:35], 0, v[130:131]
	v_lshl_add_u64 v[130:131], s[94:95], 1, v[130:131]
	v_lshlrev_b32_e32 v0, 1, v230
	v_lshl_add_u64 v[130:131], v[130:131], 0, v[0:1]
	v_lshlrev_b32_e32 v0, 1, v231
	v_lshl_add_u64 v[130:131], v[130:131], 0, v[0:1]
	v_max_f32_e32 v0, v126, v126
	v_max_f32_e32 v132, v127, v127
	v_max_f32_e32 v0, 0, v0
	v_max_f32_e32 v132, 0, v132
	v_max_f32_e32 v133, v128, v128
	v_max_f32_e32 v134, v129, v129
	v_max_f32_e32 v133, 0, v133
	v_max_f32_e32 v134, 0, v134
	v_max_f32_e32 v135, v122, v122
	v_max_f32_e32 v136, v123, v123
	v_mul_f32_e32 v0, v0, v0
	v_mul_f32_e32 v132, v132, v132
	v_max_f32_e32 v135, 0, v135
	v_max_f32_e32 v136, 0, v136
	v_max_f32_e32 v137, v124, v124
	v_max_f32_e32 v138, v125, v125
	v_cvt_pk_bf16_f32 v132, v0, v132
	v_mul_f32_e32 v0, v133, v133
	v_mul_f32_e32 v133, v134, v134
	v_max_f32_e32 v137, 0, v137
	v_max_f32_e32 v138, 0, v138
	v_cvt_pk_bf16_f32 v133, v0, v133
	v_mul_f32_e32 v0, v135, v135
	v_mul_f32_e32 v134, v136, v136
	v_cvt_pk_bf16_f32 v134, v0, v134
	v_mul_f32_e32 v0, v137, v137
	v_mul_f32_e32 v135, v138, v138
	v_cvt_pk_bf16_f32 v135, v0, v135
	v_permlane16_swap_b32_e32 v132, v134
	s_nop 0
	v_permlane16_swap_b32_e32 v133, v135
	global_store_dwordx4 v[130:131], v[132:135], off sc1
	v_max_f32_e32 v0, v118, v118
	v_max_f32_e32 v0, 0, v0
	v_max_f32_e32 v132, v119, v119
	v_max_f32_e32 v132, 0, v132
	v_max_f32_e32 v133, v120, v120
	v_max_f32_e32 v134, v121, v121
	v_max_f32_e32 v133, 0, v133
	v_max_f32_e32 v134, 0, v134
	v_max_f32_e32 v135, v114, v114
	v_max_f32_e32 v136, v115, v115
	v_mul_f32_e32 v0, v0, v0
	v_mul_f32_e32 v132, v132, v132
	v_max_f32_e32 v135, 0, v135
	v_max_f32_e32 v136, 0, v136
	v_max_f32_e32 v137, v116, v116
	v_max_f32_e32 v138, v117, v117
	v_cvt_pk_bf16_f32 v132, v0, v132
	v_mul_f32_e32 v0, v133, v133
	v_mul_f32_e32 v133, v134, v134
	v_max_f32_e32 v137, 0, v137
	v_max_f32_e32 v138, 0, v138
	v_cvt_pk_bf16_f32 v133, v0, v133
	v_mul_f32_e32 v0, v135, v135
	v_mul_f32_e32 v134, v136, v136
	v_cvt_pk_bf16_f32 v134, v0, v134
	v_mul_f32_e32 v0, v137, v137
	v_mul_f32_e32 v135, v138, v138
	v_cvt_pk_bf16_f32 v135, v0, v135
	v_add_co_u32_e32 v136, vcc, s12, v130
	v_permlane16_swap_b32_e32 v132, v134
	v_permlane16_swap_b32_e32 v133, v135
	v_addc_co_u32_e32 v137, vcc, 0, v131, vcc
	global_store_dwordx4 v[136:137], v[132:135], off sc1
	v_max_f32_e32 v0, v110, v110
	v_max_f32_e32 v0, 0, v0
	v_max_f32_e32 v132, v111, v111
	v_max_f32_e32 v132, 0, v132
	v_max_f32_e32 v133, v112, v112
	v_max_f32_e32 v134, v113, v113
	v_max_f32_e32 v133, 0, v133
	v_max_f32_e32 v134, 0, v134
	v_max_f32_e32 v135, v106, v106
	v_max_f32_e32 v138, v107, v107
	v_mul_f32_e32 v0, v0, v0
	v_mul_f32_e32 v132, v132, v132
	v_max_f32_e32 v135, 0, v135
	v_max_f32_e32 v138, 0, v138
	v_max_f32_e32 v139, v108, v108
	v_max_f32_e32 v140, v109, v109
	v_cvt_pk_bf16_f32 v132, v0, v132
	v_mul_f32_e32 v0, v133, v133
	v_mul_f32_e32 v133, v134, v134
	v_max_f32_e32 v139, 0, v139
	v_max_f32_e32 v140, 0, v140
	v_cvt_pk_bf16_f32 v133, v0, v133
	v_mul_f32_e32 v0, v135, v135
	v_mul_f32_e32 v134, v138, v138
	v_cvt_pk_bf16_f32 v134, v0, v134
	v_mul_f32_e32 v0, v139, v139
	v_mul_f32_e32 v135, v140, v140
	s_mov_b32 s2, 0x80000
	v_cvt_pk_bf16_f32 v135, v0, v135
	v_add_co_u32_e32 v138, vcc, s2, v130
	v_permlane16_swap_b32_e32 v132, v134
	v_permlane16_swap_b32_e32 v133, v135
	v_addc_co_u32_e32 v139, vcc, 0, v131, vcc
	global_store_dwordx4 v[138:139], v[132:135], off sc1
	v_max_f32_e32 v0, v102, v102
	v_max_f32_e32 v0, 0, v0
	v_max_f32_e32 v132, v103, v103
	v_max_f32_e32 v132, 0, v132
	v_max_f32_e32 v133, v104, v104
	v_max_f32_e32 v134, v105, v105
	v_max_f32_e32 v133, 0, v133
	v_max_f32_e32 v134, 0, v134
	v_max_f32_e32 v135, v98, v98
	v_max_f32_e32 v140, v99, v99
	v_mul_f32_e32 v0, v0, v0
	v_mul_f32_e32 v132, v132, v132
	v_max_f32_e32 v135, 0, v135
	v_max_f32_e32 v140, 0, v140
	v_max_f32_e32 v141, v100, v100
	v_max_f32_e32 v142, v101, v101
	v_cvt_pk_bf16_f32 v132, v0, v132
	v_mul_f32_e32 v0, v133, v133
	v_mul_f32_e32 v133, v134, v134
	v_max_f32_e32 v141, 0, v141
	v_max_f32_e32 v142, 0, v142
	v_cvt_pk_bf16_f32 v133, v0, v133
	v_mul_f32_e32 v0, v135, v135
	v_mul_f32_e32 v134, v140, v140
	v_cvt_pk_bf16_f32 v134, v0, v134
	v_mul_f32_e32 v0, v141, v141
	v_mul_f32_e32 v135, v142, v142
	s_mov_b32 s2, 0xc0000
	v_cvt_pk_bf16_f32 v135, v0, v135
	v_add_co_u32_e32 v140, vcc, s2, v130
	v_permlane16_swap_b32_e32 v132, v134
	v_permlane16_swap_b32_e32 v133, v135
	v_addc_co_u32_e32 v141, vcc, 0, v131, vcc
	global_store_dwordx4 v[140:141], v[132:135], off sc1
	v_max_f32_e32 v0, v94, v94
	v_max_f32_e32 v0, 0, v0
	v_max_f32_e32 v132, v95, v95
	v_max_f32_e32 v132, 0, v132
	v_max_f32_e32 v133, v96, v96
	v_max_f32_e32 v134, v97, v97
	v_max_f32_e32 v133, 0, v133
	v_max_f32_e32 v134, 0, v134
	v_max_f32_e32 v135, v90, v90
	v_max_f32_e32 v142, v91, v91
	v_mul_f32_e32 v0, v0, v0
	v_mul_f32_e32 v132, v132, v132
	v_max_f32_e32 v135, 0, v135
	v_max_f32_e32 v142, 0, v142
	v_max_f32_e32 v143, v92, v92
	v_max_f32_e32 v144, v93, v93
	v_cvt_pk_bf16_f32 v132, v0, v132
	v_mul_f32_e32 v0, v133, v133
	v_mul_f32_e32 v133, v134, v134
	v_max_f32_e32 v143, 0, v143
	v_max_f32_e32 v144, 0, v144
	v_cvt_pk_bf16_f32 v133, v0, v133
	v_mul_f32_e32 v0, v135, v135
	v_mul_f32_e32 v134, v142, v142
	v_cvt_pk_bf16_f32 v134, v0, v134
	v_mul_f32_e32 v0, v143, v143
	v_mul_f32_e32 v135, v144, v144
	v_cvt_pk_bf16_f32 v135, v0, v135
	v_permlane16_swap_b32_e32 v132, v134
	s_nop 0
	v_permlane16_swap_b32_e32 v133, v135
	global_store_dwordx4 v[130:131], v[132:135], off offset:256 sc1
	v_max_f32_e32 v0, v86, v86
	v_max_f32_e32 v0, 0, v0
	v_max_f32_e32 v132, v87, v87
	v_max_f32_e32 v132, 0, v132
	v_max_f32_e32 v133, v88, v88
	v_max_f32_e32 v134, v89, v89
	v_max_f32_e32 v133, 0, v133
	v_max_f32_e32 v134, 0, v134
	v_max_f32_e32 v135, v82, v82
	v_max_f32_e32 v142, v83, v83
	v_mul_f32_e32 v0, v0, v0
	v_mul_f32_e32 v132, v132, v132
	v_max_f32_e32 v135, 0, v135
	v_max_f32_e32 v142, 0, v142
	v_max_f32_e32 v143, v84, v84
	v_max_f32_e32 v144, v85, v85
	v_cvt_pk_bf16_f32 v132, v0, v132
	v_mul_f32_e32 v0, v133, v133
	v_mul_f32_e32 v133, v134, v134
	v_max_f32_e32 v143, 0, v143
	v_max_f32_e32 v144, 0, v144
	v_cvt_pk_bf16_f32 v133, v0, v133
	v_mul_f32_e32 v0, v135, v135
	v_mul_f32_e32 v134, v142, v142
	v_cvt_pk_bf16_f32 v134, v0, v134
	v_mul_f32_e32 v0, v143, v143
	v_mul_f32_e32 v135, v144, v144
	v_cvt_pk_bf16_f32 v135, v0, v135
	v_permlane16_swap_b32_e32 v132, v134
	s_nop 0
	v_permlane16_swap_b32_e32 v133, v135
	global_store_dwordx4 v[136:137], v[132:135], off offset:256 sc1
	v_max_f32_e32 v0, v78, v78
	v_max_f32_e32 v0, 0, v0
	v_max_f32_e32 v132, v79, v79
	v_max_f32_e32 v132, 0, v132
	v_max_f32_e32 v133, v80, v80
	v_max_f32_e32 v134, v81, v81
	v_max_f32_e32 v133, 0, v133
	v_max_f32_e32 v134, 0, v134
	v_max_f32_e32 v135, v74, v74
	v_max_f32_e32 v136, v75, v75
	v_mul_f32_e32 v0, v0, v0
	v_mul_f32_e32 v132, v132, v132
	v_max_f32_e32 v135, 0, v135
	v_max_f32_e32 v136, 0, v136
	v_max_f32_e32 v137, v76, v76
	v_max_f32_e32 v142, v77, v77
	v_cvt_pk_bf16_f32 v132, v0, v132
	v_mul_f32_e32 v0, v133, v133
	v_mul_f32_e32 v133, v134, v134
	v_max_f32_e32 v137, 0, v137
	v_max_f32_e32 v142, 0, v142
	v_cvt_pk_bf16_f32 v133, v0, v133
	v_mul_f32_e32 v0, v135, v135
	v_mul_f32_e32 v134, v136, v136
	v_cvt_pk_bf16_f32 v134, v0, v134
	v_mul_f32_e32 v0, v137, v137
	v_mul_f32_e32 v135, v142, v142
	v_cvt_pk_bf16_f32 v135, v0, v135
	v_permlane16_swap_b32_e32 v132, v134
	s_nop 0
	v_permlane16_swap_b32_e32 v133, v135
	global_store_dwordx4 v[138:139], v[132:135], off offset:256 sc1
	v_max_f32_e32 v0, v70, v70
	v_max_f32_e32 v0, 0, v0
	v_max_f32_e32 v132, v71, v71
	v_max_f32_e32 v132, 0, v132
	v_max_f32_e32 v133, v72, v72
	v_max_f32_e32 v134, v73, v73
	v_max_f32_e32 v133, 0, v133
	v_max_f32_e32 v134, 0, v134
	v_max_f32_e32 v135, v66, v66
	v_max_f32_e32 v136, v67, v67
	v_mul_f32_e32 v0, v0, v0
	v_mul_f32_e32 v132, v132, v132
	v_max_f32_e32 v135, 0, v135
	v_max_f32_e32 v136, 0, v136
	v_max_f32_e32 v137, v68, v68
	v_max_f32_e32 v138, v69, v69
	v_cvt_pk_bf16_f32 v132, v0, v132
	v_mul_f32_e32 v0, v133, v133
	v_mul_f32_e32 v133, v134, v134
	v_max_f32_e32 v137, 0, v137
	v_max_f32_e32 v138, 0, v138
	v_cvt_pk_bf16_f32 v133, v0, v133
	v_mul_f32_e32 v0, v135, v135
	v_mul_f32_e32 v134, v136, v136
	v_cvt_pk_bf16_f32 v134, v0, v134
	v_mul_f32_e32 v0, v137, v137
	v_mul_f32_e32 v135, v138, v138
	v_cvt_pk_bf16_f32 v135, v0, v135
	v_permlane16_swap_b32_e32 v132, v134
	s_nop 0
	v_permlane16_swap_b32_e32 v133, v135
	global_store_dwordx4 v[140:141], v[132:135], off offset:256 sc1
	v_max_f32_e32 v0, v62, v62
	v_max_f32_e32 v0, 0, v0
	v_max_f32_e32 v132, v63, v63
	v_max_f32_e32 v132, 0, v132
	v_max_f32_e32 v133, v64, v64
	v_max_f32_e32 v134, v65, v65
	v_max_f32_e32 v133, 0, v133
	v_max_f32_e32 v134, 0, v134
	v_max_f32_e32 v135, v58, v58
	v_max_f32_e32 v136, v59, v59
	v_mul_f32_e32 v0, v0, v0
	v_mul_f32_e32 v132, v132, v132
	v_max_f32_e32 v135, 0, v135
	v_max_f32_e32 v136, 0, v136
	v_max_f32_e32 v137, v60, v60
	v_max_f32_e32 v138, v61, v61
	v_cvt_pk_bf16_f32 v132, v0, v132
	v_mul_f32_e32 v0, v133, v133
	v_mul_f32_e32 v133, v134, v134
	v_max_f32_e32 v137, 0, v137
	v_max_f32_e32 v138, 0, v138
	v_cvt_pk_bf16_f32 v133, v0, v133
	v_mul_f32_e32 v0, v135, v135
	v_mul_f32_e32 v134, v136, v136
	v_cvt_pk_bf16_f32 v134, v0, v134
	v_mul_f32_e32 v0, v137, v137
	v_mul_f32_e32 v135, v138, v138
	s_mov_b32 s2, 0x200000
	v_cvt_pk_bf16_f32 v135, v0, v135
	v_add_co_u32_e32 v136, vcc, s2, v130
	v_permlane16_swap_b32_e32 v132, v134
	v_permlane16_swap_b32_e32 v133, v135
	v_addc_co_u32_e32 v137, vcc, 0, v131, vcc
	global_store_dwordx4 v[136:137], v[132:135], off sc1
	v_max_f32_e32 v0, v54, v54
	v_max_f32_e32 v0, 0, v0
	v_max_f32_e32 v132, v55, v55
	v_max_f32_e32 v132, 0, v132
	v_max_f32_e32 v133, v56, v56
	v_max_f32_e32 v134, v57, v57
	v_max_f32_e32 v133, 0, v133
	v_max_f32_e32 v134, 0, v134
	v_max_f32_e32 v135, v50, v50
	v_max_f32_e32 v138, v51, v51
	v_mul_f32_e32 v0, v0, v0
	v_mul_f32_e32 v132, v132, v132
	v_max_f32_e32 v135, 0, v135
	v_max_f32_e32 v138, 0, v138
	v_max_f32_e32 v139, v52, v52
	v_max_f32_e32 v140, v53, v53
	v_cvt_pk_bf16_f32 v132, v0, v132
	v_mul_f32_e32 v0, v133, v133
	v_mul_f32_e32 v133, v134, v134
	v_max_f32_e32 v139, 0, v139
	v_max_f32_e32 v140, 0, v140
	v_cvt_pk_bf16_f32 v133, v0, v133
	v_mul_f32_e32 v0, v135, v135
	v_mul_f32_e32 v134, v138, v138
	v_cvt_pk_bf16_f32 v134, v0, v134
	v_mul_f32_e32 v0, v139, v139
	v_mul_f32_e32 v135, v140, v140
	s_mov_b32 s2, 0x240000
	v_cvt_pk_bf16_f32 v135, v0, v135
	v_add_co_u32_e32 v138, vcc, s2, v130
	v_permlane16_swap_b32_e32 v132, v134
	v_permlane16_swap_b32_e32 v133, v135
	v_addc_co_u32_e32 v139, vcc, 0, v131, vcc
	global_store_dwordx4 v[138:139], v[132:135], off sc1
	v_max_f32_e32 v0, v46, v46
	v_max_f32_e32 v0, 0, v0
	v_max_f32_e32 v132, v47, v47
	v_max_f32_e32 v132, 0, v132
	v_max_f32_e32 v133, v48, v48
	v_max_f32_e32 v134, v49, v49
	v_max_f32_e32 v133, 0, v133
	v_max_f32_e32 v134, 0, v134
	v_max_f32_e32 v135, v42, v42
	v_max_f32_e32 v140, v43, v43
	v_mul_f32_e32 v0, v0, v0
	v_mul_f32_e32 v132, v132, v132
	v_max_f32_e32 v135, 0, v135
	v_max_f32_e32 v140, 0, v140
	v_max_f32_e32 v141, v44, v44
	v_max_f32_e32 v142, v45, v45
	v_cvt_pk_bf16_f32 v132, v0, v132
	v_mul_f32_e32 v0, v133, v133
	v_mul_f32_e32 v133, v134, v134
	v_max_f32_e32 v141, 0, v141
	v_max_f32_e32 v142, 0, v142
	v_cvt_pk_bf16_f32 v133, v0, v133
	v_mul_f32_e32 v0, v135, v135
	v_mul_f32_e32 v134, v140, v140
	v_cvt_pk_bf16_f32 v134, v0, v134
	v_mul_f32_e32 v0, v141, v141
	v_mul_f32_e32 v135, v142, v142
	s_mov_b32 s2, 0x280000
	v_cvt_pk_bf16_f32 v135, v0, v135
	v_add_co_u32_e32 v140, vcc, s2, v130
	v_permlane16_swap_b32_e32 v132, v134
	v_permlane16_swap_b32_e32 v133, v135
	v_addc_co_u32_e32 v141, vcc, 0, v131, vcc
	global_store_dwordx4 v[140:141], v[132:135], off sc1
	v_max_f32_e32 v0, v38, v38
	v_max_f32_e32 v0, 0, v0
	v_max_f32_e32 v132, v39, v39
	v_max_f32_e32 v132, 0, v132
	v_max_f32_e32 v133, v40, v40
	v_max_f32_e32 v134, v41, v41
	v_max_f32_e32 v133, 0, v133
	v_max_f32_e32 v134, 0, v134
	v_max_f32_e32 v135, v34, v34
	v_max_f32_e32 v142, v35, v35
	v_mul_f32_e32 v0, v0, v0
	v_mul_f32_e32 v132, v132, v132
	v_max_f32_e32 v135, 0, v135
	v_max_f32_e32 v142, 0, v142
	v_max_f32_e32 v143, v36, v36
	v_max_f32_e32 v144, v37, v37
	v_cvt_pk_bf16_f32 v132, v0, v132
	v_mul_f32_e32 v0, v133, v133
	v_mul_f32_e32 v133, v134, v134
	v_max_f32_e32 v143, 0, v143
	v_max_f32_e32 v144, 0, v144
	v_cvt_pk_bf16_f32 v133, v0, v133
	v_mul_f32_e32 v0, v135, v135
	v_mul_f32_e32 v134, v142, v142
	v_cvt_pk_bf16_f32 v134, v0, v134
	v_mul_f32_e32 v0, v143, v143
	v_mul_f32_e32 v135, v144, v144
	s_mov_b32 s2, 0x2c0000
	v_cvt_pk_bf16_f32 v135, v0, v135
	v_add_co_u32_e32 v142, vcc, s2, v130
	v_permlane16_swap_b32_e32 v132, v134
	v_permlane16_swap_b32_e32 v133, v135
	v_addc_co_u32_e32 v143, vcc, 0, v131, vcc
	v_max_f32_e32 v0, v30, v30
	v_max_f32_e32 v130, v31, v31
	global_store_dwordx4 v[142:143], v[132:135], off sc1
	v_max_f32_e32 v0, 0, v0
	v_max_f32_e32 v130, 0, v130
	v_max_f32_e32 v131, v32, v32
	v_max_f32_e32 v132, v33, v33
	v_max_f32_e32 v131, 0, v131
	v_max_f32_e32 v132, 0, v132
	v_max_f32_e32 v133, v26, v26
	v_max_f32_e32 v134, v27, v27
	v_mul_f32_e32 v0, v0, v0
	v_mul_f32_e32 v130, v130, v130
	v_max_f32_e32 v133, 0, v133
	v_max_f32_e32 v134, 0, v134
	v_max_f32_e32 v135, v28, v28
	v_max_f32_e32 v144, v29, v29
	v_cvt_pk_bf16_f32 v130, v0, v130
	v_mul_f32_e32 v0, v131, v131
	v_mul_f32_e32 v131, v132, v132
	v_max_f32_e32 v135, 0, v135
	v_max_f32_e32 v144, 0, v144
	v_cvt_pk_bf16_f32 v131, v0, v131
	v_mul_f32_e32 v0, v133, v133
	v_mul_f32_e32 v132, v134, v134
	v_cvt_pk_bf16_f32 v132, v0, v132
	v_mul_f32_e32 v0, v135, v135
	v_mul_f32_e32 v133, v144, v144
	v_cvt_pk_bf16_f32 v133, v0, v133
	v_permlane16_swap_b32_e32 v130, v132
	s_nop 0
	v_permlane16_swap_b32_e32 v131, v133
	global_store_dwordx4 v[136:137], v[130:133], off offset:256 sc1
	v_max_f32_e32 v0, v22, v22
	v_max_f32_e32 v0, 0, v0
	v_max_f32_e32 v130, v23, v23
	v_max_f32_e32 v130, 0, v130
	v_max_f32_e32 v131, v24, v24
	v_max_f32_e32 v132, v25, v25
	v_max_f32_e32 v131, 0, v131
	v_max_f32_e32 v132, 0, v132
	v_max_f32_e32 v133, v18, v18
	v_max_f32_e32 v134, v19, v19
	v_mul_f32_e32 v0, v0, v0
	v_mul_f32_e32 v130, v130, v130
	v_max_f32_e32 v133, 0, v133
	v_max_f32_e32 v134, 0, v134
	v_max_f32_e32 v135, v20, v20
	v_max_f32_e32 v136, v21, v21
	v_cvt_pk_bf16_f32 v130, v0, v130
	v_mul_f32_e32 v0, v131, v131
	v_mul_f32_e32 v131, v132, v132
	v_max_f32_e32 v135, 0, v135
	v_max_f32_e32 v136, 0, v136
	v_cvt_pk_bf16_f32 v131, v0, v131
	v_mul_f32_e32 v0, v133, v133
	v_mul_f32_e32 v132, v134, v134
	v_cvt_pk_bf16_f32 v132, v0, v132
	v_mul_f32_e32 v0, v135, v135
	v_mul_f32_e32 v133, v136, v136
	v_cvt_pk_bf16_f32 v133, v0, v133
	v_permlane16_swap_b32_e32 v130, v132
	s_nop 0
	v_permlane16_swap_b32_e32 v131, v133
	global_store_dwordx4 v[138:139], v[130:133], off offset:256 sc1
	v_max_f32_e32 v0, v14, v14
	v_max_f32_e32 v0, 0, v0
	v_max_f32_e32 v130, v15, v15
	v_max_f32_e32 v130, 0, v130
	v_max_f32_e32 v131, v16, v16
	v_max_f32_e32 v132, v17, v17
	v_max_f32_e32 v131, 0, v131
	v_max_f32_e32 v132, 0, v132
	v_max_f32_e32 v133, v10, v10
	v_max_f32_e32 v134, v11, v11
	v_mul_f32_e32 v0, v0, v0
	v_mul_f32_e32 v130, v130, v130
	v_max_f32_e32 v133, 0, v133
	v_max_f32_e32 v134, 0, v134
	v_max_f32_e32 v135, v12, v12
	v_max_f32_e32 v136, v13, v13
	v_cvt_pk_bf16_f32 v130, v0, v130
	v_mul_f32_e32 v0, v131, v131
	v_mul_f32_e32 v131, v132, v132
	v_max_f32_e32 v135, 0, v135
	v_max_f32_e32 v136, 0, v136
	v_cvt_pk_bf16_f32 v131, v0, v131
	v_mul_f32_e32 v0, v133, v133
	v_mul_f32_e32 v132, v134, v134
	v_cvt_pk_bf16_f32 v132, v0, v132
	v_mul_f32_e32 v0, v135, v135
	v_mul_f32_e32 v133, v136, v136
	v_cvt_pk_bf16_f32 v133, v0, v133
	v_permlane16_swap_b32_e32 v130, v132
	s_nop 0
	v_permlane16_swap_b32_e32 v131, v133
	global_store_dwordx4 v[140:141], v[130:133], off offset:256 sc1
	v_max_f32_e32 v0, v6, v6
	v_max_f32_e32 v0, 0, v0
	v_max_f32_e32 v130, v7, v7
	v_max_f32_e32 v130, 0, v130
	v_max_f32_e32 v131, v8, v8
	v_max_f32_e32 v132, v9, v9
	v_max_f32_e32 v131, 0, v131
	v_max_f32_e32 v132, 0, v132
	v_max_f32_e32 v133, v2, v2
	v_max_f32_e32 v134, v3, v3
	v_mul_f32_e32 v0, v0, v0
	v_mul_f32_e32 v130, v130, v130
	v_max_f32_e32 v133, 0, v133
	v_max_f32_e32 v134, 0, v134
	v_max_f32_e32 v135, v4, v4
	v_max_f32_e32 v136, v5, v5
	v_cvt_pk_bf16_f32 v130, v0, v130
	v_mul_f32_e32 v0, v131, v131
	v_mul_f32_e32 v131, v132, v132
	v_max_f32_e32 v135, 0, v135
	v_max_f32_e32 v136, 0, v136
	v_cvt_pk_bf16_f32 v131, v0, v131
	v_mul_f32_e32 v0, v133, v133
	v_mul_f32_e32 v132, v134, v134
	v_cvt_pk_bf16_f32 v132, v0, v132
	v_mul_f32_e32 v0, v135, v135
	v_mul_f32_e32 v133, v136, v136
	v_cvt_pk_bf16_f32 v133, v0, v133
	v_permlane16_swap_b32_e32 v130, v132
	s_nop 0
	v_permlane16_swap_b32_e32 v131, v133
	global_store_dwordx4 v[142:143], v[130:133], off offset:256 sc1
	s_mov_b64 s[24:25], 0

.LBB0_271:
	s_and_b64 vcc, exec, s[28:29]
	s_cbranch_vccz .LBB0_274
	s_cmp_eq_u32 s97, 1
	s_mov_b64 s[24:25], -1
	s_cbranch_scc0 .LBB0_274
	v_mov_b64_e32 v[130:131], s[22:23]
	v_mad_i64_i32 v[130:131], s[8:9], v198, s62, v[130:131]
	v_ashrrev_i32_e32 v201, 31, v200
	v_lshl_add_u64 v[132:133], v[200:201], 1, v[130:131]
	s_mov_b32 s2, 0x13405000
	v_add_co_u32_e32 v130, vcc, s2, v132
	s_mov_b64 s[8:9], 0x13405c00
	s_nop 0
	v_addc_co_u32_e32 v131, vcc, 0, v133, vcc
	global_load_dwordx2 v[142:143], v[130:131], off offset:3072
	v_lshl_add_u64 v[130:131], v[132:133], 0, s[8:9]
	s_mov_b32 s2, 0x13471000
	global_load_dwordx2 v[144:145], v[130:131], off offset:32
	v_add_co_u32_e32 v134, vcc, s2, v132
	s_mov_b32 s2, 0x134dd000
	s_nop 0
	v_addc_co_u32_e32 v135, vcc, 0, v133, vcc
	global_load_dwordx2 v[146:147], v[134:135], off offset:3072
	global_load_dwordx2 v[148:149], v[134:135], off offset:3104
	v_add_co_u32_e32 v136, vcc, s2, v132
	v_ashrrev_i32_e32 v199, 31, v198
	s_nop 0
	v_addc_co_u32_e32 v137, vcc, 0, v133, vcc
	global_load_dwordx2 v[150:151], v[136:137], off offset:3072
	global_load_dwordx2 v[152:153], v[136:137], off offset:3104
	v_readlane_b32 s8, v255, 21
	v_lshlrev_b64 v[138:139], 12, v[198:199]
	v_readlane_b32 s9, v255, 22
	s_mov_b32 s2, 0x13549000
	v_lshlrev_b32_e32 v0, 1, v230
	v_lshl_add_u64 v[138:139], s[8:9], 0, v[138:139]
	v_lshl_add_u64 v[138:139], s[94:95], 1, v[138:139]
	v_add_co_u32_e32 v154, vcc, s2, v132
	v_lshl_add_u64 v[156:157], v[138:139], 0, v[0:1]
	s_nop 0
	v_addc_co_u32_e32 v155, vcc, 0, v133, vcc
	global_load_dwordx2 v[158:159], v[130:131], off offset:256
	global_load_dwordx2 v[160:161], v[130:131], off offset:288
	global_load_dwordx2 v[162:163], v[134:135], off offset:3328
	global_load_dwordx2 v[164:165], v[134:135], off offset:3360
	global_load_dwordx2 v[140:141], v[136:137], off offset:3328
	global_load_dwordx2 v[138:139], v[136:137], off offset:3360
	global_load_dwordx2 v[166:167], v[154:155], off offset:3072
	global_load_dwordx2 v[168:169], v[154:155], off offset:3104
	s_nop 0
	global_load_dwordx2 v[136:137], v[154:155], off offset:3328
	global_load_dwordx2 v[134:135], v[154:155], off offset:3360
	v_lshlrev_b32_e32 v0, 1, v231
	v_lshl_add_u64 v[130:131], v[156:157], 0, v[0:1]
	s_mov_b32 s2, 0x10000
	s_mov_b64 s[24:25], 0
	s_waitcnt vmcnt(15)
	v_lshlrev_b32_e32 v0, 16, v142
	v_and_b32_e32 v142, 0xffff0000, v142
	v_lshlrev_b32_e32 v154, 16, v143
	v_and_b32_e32 v143, 0xffff0000, v143
	s_waitcnt vmcnt(14)
	v_lshlrev_b32_e32 v155, 16, v144
	v_and_b32_e32 v144, 0xffff0000, v144
	v_lshlrev_b32_e32 v156, 16, v145
	v_and_b32_e32 v145, 0xffff0000, v145
	v_mul_f32_e32 v0, v126, v0
	v_mul_f32_e32 v142, v127, v142
	v_mul_f32_e32 v154, v128, v154
	v_mul_f32_e32 v143, v129, v143
	v_mul_f32_e32 v155, v122, v155
	v_mul_f32_e32 v144, v123, v144
	v_mul_f32_e32 v156, v124, v156
	v_mul_f32_e32 v145, v125, v145
	s_waitcnt vmcnt(12)
	v_lshlrev_b32_e32 v172, 16, v149
	v_and_b32_e32 v149, 0xffff0000, v149
	v_cvt_pk_bf16_f32 v142, v0, v142
	v_cvt_pk_bf16_f32 v143, v154, v143
	v_cvt_pk_bf16_f32 v144, v155, v144
	v_cvt_pk_bf16_f32 v145, v156, v145
	v_mul_f32_e32 v172, v116, v172
	v_permlane16_swap_b32_e32 v142, v144
	v_permlane16_swap_b32_e32 v143, v145
	v_mul_f32_e32 v0, v117, v149
	global_store_dwordx4 v[130:131], v[142:145], off sc1
	v_cvt_pk_bf16_f32 v149, v172, v0
	s_waitcnt vmcnt(12)
	v_lshlrev_b32_e32 v0, 16, v150
	v_and_b32_e32 v142, 0xffff0000, v150
	v_mul_f32_e32 v0, v110, v0
	v_mul_f32_e32 v142, v111, v142
	v_cvt_pk_bf16_f32 v142, v0, v142
	v_lshlrev_b32_e32 v0, 16, v151
	v_and_b32_e32 v143, 0xffff0000, v151
	v_mul_f32_e32 v0, v112, v0
	v_mul_f32_e32 v143, v113, v143
	v_lshlrev_b32_e32 v157, 16, v146
	v_and_b32_e32 v146, 0xffff0000, v146
	v_lshlrev_b32_e32 v170, 16, v147
	v_and_b32_e32 v147, 0xffff0000, v147
	v_lshlrev_b32_e32 v171, 16, v148
	v_and_b32_e32 v148, 0xffff0000, v148
	v_cvt_pk_bf16_f32 v143, v0, v143
	s_waitcnt vmcnt(11)
	v_lshlrev_b32_e32 v0, 16, v152
	v_and_b32_e32 v144, 0xffff0000, v152
	v_mul_f32_e32 v157, v118, v157
	v_mul_f32_e32 v146, v119, v146
	v_mul_f32_e32 v170, v120, v170
	v_mul_f32_e32 v147, v121, v147
	v_mul_f32_e32 v171, v114, v171
	v_mul_f32_e32 v148, v115, v148
	v_mul_f32_e32 v0, v106, v0
	v_mul_f32_e32 v144, v107, v144
	v_cvt_pk_bf16_f32 v146, v157, v146
	v_cvt_pk_bf16_f32 v147, v170, v147
	v_cvt_pk_bf16_f32 v148, v171, v148
	v_add_co_u32_e32 v154, vcc, s2, v130
	v_cvt_pk_bf16_f32 v144, v0, v144
	v_lshlrev_b32_e32 v0, 16, v153
	v_and_b32_e32 v145, 0xffff0000, v153
	v_permlane16_swap_b32_e32 v146, v148
	v_permlane16_swap_b32_e32 v147, v149
	v_addc_co_u32_e32 v155, vcc, 0, v131, vcc
	v_mul_f32_e32 v0, v108, v0
	v_mul_f32_e32 v145, v109, v145
	global_store_dwordx4 v[154:155], v[146:149], off sc1
	v_cvt_pk_bf16_f32 v145, v0, v145
	v_permlane16_swap_b32_e32 v142, v144
	v_add_co_u32_e32 v146, vcc, s27, v130
	v_permlane16_swap_b32_e32 v143, v145
	s_nop 0
	v_addc_co_u32_e32 v147, vcc, 0, v131, vcc
	global_store_dwordx4 v[146:147], v[142:145], off sc1
	s_waitcnt vmcnt(6)
	v_lshlrev_b32_e32 v0, 16, v166
	v_mul_f32_e32 v0, v102, v0
	v_and_b32_e32 v142, 0xffff0000, v166
	v_mul_f32_e32 v142, v103, v142
	v_cvt_pk_bf16_f32 v142, v0, v142
	v_lshlrev_b32_e32 v0, 16, v167
	v_and_b32_e32 v143, 0xffff0000, v167
	v_mul_f32_e32 v0, v104, v0
	v_mul_f32_e32 v143, v105, v143
	v_cvt_pk_bf16_f32 v143, v0, v143
	s_waitcnt vmcnt(5)
	v_lshlrev_b32_e32 v0, 16, v168
	v_and_b32_e32 v144, 0xffff0000, v168
	v_mul_f32_e32 v0, v98, v0
	v_mul_f32_e32 v144, v99, v144
	v_cvt_pk_bf16_f32 v144, v0, v144
	v_lshlrev_b32_e32 v0, 16, v169
	v_and_b32_e32 v145, 0xffff0000, v169
	v_mul_f32_e32 v0, v100, v0
	v_mul_f32_e32 v145, v101, v145
	s_mov_b32 s2, 0x30000
	v_cvt_pk_bf16_f32 v145, v0, v145
	v_add_co_u32_e32 v148, vcc, s2, v130
	v_permlane16_swap_b32_e32 v142, v144
	v_permlane16_swap_b32_e32 v143, v145
	v_addc_co_u32_e32 v149, vcc, 0, v131, vcc
	global_store_dwordx4 v[148:149], v[142:145], off sc1
	v_lshlrev_b32_e32 v0, 16, v158
	v_mul_f32_e32 v0, v94, v0
	v_and_b32_e32 v142, 0xffff0000, v158
	v_mul_f32_e32 v142, v95, v142
	v_cvt_pk_bf16_f32 v142, v0, v142
	v_lshlrev_b32_e32 v0, 16, v159
	v_and_b32_e32 v143, 0xffff0000, v159
	v_mul_f32_e32 v0, v96, v0
	v_mul_f32_e32 v143, v97, v143
	v_cvt_pk_bf16_f32 v143, v0, v143
	v_lshlrev_b32_e32 v0, 16, v160
	v_and_b32_e32 v144, 0xffff0000, v160
	v_mul_f32_e32 v0, v90, v0
	v_mul_f32_e32 v144, v91, v144
	v_cvt_pk_bf16_f32 v144, v0, v144
	v_lshlrev_b32_e32 v0, 16, v161
	v_and_b32_e32 v145, 0xffff0000, v161
	v_mul_f32_e32 v0, v92, v0
	v_mul_f32_e32 v145, v93, v145
	v_cvt_pk_bf16_f32 v145, v0, v145
	v_permlane16_swap_b32_e32 v142, v144
	s_nop 0
	v_permlane16_swap_b32_e32 v143, v145
	global_store_dwordx4 v[130:131], v[142:145], off offset:256 sc1
	v_lshlrev_b32_e32 v0, 16, v162
	v_mul_f32_e32 v0, v86, v0
	v_and_b32_e32 v142, 0xffff0000, v162
	v_mul_f32_e32 v142, v87, v142
	v_cvt_pk_bf16_f32 v142, v0, v142
	v_lshlrev_b32_e32 v0, 16, v163
	v_and_b32_e32 v143, 0xffff0000, v163
	v_mul_f32_e32 v0, v88, v0
	v_mul_f32_e32 v143, v89, v143
	v_cvt_pk_bf16_f32 v143, v0, v143
	v_lshlrev_b32_e32 v0, 16, v164
	v_and_b32_e32 v144, 0xffff0000, v164
	v_mul_f32_e32 v0, v82, v0
	v_mul_f32_e32 v144, v83, v144
	v_cvt_pk_bf16_f32 v144, v0, v144
	v_lshlrev_b32_e32 v0, 16, v165
	v_and_b32_e32 v145, 0xffff0000, v165
	v_mul_f32_e32 v0, v84, v0
	v_mul_f32_e32 v145, v85, v145
	v_cvt_pk_bf16_f32 v145, v0, v145
	v_lshlrev_b32_e32 v0, 16, v140
	v_and_b32_e32 v140, 0xffff0000, v140
	v_mul_f32_e32 v0, v78, v0
	v_mul_f32_e32 v140, v79, v140
	v_cvt_pk_bf16_f32 v140, v0, v140
	v_lshlrev_b32_e32 v0, 16, v141
	v_and_b32_e32 v141, 0xffff0000, v141
	v_mul_f32_e32 v0, v80, v0
	v_mul_f32_e32 v141, v81, v141
	v_cvt_pk_bf16_f32 v141, v0, v141
	v_lshlrev_b32_e32 v0, 16, v138
	v_and_b32_e32 v138, 0xffff0000, v138
	v_permlane16_swap_b32_e32 v142, v144
	v_permlane16_swap_b32_e32 v143, v145
	v_mul_f32_e32 v0, v74, v0
	v_mul_f32_e32 v138, v75, v138
	global_store_dwordx4 v[154:155], v[142:145], off offset:256 sc1
	s_mov_b32 s2, 0x13765000
	s_nop 0
	v_cvt_pk_bf16_f32 v142, v0, v138
	v_lshlrev_b32_e32 v0, 16, v139
	v_and_b32_e32 v138, 0xffff0000, v139
	v_mul_f32_e32 v0, v76, v0
	v_mul_f32_e32 v138, v77, v138
	v_cvt_pk_bf16_f32 v143, v0, v138
	s_waitcnt vmcnt(7)
	v_lshlrev_b32_e32 v0, 16, v136
	v_and_b32_e32 v136, 0xffff0000, v136
	v_mul_f32_e32 v0, v70, v0
	v_mul_f32_e32 v136, v71, v136
	v_cvt_pk_bf16_f32 v136, v0, v136
	v_lshlrev_b32_e32 v0, 16, v137
	v_and_b32_e32 v137, 0xffff0000, v137
	v_mul_f32_e32 v0, v72, v0
	v_mul_f32_e32 v137, v73, v137
	v_cvt_pk_bf16_f32 v137, v0, v137
	s_waitcnt vmcnt(6)
	v_lshlrev_b32_e32 v0, 16, v134
	v_and_b32_e32 v134, 0xffff0000, v134
	v_mul_f32_e32 v0, v66, v0
	v_mul_f32_e32 v134, v67, v134
	v_cvt_pk_bf16_f32 v138, v0, v134
	v_lshlrev_b32_e32 v0, 16, v135
	v_and_b32_e32 v134, 0xffff0000, v135
	v_mul_f32_e32 v0, v68, v0
	v_mul_f32_e32 v134, v69, v134
	v_cvt_pk_bf16_f32 v139, v0, v134
	v_permlane16_swap_b32_e32 v140, v142
	v_permlane16_swap_b32_e32 v141, v143
	v_permlane16_swap_b32_e32 v136, v138
	v_permlane16_swap_b32_e32 v137, v139
	v_add_co_u32_e32 v134, vcc, s2, v132
	global_store_dwordx4 v[146:147], v[140:143], off offset:256 sc1
	global_store_dwordx4 v[148:149], v[136:139], off offset:256 sc1
	v_addc_co_u32_e32 v135, vcc, 0, v133, vcc
	global_load_dwordx2 v[136:137], v[134:135], off offset:3072
	global_load_dwordx2 v[138:139], v[134:135], off offset:3104
	s_mov_b32 s2, 0x137d1000
	v_add_co_u32_e32 v140, vcc, s2, v132
	s_mov_b32 s2, 0x1383d000
	s_nop 0
	v_addc_co_u32_e32 v141, vcc, 0, v133, vcc
	global_load_dwordx2 v[142:143], v[140:141], off offset:3072
	global_load_dwordx2 v[144:145], v[140:141], off offset:3104
	v_add_co_u32_e32 v146, vcc, s2, v132
	s_mov_b32 s2, 0x138a9000
	s_nop 0
	v_addc_co_u32_e32 v147, vcc, 0, v133, vcc
	global_load_dwordx2 v[148:149], v[146:147], off offset:3072
	global_load_dwordx2 v[150:151], v[146:147], off offset:3104
	v_add_co_u32_e32 v132, vcc, s2, v132
	s_mov_b32 s2, 0x80000
	s_nop 0
	v_addc_co_u32_e32 v133, vcc, 0, v133, vcc
	global_load_dwordx2 v[152:153], v[134:135], off offset:3328
	global_load_dwordx2 v[154:155], v[134:135], off offset:3360
	global_load_dwordx2 v[156:157], v[140:141], off offset:3328
	s_nop 0
	global_load_dwordx2 v[140:141], v[140:141], off offset:3360
	s_nop 0
	global_load_dwordx2 v[158:159], v[146:147], off offset:3328
	s_nop 0
	global_load_dwordx2 v[146:147], v[146:147], off offset:3360
	s_nop 0
	global_load_dwordx2 v[160:161], v[132:133], off offset:3072
	global_load_dwordx2 v[162:163], v[132:133], off offset:3104
	global_load_dwordx2 v[164:165], v[132:133], off offset:3328
	s_nop 0
	global_load_dwordx2 v[132:133], v[132:133], off offset:3360
	s_waitcnt vmcnt(15)
	v_lshlrev_b32_e32 v0, 16, v136
	v_and_b32_e32 v134, 0xffff0000, v136
	v_mul_f32_e32 v0, v62, v0
	v_mul_f32_e32 v134, v63, v134
	v_cvt_pk_bf16_f32 v134, v0, v134
	v_lshlrev_b32_e32 v0, 16, v137
	v_and_b32_e32 v135, 0xffff0000, v137
	v_mul_f32_e32 v0, v64, v0
	v_mul_f32_e32 v135, v65, v135
	v_cvt_pk_bf16_f32 v135, v0, v135
	s_waitcnt vmcnt(14)
	v_lshlrev_b32_e32 v0, 16, v138
	v_and_b32_e32 v136, 0xffff0000, v138
	v_mul_f32_e32 v0, v58, v0
	v_mul_f32_e32 v136, v59, v136
	v_cvt_pk_bf16_f32 v136, v0, v136
	v_lshlrev_b32_e32 v0, 16, v139
	v_and_b32_e32 v137, 0xffff0000, v139
	v_mul_f32_e32 v0, v60, v0
	v_mul_f32_e32 v137, v61, v137
	v_cvt_pk_bf16_f32 v137, v0, v137
	v_add_co_u32_e32 v138, vcc, s2, v130
	v_permlane16_swap_b32_e32 v134, v136
	v_permlane16_swap_b32_e32 v135, v137
	v_addc_co_u32_e32 v139, vcc, 0, v131, vcc
	global_store_dwordx4 v[138:139], v[134:137], off sc1
	s_waitcnt vmcnt(14)
	v_lshlrev_b32_e32 v0, 16, v142
	v_mul_f32_e32 v0, v54, v0
	v_and_b32_e32 v134, 0xffff0000, v142
	v_mul_f32_e32 v134, v55, v134
	v_cvt_pk_bf16_f32 v134, v0, v134
	v_lshlrev_b32_e32 v0, 16, v143
	v_and_b32_e32 v135, 0xffff0000, v143
	v_mul_f32_e32 v0, v56, v0
	v_mul_f32_e32 v135, v57, v135
	v_cvt_pk_bf16_f32 v135, v0, v135
	s_waitcnt vmcnt(13)
	v_lshlrev_b32_e32 v0, 16, v144
	v_and_b32_e32 v136, 0xffff0000, v144
	v_mul_f32_e32 v0, v50, v0
	v_mul_f32_e32 v136, v51, v136
	v_cvt_pk_bf16_f32 v136, v0, v136
	v_lshlrev_b32_e32 v0, 16, v145
	v_and_b32_e32 v137, 0xffff0000, v145
	v_mul_f32_e32 v0, v52, v0
	v_mul_f32_e32 v137, v53, v137
	s_mov_b32 s2, 0x90000
	v_cvt_pk_bf16_f32 v137, v0, v137
	v_add_co_u32_e32 v142, vcc, s2, v130
	v_permlane16_swap_b32_e32 v134, v136
	v_permlane16_swap_b32_e32 v135, v137
	v_addc_co_u32_e32 v143, vcc, 0, v131, vcc
	global_store_dwordx4 v[142:143], v[134:137], off sc1
	s_waitcnt vmcnt(13)
	v_lshlrev_b32_e32 v0, 16, v148
	v_mul_f32_e32 v0, v46, v0
	v_and_b32_e32 v134, 0xffff0000, v148
	v_mul_f32_e32 v134, v47, v134
	v_cvt_pk_bf16_f32 v134, v0, v134
	v_lshlrev_b32_e32 v0, 16, v149
	v_and_b32_e32 v135, 0xffff0000, v149
	v_mul_f32_e32 v0, v48, v0
	v_mul_f32_e32 v135, v49, v135
	v_cvt_pk_bf16_f32 v135, v0, v135
	s_waitcnt vmcnt(12)
	v_lshlrev_b32_e32 v0, 16, v150
	v_and_b32_e32 v136, 0xffff0000, v150
	v_mul_f32_e32 v0, v42, v0
	v_mul_f32_e32 v136, v43, v136
	v_cvt_pk_bf16_f32 v136, v0, v136
	v_lshlrev_b32_e32 v0, 16, v151
	v_and_b32_e32 v137, 0xffff0000, v151
	v_mul_f32_e32 v0, v44, v0
	v_mul_f32_e32 v137, v45, v137
	s_mov_b32 s2, 0xa0000
	v_cvt_pk_bf16_f32 v137, v0, v137
	v_add_co_u32_e32 v144, vcc, s2, v130
	v_permlane16_swap_b32_e32 v134, v136
	v_permlane16_swap_b32_e32 v135, v137
	v_addc_co_u32_e32 v145, vcc, 0, v131, vcc
	global_store_dwordx4 v[144:145], v[134:137], off sc1
	s_waitcnt vmcnt(6)
	v_lshlrev_b32_e32 v0, 16, v160
	v_mul_f32_e32 v0, v38, v0
	v_and_b32_e32 v134, 0xffff0000, v160
	v_mul_f32_e32 v134, v39, v134
	v_cvt_pk_bf16_f32 v134, v0, v134
	v_lshlrev_b32_e32 v0, 16, v161
	v_and_b32_e32 v135, 0xffff0000, v161
	v_mul_f32_e32 v0, v40, v0
	v_mul_f32_e32 v135, v41, v135
	v_cvt_pk_bf16_f32 v135, v0, v135
	s_waitcnt vmcnt(5)
	v_lshlrev_b32_e32 v0, 16, v162
	v_and_b32_e32 v136, 0xffff0000, v162
	v_mul_f32_e32 v0, v34, v0
	v_mul_f32_e32 v136, v35, v136
	v_cvt_pk_bf16_f32 v136, v0, v136
	v_lshlrev_b32_e32 v0, 16, v163
	v_and_b32_e32 v137, 0xffff0000, v163
	v_mul_f32_e32 v0, v36, v0
	v_mul_f32_e32 v137, v37, v137
	s_mov_b32 s2, 0xb0000
	v_cvt_pk_bf16_f32 v137, v0, v137
	v_add_co_u32_e32 v148, vcc, s2, v130
	v_lshlrev_b32_e32 v0, 16, v152
	v_and_b32_e32 v130, 0xffff0000, v152
	v_permlane16_swap_b32_e32 v134, v136
	v_permlane16_swap_b32_e32 v135, v137
	v_addc_co_u32_e32 v149, vcc, 0, v131, vcc
	v_mul_f32_e32 v0, v30, v0
	v_mul_f32_e32 v130, v31, v130
	global_store_dwordx4 v[148:149], v[134:137], off sc1
	s_waitcnt vmcnt(5)
	v_and_b32_e32 v131, 0xffff0000, v165
	v_mul_f32_e32 v131, v9, v131
	v_cvt_pk_bf16_f32 v134, v0, v130
	v_lshlrev_b32_e32 v0, 16, v153
	v_and_b32_e32 v130, 0xffff0000, v153
	v_mul_f32_e32 v0, v32, v0
	v_mul_f32_e32 v130, v33, v130
	v_cvt_pk_bf16_f32 v135, v0, v130
	v_lshlrev_b32_e32 v0, 16, v154
	v_and_b32_e32 v130, 0xffff0000, v154
	v_mul_f32_e32 v0, v26, v0
	v_mul_f32_e32 v130, v27, v130
	v_cvt_pk_bf16_f32 v136, v0, v130
	v_lshlrev_b32_e32 v0, 16, v155
	v_and_b32_e32 v130, 0xffff0000, v155
	v_mul_f32_e32 v0, v28, v0
	v_mul_f32_e32 v130, v29, v130
	v_cvt_pk_bf16_f32 v137, v0, v130
	v_lshlrev_b32_e32 v0, 16, v156
	v_and_b32_e32 v130, 0xffff0000, v156
	v_permlane16_swap_b32_e32 v134, v136
	v_permlane16_swap_b32_e32 v135, v137
	v_mul_f32_e32 v0, v22, v0
	v_mul_f32_e32 v130, v23, v130
	global_store_dwordx4 v[138:139], v[134:137], off offset:256 sc1
	s_nop 1
	v_cvt_pk_bf16_f32 v134, v0, v130
	v_lshlrev_b32_e32 v0, 16, v157
	v_and_b32_e32 v130, 0xffff0000, v157
	v_mul_f32_e32 v0, v24, v0
	v_mul_f32_e32 v130, v25, v130
	v_cvt_pk_bf16_f32 v135, v0, v130
	v_lshlrev_b32_e32 v0, 16, v140
	v_and_b32_e32 v130, 0xffff0000, v140
	v_mul_f32_e32 v0, v18, v0
	v_mul_f32_e32 v130, v19, v130
	v_cvt_pk_bf16_f32 v136, v0, v130
	v_lshlrev_b32_e32 v0, 16, v141
	v_and_b32_e32 v130, 0xffff0000, v141
	v_mul_f32_e32 v0, v20, v0
	v_mul_f32_e32 v130, v21, v130
	v_cvt_pk_bf16_f32 v137, v0, v130
	v_lshlrev_b32_e32 v0, 16, v158
	v_and_b32_e32 v130, 0xffff0000, v158
	v_permlane16_swap_b32_e32 v134, v136
	v_permlane16_swap_b32_e32 v135, v137
	v_mul_f32_e32 v0, v14, v0
	v_mul_f32_e32 v130, v15, v130
	global_store_dwordx4 v[142:143], v[134:137], off offset:256 sc1
	s_nop 1
	v_cvt_pk_bf16_f32 v134, v0, v130
	v_lshlrev_b32_e32 v0, 16, v159
	v_and_b32_e32 v130, 0xffff0000, v159
	v_mul_f32_e32 v0, v16, v0
	v_mul_f32_e32 v130, v17, v130
	v_cvt_pk_bf16_f32 v135, v0, v130
	v_lshlrev_b32_e32 v0, 16, v146
	v_and_b32_e32 v130, 0xffff0000, v146
	v_mul_f32_e32 v0, v10, v0
	v_mul_f32_e32 v130, v11, v130
	v_cvt_pk_bf16_f32 v136, v0, v130
	v_lshlrev_b32_e32 v0, 16, v147
	v_and_b32_e32 v130, 0xffff0000, v147
	v_mul_f32_e32 v0, v12, v0
	v_mul_f32_e32 v130, v13, v130
	v_cvt_pk_bf16_f32 v137, v0, v130
	v_lshlrev_b32_e32 v0, 16, v164
	v_and_b32_e32 v130, 0xffff0000, v164
	v_mul_f32_e32 v0, v6, v0
	v_mul_f32_e32 v130, v7, v130
	v_cvt_pk_bf16_f32 v130, v0, v130
	v_lshlrev_b32_e32 v0, 16, v165
	v_mul_f32_e32 v0, v8, v0
	v_cvt_pk_bf16_f32 v131, v0, v131
	s_waitcnt vmcnt(6)
	v_lshlrev_b32_e32 v0, 16, v132
	v_and_b32_e32 v132, 0xffff0000, v132
	v_mul_f32_e32 v0, v2, v0
	v_mul_f32_e32 v132, v3, v132
	v_cvt_pk_bf16_f32 v132, v0, v132
	v_lshlrev_b32_e32 v0, 16, v133
	v_and_b32_e32 v133, 0xffff0000, v133
	v_mul_f32_e32 v0, v4, v0
	v_mul_f32_e32 v133, v5, v133
	v_cvt_pk_bf16_f32 v133, v0, v133
	v_permlane16_swap_b32_e32 v134, v136
	v_permlane16_swap_b32_e32 v135, v137
	v_permlane16_swap_b32_e32 v130, v132
	v_permlane16_swap_b32_e32 v131, v133
	global_store_dwordx4 v[144:145], v[134:137], off offset:256 sc1
	global_store_dwordx4 v[148:149], v[130:133], off offset:256 sc1

.LBB0_281:
	v_lshlrev_b64 v[150:151], 2, v[200:201]
	v_lshl_add_u64 v[204:205], v[148:149], 0, v[150:151]
	v_lshl_add_u64 v[202:203], v[146:147], 0, v[150:151]
	global_load_dwordx4 v[146:149], v[204:205], off
	v_add_co_u32_e32 v150, vcc, s27, v204
	s_nop 1
	v_addc_co_u32_e32 v151, vcc, 0, v205, vcc
	v_add_co_u32_e32 v166, vcc, s12, v204
	s_nop 1
	v_addc_co_u32_e32 v167, vcc, 0, v205, vcc
	v_add_co_u32_e32 v174, vcc, s37, v204
	global_load_dwordx4 v[162:165], v[166:167], off
	s_nop 0
	v_addc_co_u32_e32 v175, vcc, 0, v205, vcc
	global_load_dwordx4 v[170:173], v[174:175], off
	s_waitcnt vmcnt(2)
	v_pk_fma_f32 v[178:179], v[126:127], v[142:143], v[146:147]
	v_pk_fma_f32 v[180:181], v[128:129], v[144:145], v[148:149]
	global_load_dwordx4 v[146:149], v[204:205], off offset:64
	s_waitcnt vmcnt(2)
	v_pk_fma_f32 v[236:237], v[110:111], v[142:143], v[162:163]
	v_pk_fma_f32 v[238:239], v[112:113], v[144:145], v[164:165]
	global_load_dwordx4 v[162:165], v[166:167], off offset:64
	s_waitcnt vmcnt(2)
	v_pk_fma_f32 v[244:245], v[102:103], v[142:143], v[170:171]
	v_pk_fma_f32 v[246:247], v[104:105], v[144:145], v[172:173]
	global_load_dwordx4 v[170:173], v[174:175], off offset:64
	s_waitcnt vmcnt(2)
	v_pk_fma_f32 v[182:183], v[122:123], v[138:139], v[146:147]
	v_pk_fma_f32 v[184:185], v[124:125], v[140:141], v[148:149]
	global_load_dwordx4 v[146:149], v[204:205], off offset:512
	s_waitcnt vmcnt(2)
	v_pk_fma_f32 v[240:241], v[106:107], v[138:139], v[162:163]
	v_pk_fma_f32 v[242:243], v[108:109], v[140:141], v[164:165]
	global_load_dwordx4 v[162:165], v[166:167], off offset:512
	s_waitcnt vmcnt(2)
	v_pk_fma_f32 v[248:249], v[98:99], v[138:139], v[170:171]
	v_pk_fma_f32 v[250:251], v[100:101], v[140:141], v[172:173]
	global_load_dwordx4 v[170:173], v[174:175], off offset:512
	s_waitcnt vmcnt(2)
	v_pk_fma_f32 v[154:155], v[94:95], v[134:135], v[146:147]
	v_pk_fma_f32 v[156:157], v[96:97], v[136:137], v[148:149]
	global_load_dwordx4 v[146:149], v[204:205], off offset:576
	s_waitcnt vmcnt(2)
	v_pk_fma_f32 v[162:163], v[78:79], v[134:135], v[162:163]
	global_load_dwordx4 v[174:177], v[174:175], off offset:576
	v_pk_fma_f32 v[164:165], v[80:81], v[136:137], v[164:165]
	global_load_dwordx4 v[166:169], v[166:167], off offset:576
	s_waitcnt vmcnt(3)
	v_pk_fma_f32 v[170:171], v[70:71], v[134:135], v[170:171]
	v_pk_fma_f32 v[172:173], v[72:73], v[136:137], v[172:173]
	s_waitcnt vmcnt(2)
	v_pk_fma_f32 v[158:159], v[90:91], v[130:131], v[146:147]
	v_pk_fma_f32 v[160:161], v[92:93], v[132:133], v[148:149]
	global_load_dwordx4 v[146:149], v[150:151], off
	s_waitcnt vmcnt(2)
	v_pk_fma_f32 v[174:175], v[66:67], v[130:131], v[174:175]
	v_pk_fma_f32 v[176:177], v[68:69], v[132:133], v[176:177]
	s_waitcnt vmcnt(1)
	v_pk_fma_f32 v[166:167], v[74:75], v[130:131], v[166:167]
	v_pk_fma_f32 v[168:169], v[76:77], v[132:133], v[168:169]
	s_waitcnt vmcnt(0)
	v_pk_fma_f32 v[186:187], v[118:119], v[142:143], v[146:147]
	v_pk_fma_f32 v[188:189], v[120:121], v[144:145], v[148:149]
	global_load_dwordx4 v[146:149], v[150:151], off offset:64
	s_waitcnt vmcnt(0)
	v_pk_fma_f32 v[232:233], v[114:115], v[138:139], v[146:147]
	v_pk_fma_f32 v[234:235], v[116:117], v[140:141], v[148:149]
	global_load_dwordx4 v[146:149], v[150:151], off offset:512
	s_waitcnt vmcnt(0)
	v_pk_fma_f32 v[146:147], v[86:87], v[134:135], v[146:147]
	global_load_dwordx4 v[150:153], v[150:151], off offset:576
	s_nop 0
	global_store_dwordx4 v[202:203], v[178:181], off sc1
	global_store_dwordx4 v[202:203], v[182:185], off offset:64 sc1
	v_pk_fma_f32 v[148:149], v[88:89], v[136:137], v[148:149]
	v_add_co_u32_e32 v178, vcc, s27, v202
	s_waitcnt vmcnt(2)
	v_pk_fma_f32 v[150:151], v[82:83], v[130:131], v[150:151]
	v_addc_co_u32_e32 v179, vcc, 0, v203, vcc
	v_add_co_u32_e32 v180, vcc, s12, v202
	v_pk_fma_f32 v[152:153], v[84:85], v[132:133], v[152:153]
	s_nop 0
	v_addc_co_u32_e32 v181, vcc, 0, v203, vcc
	v_add_co_u32_e32 v182, vcc, s37, v202
	global_store_dwordx4 v[178:179], v[186:189], off sc1
	global_store_dwordx4 v[178:179], v[232:235], off offset:64 sc1
	v_addc_co_u32_e32 v183, vcc, 0, v203, vcc
	global_store_dwordx4 v[180:181], v[236:239], off sc1
	global_store_dwordx4 v[180:181], v[240:243], off offset:64 sc1
	global_store_dwordx4 v[182:183], v[244:247], off sc1
	global_store_dwordx4 v[182:183], v[248:251], off offset:64 sc1
	global_store_dwordx4 v[202:203], v[154:157], off offset:512 sc1
	global_store_dwordx4 v[202:203], v[158:161], off offset:576 sc1
	global_store_dwordx4 v[178:179], v[146:149], off offset:512 sc1
	global_store_dwordx4 v[178:179], v[150:153], off offset:576 sc1
	global_store_dwordx4 v[180:181], v[162:165], off offset:512 sc1
	global_store_dwordx4 v[180:181], v[166:169], off offset:576 sc1
	global_store_dwordx4 v[182:183], v[170:173], off offset:512 sc1
	global_store_dwordx4 v[182:183], v[174:177], off offset:576 sc1
	v_add_co_u32_e32 v150, vcc, s69, v204
	s_nop 1
	v_addc_co_u32_e32 v151, vcc, 0, v205, vcc
	v_add_co_u32_e32 v158, vcc, s38, v204
	global_load_dwordx4 v[146:149], v[150:151], off
	s_nop 0
	v_addc_co_u32_e32 v159, vcc, 0, v205, vcc
	v_add_co_u32_e32 v174, vcc, s36, v204
	global_load_dwordx4 v[154:157], v[158:159], off
	s_nop 0
	v_addc_co_u32_e32 v175, vcc, 0, v205, vcc
	v_add_co_u32_e32 v204, vcc, s39, v204
	global_load_dwordx4 v[170:173], v[174:175], off
	s_nop 0
	v_addc_co_u32_e32 v205, vcc, 0, v205, vcc
	global_load_dwordx4 v[236:239], v[204:205], off
	s_waitcnt vmcnt(3)
	v_pk_fma_f32 v[186:187], v[62:63], v[142:143], v[146:147]
	v_pk_fma_f32 v[188:189], v[64:65], v[144:145], v[148:149]
	global_load_dwordx4 v[146:149], v[150:151], off offset:64
	s_waitcnt vmcnt(3)
	v_pk_fma_f32 v[162:163], v[54:55], v[142:143], v[154:155]
	v_pk_fma_f32 v[164:165], v[56:57], v[144:145], v[156:157]
	global_load_dwordx4 v[154:157], v[158:159], off offset:64
	s_waitcnt vmcnt(3)
	v_pk_fma_f32 v[178:179], v[46:47], v[142:143], v[170:171]
	v_pk_fma_f32 v[180:181], v[48:49], v[144:145], v[172:173]
	global_load_dwordx4 v[170:173], v[174:175], off offset:64
	s_waitcnt vmcnt(3)
	v_pk_fma_f32 v[142:143], v[38:39], v[142:143], v[236:237]
	v_pk_fma_f32 v[144:145], v[40:41], v[144:145], v[238:239]
	global_load_dwordx4 v[236:239], v[204:205], off offset:64
	s_waitcnt vmcnt(3)
	v_pk_fma_f32 v[232:233], v[58:59], v[138:139], v[146:147]
	v_pk_fma_f32 v[234:235], v[60:61], v[140:141], v[148:149]
	global_load_dwordx4 v[146:149], v[150:151], off offset:512
	s_waitcnt vmcnt(3)
	v_pk_fma_f32 v[166:167], v[50:51], v[138:139], v[154:155]
	v_pk_fma_f32 v[168:169], v[52:53], v[140:141], v[156:157]
	global_load_dwordx4 v[154:157], v[158:159], off offset:512
	s_waitcnt vmcnt(3)
	v_pk_fma_f32 v[182:183], v[42:43], v[138:139], v[170:171]
	v_pk_fma_f32 v[184:185], v[44:45], v[140:141], v[172:173]
	global_load_dwordx4 v[170:173], v[174:175], off offset:512
	s_waitcnt vmcnt(3)
	v_pk_fma_f32 v[138:139], v[34:35], v[138:139], v[236:237]
	v_pk_fma_f32 v[140:141], v[36:37], v[140:141], v[238:239]
	global_load_dwordx4 v[236:239], v[204:205], off offset:512
	s_waitcnt vmcnt(3)
	v_pk_fma_f32 v[146:147], v[30:31], v[134:135], v[146:147]
	v_pk_fma_f32 v[148:149], v[32:33], v[136:137], v[148:149]
	global_load_dwordx4 v[150:153], v[150:151], off offset:576
	s_waitcnt vmcnt(3)
	v_pk_fma_f32 v[154:155], v[22:23], v[134:135], v[154:155]
	v_pk_fma_f32 v[156:157], v[24:25], v[136:137], v[156:157]
	global_load_dwordx4 v[158:161], v[158:159], off offset:576
	s_waitcnt vmcnt(3)
	v_pk_fma_f32 v[170:171], v[14:15], v[134:135], v[170:171]
	v_pk_fma_f32 v[172:173], v[16:17], v[136:137], v[172:173]
	global_load_dwordx4 v[174:177], v[174:175], off offset:576
	s_waitcnt vmcnt(3)
	v_pk_fma_f32 v[134:135], v[6:7], v[134:135], v[236:237]
	v_pk_fma_f32 v[136:137], v[8:9], v[136:137], v[238:239]
	global_load_dwordx4 v[236:239], v[204:205], off offset:576
	v_add_co_u32_e32 v204, vcc, s69, v202
	s_waitcnt vmcnt(3)
	v_pk_fma_f32 v[150:151], v[26:27], v[130:131], v[150:151]
	v_addc_co_u32_e32 v205, vcc, 0, v203, vcc
	global_store_dwordx4 v[204:205], v[186:189], off sc1
	global_store_dwordx4 v[204:205], v[232:235], off offset:64 sc1
	v_pk_fma_f32 v[152:153], v[28:29], v[132:133], v[152:153]
	v_add_co_u32_e32 v186, vcc, s38, v202
	s_waitcnt vmcnt(4)
	v_pk_fma_f32 v[158:159], v[18:19], v[130:131], v[158:159]
	v_addc_co_u32_e32 v187, vcc, 0, v203, vcc
	global_store_dwordx4 v[186:187], v[162:165], off sc1
	global_store_dwordx4 v[186:187], v[166:169], off offset:64 sc1
	v_pk_fma_f32 v[160:161], v[20:21], v[132:133], v[160:161]
	v_add_co_u32_e32 v162, vcc, s36, v202
	s_waitcnt vmcnt(5)
	v_pk_fma_f32 v[174:175], v[10:11], v[130:131], v[174:175]
	v_addc_co_u32_e32 v163, vcc, 0, v203, vcc
	v_add_co_u32_e32 v164, vcc, s39, v202
	v_pk_fma_f32 v[176:177], v[12:13], v[132:133], v[176:177]
	s_nop 0
	v_addc_co_u32_e32 v165, vcc, 0, v203, vcc
	s_waitcnt vmcnt(4)
	v_pk_fma_f32 v[130:131], v[2:3], v[130:131], v[236:237]
	v_pk_fma_f32 v[132:133], v[4:5], v[132:133], v[238:239]
	global_store_dwordx4 v[162:163], v[178:181], off sc1
	global_store_dwordx4 v[162:163], v[182:185], off offset:64 sc1
	global_store_dwordx4 v[164:165], v[142:145], off sc1
	global_store_dwordx4 v[164:165], v[138:141], off offset:64 sc1
	global_store_dwordx4 v[204:205], v[146:149], off offset:512 sc1
	global_store_dwordx4 v[204:205], v[150:153], off offset:576 sc1
	global_store_dwordx4 v[186:187], v[154:157], off offset:512 sc1
	global_store_dwordx4 v[186:187], v[158:161], off offset:576 sc1
	global_store_dwordx4 v[162:163], v[170:173], off offset:512 sc1
	global_store_dwordx4 v[162:163], v[174:177], off offset:576 sc1
	global_store_dwordx4 v[164:165], v[134:137], off offset:512 sc1
	global_store_dwordx4 v[164:165], v[130:133], off offset:576 sc1
	s_branch .LBB0_247

.Lkv_k_body_ctx:
	v_lshlrev_b32_e32 v132, s84, v130
	v_lshl_add_u32 v132, v131, 1, v132
	s_lshl_b32 s58, 16, s84
	s_mul_i32 s59, s58, 5
	v_cvt_pk_bf16_f32 v134, v126, v127
	v_cvt_pk_bf16_f32 v135, v128, v129
	global_store_dwordx2 v132, v[134:135], s[6:7] offset:0
	global_store_dwordx4 v133, v[126:129], s[8:9] offset:0 sc1
	v_cvt_pk_bf16_f32 v136, v122, v123
	v_cvt_pk_bf16_f32 v137, v124, v125
	global_store_dwordx2 v132, v[136:137], s[6:7] offset:32
	global_store_dwordx4 v133, v[122:125], s[8:9] offset:64 sc1
	v_cvt_pk_bf16_f32 v138, v94, v95
	v_cvt_pk_bf16_f32 v139, v96, v97
	global_store_dwordx2 v132, v[138:139], s[6:7] offset:256
	global_store_dwordx4 v133, v[94:97], s[8:9] offset:512 sc1
	v_cvt_pk_bf16_f32 v140, v90, v91
	v_cvt_pk_bf16_f32 v141, v92, v93
	global_store_dwordx2 v132, v[140:141], s[6:7] offset:288
	global_store_dwordx4 v133, v[90:93], s[8:9] offset:576 sc1
	s_add_u32 s6, s6, s58
	s_addc_u32 s7, s7, 0
	s_add_u32 s8, s8, s70
	s_addc_u32 s9, s9, 0
	v_cvt_pk_bf16_f32 v142, v118, v119
	v_cvt_pk_bf16_f32 v143, v120, v121
	global_store_dwordx2 v132, v[142:143], s[6:7] offset:0
	global_store_dwordx4 v133, v[118:121], s[8:9] offset:0 sc1
	v_cvt_pk_bf16_f32 v144, v114, v115
	v_cvt_pk_bf16_f32 v145, v116, v117
	global_store_dwordx2 v132, v[144:145], s[6:7] offset:32
	global_store_dwordx4 v133, v[114:117], s[8:9] offset:64 sc1
	v_cvt_pk_bf16_f32 v146, v86, v87
	v_cvt_pk_bf16_f32 v147, v88, v89
	global_store_dwordx2 v132, v[146:147], s[6:7] offset:256
	global_store_dwordx4 v133, v[86:89], s[8:9] offset:512 sc1
	v_cvt_pk_bf16_f32 v148, v82, v83
	v_cvt_pk_bf16_f32 v149, v84, v85
	global_store_dwordx2 v132, v[148:149], s[6:7] offset:288
	global_store_dwordx4 v133, v[82:85], s[8:9] offset:576 sc1
	s_add_u32 s6, s6, s58
	s_addc_u32 s7, s7, 0
	s_add_u32 s8, s8, s70
	s_addc_u32 s9, s9, 0
	v_cvt_pk_bf16_f32 v150, v110, v111
	v_cvt_pk_bf16_f32 v151, v112, v113
	global_store_dwordx2 v132, v[150:151], s[6:7] offset:0
	global_store_dwordx4 v133, v[110:113], s[8:9] offset:0 sc1
	v_cvt_pk_bf16_f32 v152, v106, v107
	v_cvt_pk_bf16_f32 v153, v108, v109
	global_store_dwordx2 v132, v[152:153], s[6:7] offset:32
	global_store_dwordx4 v133, v[106:109], s[8:9] offset:64 sc1
	v_cvt_pk_bf16_f32 v154, v78, v79
	v_cvt_pk_bf16_f32 v155, v80, v81
	global_store_dwordx2 v132, v[154:155], s[6:7] offset:256
	global_store_dwordx4 v133, v[78:81], s[8:9] offset:512 sc1
	v_cvt_pk_bf16_f32 v156, v74, v75
	v_cvt_pk_bf16_f32 v157, v76, v77
	global_store_dwordx2 v132, v[156:157], s[6:7] offset:288
	global_store_dwordx4 v133, v[74:77], s[8:9] offset:576 sc1
	s_add_u32 s6, s6, s58
	s_addc_u32 s7, s7, 0
	s_add_u32 s8, s8, s70
	s_addc_u32 s9, s9, 0
	v_cvt_pk_bf16_f32 v158, v102, v103
	v_cvt_pk_bf16_f32 v159, v104, v105
	global_store_dwordx2 v132, v[158:159], s[6:7] offset:0
	global_store_dwordx4 v133, v[102:105], s[8:9] offset:0 sc1
	v_cvt_pk_bf16_f32 v160, v98, v99
	v_cvt_pk_bf16_f32 v161, v100, v101
	global_store_dwordx2 v132, v[160:161], s[6:7] offset:32
	global_store_dwordx4 v133, v[98:101], s[8:9] offset:64 sc1
	v_cvt_pk_bf16_f32 v162, v70, v71
	v_cvt_pk_bf16_f32 v163, v72, v73
	global_store_dwordx2 v132, v[162:163], s[6:7] offset:256
	global_store_dwordx4 v133, v[70:73], s[8:9] offset:512 sc1
	v_cvt_pk_bf16_f32 v164, v66, v67
	v_cvt_pk_bf16_f32 v165, v68, v69
	global_store_dwordx2 v132, v[164:165], s[6:7] offset:288
	global_store_dwordx4 v133, v[66:69], s[8:9] offset:576 sc1
	s_add_u32 s6, s6, s59
	s_addc_u32 s7, s7, 0
	s_add_u32 s8, s8, s71
	s_addc_u32 s9, s9, 0
	v_cvt_pk_bf16_f32 v134, v62, v63
	v_cvt_pk_bf16_f32 v135, v64, v65
	global_store_dwordx2 v132, v[134:135], s[6:7] offset:0
	global_store_dwordx4 v133, v[62:65], s[8:9] offset:0 sc1
	v_cvt_pk_bf16_f32 v136, v58, v59
	v_cvt_pk_bf16_f32 v137, v60, v61
	global_store_dwordx2 v132, v[136:137], s[6:7] offset:32
	global_store_dwordx4 v133, v[58:61], s[8:9] offset:64 sc1
	v_cvt_pk_bf16_f32 v138, v30, v31
	v_cvt_pk_bf16_f32 v139, v32, v33
	global_store_dwordx2 v132, v[138:139], s[6:7] offset:256
	global_store_dwordx4 v133, v[30:33], s[8:9] offset:512 sc1
	v_cvt_pk_bf16_f32 v140, v26, v27
	v_cvt_pk_bf16_f32 v141, v28, v29
	global_store_dwordx2 v132, v[140:141], s[6:7] offset:288
	global_store_dwordx4 v133, v[26:29], s[8:9] offset:576 sc1
	s_add_u32 s6, s6, s58
	s_addc_u32 s7, s7, 0
	s_add_u32 s8, s8, s70
	s_addc_u32 s9, s9, 0
	v_cvt_pk_bf16_f32 v142, v54, v55
	v_cvt_pk_bf16_f32 v143, v56, v57
	global_store_dwordx2 v132, v[142:143], s[6:7] offset:0
	global_store_dwordx4 v133, v[54:57], s[8:9] offset:0 sc1
	v_cvt_pk_bf16_f32 v144, v50, v51
	v_cvt_pk_bf16_f32 v145, v52, v53
	global_store_dwordx2 v132, v[144:145], s[6:7] offset:32
	global_store_dwordx4 v133, v[50:53], s[8:9] offset:64 sc1
	v_cvt_pk_bf16_f32 v146, v22, v23
	v_cvt_pk_bf16_f32 v147, v24, v25
	global_store_dwordx2 v132, v[146:147], s[6:7] offset:256
	global_store_dwordx4 v133, v[22:25], s[8:9] offset:512 sc1
	v_cvt_pk_bf16_f32 v148, v18, v19
	v_cvt_pk_bf16_f32 v149, v20, v21
	global_store_dwordx2 v132, v[148:149], s[6:7] offset:288
	global_store_dwordx4 v133, v[18:21], s[8:9] offset:576 sc1
	s_add_u32 s6, s6, s58
	s_addc_u32 s7, s7, 0
	s_add_u32 s8, s8, s70
	s_addc_u32 s9, s9, 0
	v_cvt_pk_bf16_f32 v150, v46, v47
	v_cvt_pk_bf16_f32 v151, v48, v49
	global_store_dwordx2 v132, v[150:151], s[6:7] offset:0
	global_store_dwordx4 v133, v[46:49], s[8:9] offset:0 sc1
	v_cvt_pk_bf16_f32 v152, v42, v43
	v_cvt_pk_bf16_f32 v153, v44, v45
	global_store_dwordx2 v132, v[152:153], s[6:7] offset:32
	global_store_dwordx4 v133, v[42:45], s[8:9] offset:64 sc1
	v_cvt_pk_bf16_f32 v154, v14, v15
	v_cvt_pk_bf16_f32 v155, v16, v17
	global_store_dwordx2 v132, v[154:155], s[6:7] offset:256
	global_store_dwordx4 v133, v[14:17], s[8:9] offset:512 sc1
	v_cvt_pk_bf16_f32 v156, v10, v11
	v_cvt_pk_bf16_f32 v157, v12, v13
	global_store_dwordx2 v132, v[156:157], s[6:7] offset:288
	global_store_dwordx4 v133, v[10:13], s[8:9] offset:576 sc1
	s_add_u32 s6, s6, s58
	s_addc_u32 s7, s7, 0
	s_add_u32 s8, s8, s70
	s_addc_u32 s9, s9, 0
	v_cvt_pk_bf16_f32 v158, v38, v39
	v_cvt_pk_bf16_f32 v159, v40, v41
	global_store_dwordx2 v132, v[158:159], s[6:7] offset:0
	global_store_dwordx4 v133, v[38:41], s[8:9] offset:0 sc1
	v_cvt_pk_bf16_f32 v160, v34, v35
	v_cvt_pk_bf16_f32 v161, v36, v37
	global_store_dwordx2 v132, v[160:161], s[6:7] offset:32
	global_store_dwordx4 v133, v[34:37], s[8:9] offset:64 sc1
	v_cvt_pk_bf16_f32 v162, v6, v7
	v_cvt_pk_bf16_f32 v163, v8, v9
	global_store_dwordx2 v132, v[162:163], s[6:7] offset:256
	global_store_dwordx4 v133, v[6:9], s[8:9] offset:512 sc1
	v_cvt_pk_bf16_f32 v164, v2, v3
	v_cvt_pk_bf16_f32 v165, v4, v5
	global_store_dwordx2 v132, v[164:165], s[6:7] offset:288
	global_store_dwordx4 v133, v[2:5], s[8:9] offset:576 sc1
	s_branch .LBB0_247

.Lkv_v_body_ctx:
	v_mul_u32_u24_e32 v132, s76, v131
	v_lshl_add_u32 v132, v130, 1, v132
	s_mul_i32 s77, s76, 13
	s_mul_i32 s60, s76, 109
	v_cvt_pk_bf16_f32 v134, v126, v127
	v_cvt_pk_bf16_f32 v135, v128, v129
	v_cvt_pk_bf16_f32 v136, v118, v119
	v_cvt_pk_bf16_f32 v137, v120, v121
	v_cvt_pk_bf16_f32 v138, v110, v111
	v_cvt_pk_bf16_f32 v139, v112, v113
	v_cvt_pk_bf16_f32 v140, v102, v103
	v_cvt_pk_bf16_f32 v141, v104, v105
	v_cvt_pk_bf16_f32 v142, v62, v63
	v_cvt_pk_bf16_f32 v143, v64, v65
	v_cvt_pk_bf16_f32 v144, v54, v55
	v_cvt_pk_bf16_f32 v145, v56, v57
	v_cvt_pk_bf16_f32 v146, v46, v47
	v_cvt_pk_bf16_f32 v147, v48, v49
	v_cvt_pk_bf16_f32 v148, v38, v39
	v_cvt_pk_bf16_f32 v149, v40, v41
	global_store_short v132, v134, s[6:7] offset:0
	global_store_short v132, v136, s[6:7] offset:32
	global_store_short v132, v138, s[6:7] offset:64
	global_store_short v132, v140, s[6:7] offset:96
	global_store_short v132, v142, s[6:7] offset:256
	global_store_short v132, v144, s[6:7] offset:288
	global_store_short v132, v146, s[6:7] offset:320
	global_store_short v132, v148, s[6:7] offset:352
	s_add_u32 s6, s6, s76
	s_addc_u32 s7, s7, 0
	global_store_short_d16_hi v132, v134, s[6:7] offset:0
	global_store_short_d16_hi v132, v136, s[6:7] offset:32
	global_store_short_d16_hi v132, v138, s[6:7] offset:64
	global_store_short_d16_hi v132, v140, s[6:7] offset:96
	global_store_short_d16_hi v132, v142, s[6:7] offset:256
	global_store_short_d16_hi v132, v144, s[6:7] offset:288
	global_store_short_d16_hi v132, v146, s[6:7] offset:320
	global_store_short_d16_hi v132, v148, s[6:7] offset:352
	s_add_u32 s6, s6, s76
	s_addc_u32 s7, s7, 0
	global_store_short v132, v135, s[6:7] offset:0
	global_store_short v132, v137, s[6:7] offset:32
	global_store_short v132, v139, s[6:7] offset:64
	global_store_short v132, v141, s[6:7] offset:96
	global_store_short v132, v143, s[6:7] offset:256
	global_store_short v132, v145, s[6:7] offset:288
	global_store_short v132, v147, s[6:7] offset:320
	global_store_short v132, v149, s[6:7] offset:352
	s_add_u32 s6, s6, s76
	s_addc_u32 s7, s7, 0
	global_store_short_d16_hi v132, v135, s[6:7] offset:0
	global_store_short_d16_hi v132, v137, s[6:7] offset:32
	global_store_short_d16_hi v132, v139, s[6:7] offset:64
	global_store_short_d16_hi v132, v141, s[6:7] offset:96
	global_store_short_d16_hi v132, v143, s[6:7] offset:256
	global_store_short_d16_hi v132, v145, s[6:7] offset:288
	global_store_short_d16_hi v132, v147, s[6:7] offset:320
	global_store_short_d16_hi v132, v149, s[6:7] offset:352
	s_add_u32 s6, s6, s77
	s_addc_u32 s7, s7, 0
	v_cvt_pk_bf16_f32 v150, v122, v123
	v_cvt_pk_bf16_f32 v151, v124, v125
	v_cvt_pk_bf16_f32 v152, v114, v115
	v_cvt_pk_bf16_f32 v153, v116, v117
	v_cvt_pk_bf16_f32 v154, v106, v107
	v_cvt_pk_bf16_f32 v155, v108, v109
	v_cvt_pk_bf16_f32 v156, v98, v99
	v_cvt_pk_bf16_f32 v157, v100, v101
	v_cvt_pk_bf16_f32 v158, v58, v59
	v_cvt_pk_bf16_f32 v159, v60, v61
	v_cvt_pk_bf16_f32 v160, v50, v51
	v_cvt_pk_bf16_f32 v161, v52, v53
	v_cvt_pk_bf16_f32 v162, v42, v43
	v_cvt_pk_bf16_f32 v163, v44, v45
	v_cvt_pk_bf16_f32 v164, v34, v35
	v_cvt_pk_bf16_f32 v165, v36, v37
	global_store_short v132, v150, s[6:7] offset:0
	global_store_short v132, v152, s[6:7] offset:32
	global_store_short v132, v154, s[6:7] offset:64
	global_store_short v132, v156, s[6:7] offset:96
	global_store_short v132, v158, s[6:7] offset:256
	global_store_short v132, v160, s[6:7] offset:288
	global_store_short v132, v162, s[6:7] offset:320
	global_store_short v132, v164, s[6:7] offset:352
	s_add_u32 s6, s6, s76
	s_addc_u32 s7, s7, 0
	global_store_short_d16_hi v132, v150, s[6:7] offset:0
	global_store_short_d16_hi v132, v152, s[6:7] offset:32
	global_store_short_d16_hi v132, v154, s[6:7] offset:64
	global_store_short_d16_hi v132, v156, s[6:7] offset:96
	global_store_short_d16_hi v132, v158, s[6:7] offset:256
	global_store_short_d16_hi v132, v160, s[6:7] offset:288
	global_store_short_d16_hi v132, v162, s[6:7] offset:320
	global_store_short_d16_hi v132, v164, s[6:7] offset:352
	s_add_u32 s6, s6, s76
	s_addc_u32 s7, s7, 0
	global_store_short v132, v151, s[6:7] offset:0
	global_store_short v132, v153, s[6:7] offset:32
	global_store_short v132, v155, s[6:7] offset:64
	global_store_short v132, v157, s[6:7] offset:96
	global_store_short v132, v159, s[6:7] offset:256
	global_store_short v132, v161, s[6:7] offset:288
	global_store_short v132, v163, s[6:7] offset:320
	global_store_short v132, v165, s[6:7] offset:352
	s_add_u32 s6, s6, s76
	s_addc_u32 s7, s7, 0
	global_store_short_d16_hi v132, v151, s[6:7] offset:0
	global_store_short_d16_hi v132, v153, s[6:7] offset:32
	global_store_short_d16_hi v132, v155, s[6:7] offset:64
	global_store_short_d16_hi v132, v157, s[6:7] offset:96
	global_store_short_d16_hi v132, v159, s[6:7] offset:256
	global_store_short_d16_hi v132, v161, s[6:7] offset:288
	global_store_short_d16_hi v132, v163, s[6:7] offset:320
	global_store_short_d16_hi v132, v165, s[6:7] offset:352
	s_add_u32 s6, s6, s60
	s_addc_u32 s7, s7, 0
	v_cvt_pk_bf16_f32 v134, v94, v95
	v_cvt_pk_bf16_f32 v135, v96, v97
	v_cvt_pk_bf16_f32 v136, v86, v87
	v_cvt_pk_bf16_f32 v137, v88, v89
	v_cvt_pk_bf16_f32 v138, v78, v79
	v_cvt_pk_bf16_f32 v139, v80, v81
	v_cvt_pk_bf16_f32 v140, v70, v71
	v_cvt_pk_bf16_f32 v141, v72, v73
	v_cvt_pk_bf16_f32 v142, v30, v31
	v_cvt_pk_bf16_f32 v143, v32, v33
	v_cvt_pk_bf16_f32 v144, v22, v23
	v_cvt_pk_bf16_f32 v145, v24, v25
	v_cvt_pk_bf16_f32 v146, v14, v15
	v_cvt_pk_bf16_f32 v147, v16, v17
	v_cvt_pk_bf16_f32 v148, v6, v7
	v_cvt_pk_bf16_f32 v149, v8, v9
	global_store_short v132, v134, s[6:7] offset:0
	global_store_short v132, v136, s[6:7] offset:32
	global_store_short v132, v138, s[6:7] offset:64
	global_store_short v132, v140, s[6:7] offset:96
	global_store_short v132, v142, s[6:7] offset:256
	global_store_short v132, v144, s[6:7] offset:288
	global_store_short v132, v146, s[6:7] offset:320
	global_store_short v132, v148, s[6:7] offset:352
	s_add_u32 s6, s6, s76
	s_addc_u32 s7, s7, 0
	global_store_short_d16_hi v132, v134, s[6:7] offset:0
	global_store_short_d16_hi v132, v136, s[6:7] offset:32
	global_store_short_d16_hi v132, v138, s[6:7] offset:64
	global_store_short_d16_hi v132, v140, s[6:7] offset:96
	global_store_short_d16_hi v132, v142, s[6:7] offset:256
	global_store_short_d16_hi v132, v144, s[6:7] offset:288
	global_store_short_d16_hi v132, v146, s[6:7] offset:320
	global_store_short_d16_hi v132, v148, s[6:7] offset:352
	s_add_u32 s6, s6, s76
	s_addc_u32 s7, s7, 0
	global_store_short v132, v135, s[6:7] offset:0
	global_store_short v132, v137, s[6:7] offset:32
	global_store_short v132, v139, s[6:7] offset:64
	global_store_short v132, v141, s[6:7] offset:96
	global_store_short v132, v143, s[6:7] offset:256
	global_store_short v132, v145, s[6:7] offset:288
	global_store_short v132, v147, s[6:7] offset:320
	global_store_short v132, v149, s[6:7] offset:352
	s_add_u32 s6, s6, s76
	s_addc_u32 s7, s7, 0
	global_store_short_d16_hi v132, v135, s[6:7] offset:0
	global_store_short_d16_hi v132, v137, s[6:7] offset:32
	global_store_short_d16_hi v132, v139, s[6:7] offset:64
	global_store_short_d16_hi v132, v141, s[6:7] offset:96
	global_store_short_d16_hi v132, v143, s[6:7] offset:256
	global_store_short_d16_hi v132, v145, s[6:7] offset:288
	global_store_short_d16_hi v132, v147, s[6:7] offset:320
	global_store_short_d16_hi v132, v149, s[6:7] offset:352
	s_add_u32 s6, s6, s77
	s_addc_u32 s7, s7, 0
	v_cvt_pk_bf16_f32 v150, v90, v91
	v_cvt_pk_bf16_f32 v151, v92, v93
	v_cvt_pk_bf16_f32 v152, v82, v83
	v_cvt_pk_bf16_f32 v153, v84, v85
	v_cvt_pk_bf16_f32 v154, v74, v75
	v_cvt_pk_bf16_f32 v155, v76, v77
	v_cvt_pk_bf16_f32 v156, v66, v67
	v_cvt_pk_bf16_f32 v157, v68, v69
	v_cvt_pk_bf16_f32 v158, v26, v27
	v_cvt_pk_bf16_f32 v159, v28, v29
	v_cvt_pk_bf16_f32 v160, v18, v19
	v_cvt_pk_bf16_f32 v161, v20, v21
	v_cvt_pk_bf16_f32 v162, v10, v11
	v_cvt_pk_bf16_f32 v163, v12, v13
	v_cvt_pk_bf16_f32 v164, v2, v3
	v_cvt_pk_bf16_f32 v165, v4, v5
	global_store_short v132, v150, s[6:7] offset:0
	global_store_short v132, v152, s[6:7] offset:32
	global_store_short v132, v154, s[6:7] offset:64
	global_store_short v132, v156, s[6:7] offset:96
	global_store_short v132, v158, s[6:7] offset:256
	global_store_short v132, v160, s[6:7] offset:288
	global_store_short v132, v162, s[6:7] offset:320
	global_store_short v132, v164, s[6:7] offset:352
	s_add_u32 s6, s6, s76
	s_addc_u32 s7, s7, 0
	global_store_short_d16_hi v132, v150, s[6:7] offset:0
	global_store_short_d16_hi v132, v152, s[6:7] offset:32
	global_store_short_d16_hi v132, v154, s[6:7] offset:64
	global_store_short_d16_hi v132, v156, s[6:7] offset:96
	global_store_short_d16_hi v132, v158, s[6:7] offset:256
	global_store_short_d16_hi v132, v160, s[6:7] offset:288
	global_store_short_d16_hi v132, v162, s[6:7] offset:320
	global_store_short_d16_hi v132, v164, s[6:7] offset:352
	s_add_u32 s6, s6, s76
	s_addc_u32 s7, s7, 0
	global_store_short v132, v151, s[6:7] offset:0
	global_store_short v132, v153, s[6:7] offset:32
	global_store_short v132, v155, s[6:7] offset:64
	global_store_short v132, v157, s[6:7] offset:96
	global_store_short v132, v159, s[6:7] offset:256
	global_store_short v132, v161, s[6:7] offset:288
	global_store_short v132, v163, s[6:7] offset:320
	global_store_short v132, v165, s[6:7] offset:352
	s_add_u32 s6, s6, s76
	s_addc_u32 s7, s7, 0
	global_store_short_d16_hi v132, v151, s[6:7] offset:0
	global_store_short_d16_hi v132, v153, s[6:7] offset:32
	global_store_short_d16_hi v132, v155, s[6:7] offset:64
	global_store_short_d16_hi v132, v157, s[6:7] offset:96
	global_store_short_d16_hi v132, v159, s[6:7] offset:256
	global_store_short_d16_hi v132, v161, s[6:7] offset:288
	global_store_short_d16_hi v132, v163, s[6:7] offset:320
	global_store_short_d16_hi v132, v165, s[6:7] offset:352
	global_store_dwordx4 v133, v[126:129], s[8:9] offset:0 sc1
	global_store_dwordx4 v133, v[122:125], s[8:9] offset:64 sc1
	global_store_dwordx4 v133, v[94:97], s[8:9] offset:512 sc1
	global_store_dwordx4 v133, v[90:93], s[8:9] offset:576 sc1
	s_add_u32 s8, s8, s70
	s_addc_u32 s9, s9, 0
	global_store_dwordx4 v133, v[118:121], s[8:9] offset:0 sc1
	global_store_dwordx4 v133, v[114:117], s[8:9] offset:64 sc1
	global_store_dwordx4 v133, v[86:89], s[8:9] offset:512 sc1
	global_store_dwordx4 v133, v[82:85], s[8:9] offset:576 sc1
	s_add_u32 s8, s8, s70
	s_addc_u32 s9, s9, 0
	global_store_dwordx4 v133, v[110:113], s[8:9] offset:0 sc1
	global_store_dwordx4 v133, v[106:109], s[8:9] offset:64 sc1
	global_store_dwordx4 v133, v[78:81], s[8:9] offset:512 sc1
	global_store_dwordx4 v133, v[74:77], s[8:9] offset:576 sc1
	s_add_u32 s8, s8, s70
	s_addc_u32 s9, s9, 0
	global_store_dwordx4 v133, v[102:105], s[8:9] offset:0 sc1
	global_store_dwordx4 v133, v[98:101], s[8:9] offset:64 sc1
	global_store_dwordx4 v133, v[70:73], s[8:9] offset:512 sc1
	global_store_dwordx4 v133, v[66:69], s[8:9] offset:576 sc1
	s_add_u32 s8, s8, s71
	s_addc_u32 s9, s9, 0
	global_store_dwordx4 v133, v[62:65], s[8:9] offset:0 sc1
	global_store_dwordx4 v133, v[58:61], s[8:9] offset:64 sc1
	global_store_dwordx4 v133, v[30:33], s[8:9] offset:512 sc1
	global_store_dwordx4 v133, v[26:29], s[8:9] offset:576 sc1
	s_add_u32 s8, s8, s70
	s_addc_u32 s9, s9, 0
	global_store_dwordx4 v133, v[54:57], s[8:9] offset:0 sc1
	global_store_dwordx4 v133, v[50:53], s[8:9] offset:64 sc1
	global_store_dwordx4 v133, v[22:25], s[8:9] offset:512 sc1
	global_store_dwordx4 v133, v[18:21], s[8:9] offset:576 sc1
	s_add_u32 s8, s8, s70
	s_addc_u32 s9, s9, 0
	global_store_dwordx4 v133, v[46:49], s[8:9] offset:0 sc1
	global_store_dwordx4 v133, v[42:45], s[8:9] offset:64 sc1
	global_store_dwordx4 v133, v[14:17], s[8:9] offset:512 sc1
	global_store_dwordx4 v133, v[10:13], s[8:9] offset:576 sc1
	s_add_u32 s8, s8, s70
	s_addc_u32 s9, s9, 0
	global_store_dwordx4 v133, v[38:41], s[8:9] offset:0 sc1
	global_store_dwordx4 v133, v[34:37], s[8:9] offset:64 sc1
	global_store_dwordx4 v133, v[6:9], s[8:9] offset:512 sc1
	global_store_dwordx4 v133, v[2:5], s[8:9] offset:576 sc1
	s_branch .LBB0_247

.LBB0_771:
	v_mov_b64_e32 v[130:131], s[34:35]
	v_mad_i64_i32 v[130:131], s[6:7], v198, s62, v[130:131]
	v_lshl_add_u64 v[130:131], s[94:95], 1, v[130:131]
	v_lshlrev_b32_e32 v0, 1, v230
	v_lshl_add_u64 v[130:131], v[130:131], 0, v[0:1]
	v_lshlrev_b32_e32 v0, 1, v231
	v_lshl_add_u64 v[130:131], v[130:131], 0, v[0:1]
	v_cvt_pk_bf16_f32 v126, v126, v127
	v_cvt_pk_bf16_f32 v127, v128, v129
	v_cvt_pk_bf16_f32 v128, v122, v123
	v_cvt_pk_bf16_f32 v129, v124, v125
	v_cndmask_b32_e64 v0, 0, 1, s[24:25]
	v_permlane16_swap_b32_e32 v126, v128
	v_permlane16_swap_b32_e32 v127, v129
	v_cmp_ne_u32_e64 s[6:7], 1, v0
	s_andn2_b64 vcc, exec, s[24:25]
	global_store_dwordx4 v[130:131], v[126:129], off sc1
	s_cbranch_vccnz .LBB0_773
	v_mul_f32_e32 v0, 0xbfb8aa3b, v118
	v_exp_f32_e32 v0, v0
	v_mul_f32_e32 v115, 0xbfb8aa3b, v115
	v_exp_f32_e32 v115, v115
	v_mul_f32_e32 v114, 0xbfb8aa3b, v114
	v_add_f32_e32 v0, 1.0, v0
	v_rcp_f32_e32 v118, v0
	v_mul_f32_e32 v0, 0xbfb8aa3b, v119
	v_exp_f32_e32 v0, v0
	v_exp_f32_e32 v114, v114
	v_add_f32_e32 v0, 1.0, v0
	v_rcp_f32_e32 v119, v0
	v_add_f32_e32 v0, 1.0, v115
	v_mul_f32_e32 v115, 0xbfb8aa3b, v120
	v_exp_f32_e32 v120, v115
	v_mul_f32_e32 v115, 0xbfb8aa3b, v116
	v_exp_f32_e32 v116, v115
	v_rcp_f32_e32 v115, v0
	v_add_f32_e32 v0, 1.0, v120
	v_rcp_f32_e32 v120, v0
	v_add_f32_e32 v0, 1.0, v116
	v_mul_f32_e32 v116, 0xbfb8aa3b, v121
	v_exp_f32_e32 v121, v116
	v_mul_f32_e32 v116, 0xbfb8aa3b, v117
	v_exp_f32_e32 v117, v116
	v_rcp_f32_e32 v116, v0
	v_add_f32_e32 v0, 1.0, v121
	v_add_f32_e32 v114, 1.0, v114
	v_rcp_f32_e32 v121, v0
	v_add_f32_e32 v0, 1.0, v117
	v_rcp_f32_e32 v114, v114
	v_rcp_f32_e32 v117, v0
.LBB0_773:
	v_cvt_pk_bf16_f32 v118, v118, v119
	v_cvt_pk_bf16_f32 v119, v120, v121
	v_cvt_pk_bf16_f32 v120, v114, v115
	v_add_co_u32_e32 v114, vcc, 0x6c000, v130
	v_cvt_pk_bf16_f32 v121, v116, v117
	s_nop 0
	v_addc_co_u32_e32 v115, vcc, 0, v131, vcc
	v_permlane16_swap_b32_e32 v118, v120
	v_permlane16_swap_b32_e32 v119, v121
	s_and_b64 vcc, exec, s[6:7]
	global_store_dwordx4 v[114:115], v[118:121], off sc1
	s_cbranch_vccnz .LBB0_775
	v_mul_f32_e32 v0, 0xbfb8aa3b, v110
	v_exp_f32_e32 v0, v0
	v_mul_f32_e32 v107, 0xbfb8aa3b, v107
	v_exp_f32_e32 v107, v107
	v_mul_f32_e32 v106, 0xbfb8aa3b, v106
	v_add_f32_e32 v0, 1.0, v0
	v_rcp_f32_e32 v110, v0
	v_mul_f32_e32 v0, 0xbfb8aa3b, v111
	v_exp_f32_e32 v0, v0
	v_exp_f32_e32 v106, v106
	v_add_f32_e32 v0, 1.0, v0
	v_rcp_f32_e32 v111, v0
	v_add_f32_e32 v0, 1.0, v107
	v_mul_f32_e32 v107, 0xbfb8aa3b, v112
	v_exp_f32_e32 v112, v107
	v_mul_f32_e32 v107, 0xbfb8aa3b, v108
	v_exp_f32_e32 v108, v107
	v_rcp_f32_e32 v107, v0
	v_add_f32_e32 v0, 1.0, v112
	v_rcp_f32_e32 v112, v0
	v_add_f32_e32 v0, 1.0, v108
	v_mul_f32_e32 v108, 0xbfb8aa3b, v113
	v_exp_f32_e32 v113, v108
	v_mul_f32_e32 v108, 0xbfb8aa3b, v109
	v_exp_f32_e32 v109, v108
	v_rcp_f32_e32 v108, v0
	v_add_f32_e32 v0, 1.0, v113
	v_add_f32_e32 v106, 1.0, v106
	v_rcp_f32_e32 v113, v0
	v_add_f32_e32 v0, 1.0, v109
	v_rcp_f32_e32 v106, v106
	v_rcp_f32_e32 v109, v0
.LBB0_775:
	v_cvt_pk_bf16_f32 v110, v110, v111
	v_cvt_pk_bf16_f32 v111, v112, v113
	v_cvt_pk_bf16_f32 v112, v106, v107
	v_add_co_u32_e32 v106, vcc, 0xd8000, v130
	v_cvt_pk_bf16_f32 v113, v108, v109
	s_nop 0
	v_addc_co_u32_e32 v107, vcc, 0, v131, vcc
	v_permlane16_swap_b32_e32 v110, v112
	v_permlane16_swap_b32_e32 v111, v113
	s_and_b64 vcc, exec, s[6:7]
	global_store_dwordx4 v[106:107], v[110:113], off sc1
	s_cbranch_vccnz .LBB0_777
	v_mul_f32_e32 v0, 0xbfb8aa3b, v102
	v_exp_f32_e32 v0, v0
	v_mul_f32_e32 v99, 0xbfb8aa3b, v99
	v_exp_f32_e32 v99, v99
	v_mul_f32_e32 v98, 0xbfb8aa3b, v98
	v_add_f32_e32 v0, 1.0, v0
	v_rcp_f32_e32 v102, v0
	v_mul_f32_e32 v0, 0xbfb8aa3b, v103
	v_exp_f32_e32 v0, v0
	v_exp_f32_e32 v98, v98
	v_add_f32_e32 v0, 1.0, v0
	v_rcp_f32_e32 v103, v0
	v_add_f32_e32 v0, 1.0, v99
	v_mul_f32_e32 v99, 0xbfb8aa3b, v104
	v_exp_f32_e32 v104, v99
	v_mul_f32_e32 v99, 0xbfb8aa3b, v100
	v_exp_f32_e32 v100, v99
	v_rcp_f32_e32 v99, v0
	v_add_f32_e32 v0, 1.0, v104
	v_rcp_f32_e32 v104, v0
	v_add_f32_e32 v0, 1.0, v100
	v_mul_f32_e32 v100, 0xbfb8aa3b, v105
	v_exp_f32_e32 v105, v100
	v_mul_f32_e32 v100, 0xbfb8aa3b, v101
	v_exp_f32_e32 v101, v100
	v_rcp_f32_e32 v100, v0
	v_add_f32_e32 v0, 1.0, v105
	v_add_f32_e32 v98, 1.0, v98
	v_rcp_f32_e32 v105, v0
	v_add_f32_e32 v0, 1.0, v101
	v_rcp_f32_e32 v98, v98
	v_rcp_f32_e32 v101, v0
.LBB0_777:
	v_cvt_pk_bf16_f32 v102, v102, v103
	v_cvt_pk_bf16_f32 v103, v104, v105
	v_cvt_pk_bf16_f32 v104, v98, v99
	v_add_co_u32_e32 v98, vcc, 0x144000, v130
	v_cvt_pk_bf16_f32 v105, v100, v101
	s_nop 0
	v_addc_co_u32_e32 v99, vcc, 0, v131, vcc
	v_permlane16_swap_b32_e32 v102, v104
	v_permlane16_swap_b32_e32 v103, v105
	s_and_b64 vcc, exec, s[6:7]
	global_store_dwordx4 v[98:99], v[102:105], off sc1
	s_cbranch_vccnz .LBB0_779
	v_mul_f32_e32 v0, 0xbfb8aa3b, v94
	v_exp_f32_e32 v0, v0
	v_mul_f32_e32 v91, 0xbfb8aa3b, v91
	v_exp_f32_e32 v91, v91
	v_mul_f32_e32 v90, 0xbfb8aa3b, v90
	v_add_f32_e32 v0, 1.0, v0
	v_rcp_f32_e32 v94, v0
	v_mul_f32_e32 v0, 0xbfb8aa3b, v95
	v_exp_f32_e32 v0, v0
	v_exp_f32_e32 v90, v90
	v_add_f32_e32 v0, 1.0, v0
	v_rcp_f32_e32 v95, v0
	v_add_f32_e32 v0, 1.0, v91
	v_mul_f32_e32 v91, 0xbfb8aa3b, v96
	v_exp_f32_e32 v96, v91
	v_mul_f32_e32 v91, 0xbfb8aa3b, v92
	v_exp_f32_e32 v92, v91
	v_rcp_f32_e32 v91, v0
	v_add_f32_e32 v0, 1.0, v96
	v_rcp_f32_e32 v96, v0
	v_add_f32_e32 v0, 1.0, v92
	v_mul_f32_e32 v92, 0xbfb8aa3b, v97
	v_exp_f32_e32 v97, v92
	v_mul_f32_e32 v92, 0xbfb8aa3b, v93
	v_exp_f32_e32 v93, v92
	v_rcp_f32_e32 v92, v0
	v_add_f32_e32 v0, 1.0, v97
	v_add_f32_e32 v90, 1.0, v90
	v_rcp_f32_e32 v97, v0
	v_add_f32_e32 v0, 1.0, v93
	v_rcp_f32_e32 v90, v90
	v_rcp_f32_e32 v93, v0
.LBB0_779:
	v_cvt_pk_bf16_f32 v94, v94, v95
	v_cvt_pk_bf16_f32 v95, v96, v97
	v_cvt_pk_bf16_f32 v96, v90, v91
	v_cvt_pk_bf16_f32 v97, v92, v93
	s_nop 0
	v_permlane16_swap_b32_e32 v94, v96
	v_permlane16_swap_b32_e32 v95, v97
	s_and_b64 vcc, exec, s[6:7]
	global_store_dwordx4 v[130:131], v[94:97], off offset:256 sc1
	s_cbranch_vccnz .LBB0_781
	v_mul_f32_e32 v0, 0xbfb8aa3b, v86
	v_exp_f32_e32 v0, v0
	v_mul_f32_e32 v83, 0xbfb8aa3b, v83
	v_exp_f32_e32 v83, v83
	v_mul_f32_e32 v82, 0xbfb8aa3b, v82
	v_add_f32_e32 v0, 1.0, v0
	v_rcp_f32_e32 v86, v0
	v_mul_f32_e32 v0, 0xbfb8aa3b, v87
	v_exp_f32_e32 v0, v0
	v_exp_f32_e32 v82, v82
	v_add_f32_e32 v0, 1.0, v0
	v_rcp_f32_e32 v87, v0
	v_add_f32_e32 v0, 1.0, v83
	v_mul_f32_e32 v83, 0xbfb8aa3b, v88
	v_exp_f32_e32 v88, v83
	v_mul_f32_e32 v83, 0xbfb8aa3b, v84
	v_exp_f32_e32 v84, v83
	v_rcp_f32_e32 v83, v0
	v_add_f32_e32 v0, 1.0, v88
	v_rcp_f32_e32 v88, v0
	v_add_f32_e32 v0, 1.0, v84
	v_mul_f32_e32 v84, 0xbfb8aa3b, v89
	v_exp_f32_e32 v89, v84
	v_mul_f32_e32 v84, 0xbfb8aa3b, v85
	v_exp_f32_e32 v85, v84
	v_rcp_f32_e32 v84, v0
	v_add_f32_e32 v0, 1.0, v89
	v_add_f32_e32 v82, 1.0, v82
	v_rcp_f32_e32 v89, v0
	v_add_f32_e32 v0, 1.0, v85
	v_rcp_f32_e32 v82, v82
	v_rcp_f32_e32 v85, v0
.LBB0_781:
	v_cvt_pk_bf16_f32 v86, v86, v87
	v_cvt_pk_bf16_f32 v87, v88, v89
	v_cvt_pk_bf16_f32 v88, v82, v83
	v_add_co_u32_e32 v82, vcc, 0x6c000, v130
	v_cvt_pk_bf16_f32 v89, v84, v85
	s_nop 0
	v_addc_co_u32_e32 v83, vcc, 0, v131, vcc
	v_permlane16_swap_b32_e32 v86, v88
	v_permlane16_swap_b32_e32 v87, v89
	s_and_b64 vcc, exec, s[6:7]
	global_store_dwordx4 v[82:83], v[86:89], off offset:256 sc1
	s_cbranch_vccnz .LBB0_783
	v_mul_f32_e32 v0, 0xbfb8aa3b, v78
	v_exp_f32_e32 v0, v0
	v_mul_f32_e32 v75, 0xbfb8aa3b, v75
	v_exp_f32_e32 v75, v75
	v_mul_f32_e32 v74, 0xbfb8aa3b, v74
	v_add_f32_e32 v0, 1.0, v0
	v_rcp_f32_e32 v78, v0
	v_mul_f32_e32 v0, 0xbfb8aa3b, v79
	v_exp_f32_e32 v0, v0
	v_exp_f32_e32 v74, v74
	v_add_f32_e32 v0, 1.0, v0
	v_rcp_f32_e32 v79, v0
	v_add_f32_e32 v0, 1.0, v75
	v_mul_f32_e32 v75, 0xbfb8aa3b, v80
	v_exp_f32_e32 v80, v75
	v_mul_f32_e32 v75, 0xbfb8aa3b, v76
	v_exp_f32_e32 v76, v75
	v_rcp_f32_e32 v75, v0
	v_add_f32_e32 v0, 1.0, v80
	v_rcp_f32_e32 v80, v0
	v_add_f32_e32 v0, 1.0, v76
	v_mul_f32_e32 v76, 0xbfb8aa3b, v81
	v_exp_f32_e32 v81, v76
	v_mul_f32_e32 v76, 0xbfb8aa3b, v77
	v_exp_f32_e32 v77, v76
	v_rcp_f32_e32 v76, v0
	v_add_f32_e32 v0, 1.0, v81
	v_add_f32_e32 v74, 1.0, v74
	v_rcp_f32_e32 v81, v0
	v_add_f32_e32 v0, 1.0, v77
	v_rcp_f32_e32 v74, v74
	v_rcp_f32_e32 v77, v0
.LBB0_783:
	v_cvt_pk_bf16_f32 v78, v78, v79
	v_cvt_pk_bf16_f32 v79, v80, v81
	v_cvt_pk_bf16_f32 v80, v74, v75
	v_add_co_u32_e32 v74, vcc, 0xd8000, v130
	v_cvt_pk_bf16_f32 v81, v76, v77
	s_nop 0
	v_addc_co_u32_e32 v75, vcc, 0, v131, vcc
	v_permlane16_swap_b32_e32 v78, v80
	v_permlane16_swap_b32_e32 v79, v81
	s_and_b64 vcc, exec, s[6:7]
	global_store_dwordx4 v[74:75], v[78:81], off offset:256 sc1
	s_cbranch_vccnz .LBB0_785
	v_mul_f32_e32 v0, 0xbfb8aa3b, v70
	v_exp_f32_e32 v0, v0
	v_mul_f32_e32 v67, 0xbfb8aa3b, v67
	v_exp_f32_e32 v67, v67
	v_mul_f32_e32 v66, 0xbfb8aa3b, v66
	v_add_f32_e32 v0, 1.0, v0
	v_rcp_f32_e32 v70, v0
	v_mul_f32_e32 v0, 0xbfb8aa3b, v71
	v_exp_f32_e32 v0, v0
	v_exp_f32_e32 v66, v66
	v_add_f32_e32 v0, 1.0, v0
	v_rcp_f32_e32 v71, v0
	v_add_f32_e32 v0, 1.0, v67
	v_mul_f32_e32 v67, 0xbfb8aa3b, v72
	v_exp_f32_e32 v72, v67
	v_mul_f32_e32 v67, 0xbfb8aa3b, v68
	v_exp_f32_e32 v68, v67
	v_rcp_f32_e32 v67, v0
	v_add_f32_e32 v0, 1.0, v72
	v_rcp_f32_e32 v72, v0
	v_add_f32_e32 v0, 1.0, v68
	v_mul_f32_e32 v68, 0xbfb8aa3b, v73
	v_exp_f32_e32 v73, v68
	v_mul_f32_e32 v68, 0xbfb8aa3b, v69
	v_exp_f32_e32 v69, v68
	v_rcp_f32_e32 v68, v0
	v_add_f32_e32 v0, 1.0, v73
	v_add_f32_e32 v66, 1.0, v66
	v_rcp_f32_e32 v73, v0
	v_add_f32_e32 v0, 1.0, v69
	v_rcp_f32_e32 v66, v66
	v_rcp_f32_e32 v69, v0
.LBB0_785:
	v_cvt_pk_bf16_f32 v70, v70, v71
	v_cvt_pk_bf16_f32 v71, v72, v73
	v_cvt_pk_bf16_f32 v72, v66, v67
	v_add_co_u32_e32 v66, vcc, 0x144000, v130
	v_cvt_pk_bf16_f32 v73, v68, v69
	s_nop 0
	v_addc_co_u32_e32 v67, vcc, 0, v131, vcc
	v_permlane16_swap_b32_e32 v70, v72
	v_permlane16_swap_b32_e32 v71, v73
	s_and_b64 vcc, exec, s[6:7]
	global_store_dwordx4 v[66:67], v[70:73], off offset:256 sc1
	s_cbranch_vccnz .LBB0_787
	v_mul_f32_e32 v0, 0xbfb8aa3b, v62
	v_exp_f32_e32 v0, v0
	v_mul_f32_e32 v59, 0xbfb8aa3b, v59
	v_exp_f32_e32 v59, v59
	v_mul_f32_e32 v58, 0xbfb8aa3b, v58
	v_add_f32_e32 v0, 1.0, v0
	v_rcp_f32_e32 v62, v0
	v_mul_f32_e32 v0, 0xbfb8aa3b, v63
	v_exp_f32_e32 v0, v0
	v_exp_f32_e32 v58, v58
	v_add_f32_e32 v0, 1.0, v0
	v_rcp_f32_e32 v63, v0
	v_add_f32_e32 v0, 1.0, v59
	v_mul_f32_e32 v59, 0xbfb8aa3b, v64
	v_exp_f32_e32 v64, v59
	v_mul_f32_e32 v59, 0xbfb8aa3b, v60
	v_exp_f32_e32 v60, v59
	v_rcp_f32_e32 v59, v0
	v_add_f32_e32 v0, 1.0, v64
	v_rcp_f32_e32 v64, v0
	v_add_f32_e32 v0, 1.0, v60
	v_mul_f32_e32 v60, 0xbfb8aa3b, v65
	v_exp_f32_e32 v65, v60
	v_mul_f32_e32 v60, 0xbfb8aa3b, v61
	v_exp_f32_e32 v61, v60
	v_rcp_f32_e32 v60, v0
	v_add_f32_e32 v0, 1.0, v65
	v_add_f32_e32 v58, 1.0, v58
	v_rcp_f32_e32 v65, v0
	v_add_f32_e32 v0, 1.0, v61
	v_rcp_f32_e32 v58, v58
	v_rcp_f32_e32 v61, v0
.LBB0_787:
	v_cvt_pk_bf16_f32 v62, v62, v63
	v_cvt_pk_bf16_f32 v63, v64, v65
	v_cvt_pk_bf16_f32 v64, v58, v59
	v_add_co_u32_e32 v58, vcc, 0x360000, v130
	v_cvt_pk_bf16_f32 v65, v60, v61
	s_nop 0
	v_addc_co_u32_e32 v59, vcc, 0, v131, vcc
	v_permlane16_swap_b32_e32 v62, v64
	v_permlane16_swap_b32_e32 v63, v65
	s_and_b64 vcc, exec, s[6:7]
	global_store_dwordx4 v[58:59], v[62:65], off sc1
	s_cbranch_vccnz .LBB0_789
	v_mul_f32_e32 v0, 0xbfb8aa3b, v54
	v_exp_f32_e32 v0, v0
	v_mul_f32_e32 v51, 0xbfb8aa3b, v51
	v_exp_f32_e32 v51, v51
	v_mul_f32_e32 v50, 0xbfb8aa3b, v50
	v_add_f32_e32 v0, 1.0, v0
	v_rcp_f32_e32 v54, v0
	v_mul_f32_e32 v0, 0xbfb8aa3b, v55
	v_exp_f32_e32 v0, v0
	v_exp_f32_e32 v50, v50
	v_add_f32_e32 v0, 1.0, v0
	v_rcp_f32_e32 v55, v0
	v_add_f32_e32 v0, 1.0, v51
	v_mul_f32_e32 v51, 0xbfb8aa3b, v56
	v_exp_f32_e32 v56, v51
	v_mul_f32_e32 v51, 0xbfb8aa3b, v52
	v_exp_f32_e32 v52, v51
	v_rcp_f32_e32 v51, v0
	v_add_f32_e32 v0, 1.0, v56
	v_rcp_f32_e32 v56, v0
	v_add_f32_e32 v0, 1.0, v52
	v_mul_f32_e32 v52, 0xbfb8aa3b, v57
	v_exp_f32_e32 v57, v52
	v_mul_f32_e32 v52, 0xbfb8aa3b, v53
	v_exp_f32_e32 v53, v52
	v_rcp_f32_e32 v52, v0
	v_add_f32_e32 v0, 1.0, v57
	v_add_f32_e32 v50, 1.0, v50
	v_rcp_f32_e32 v57, v0
	v_add_f32_e32 v0, 1.0, v53
	v_rcp_f32_e32 v50, v50
	v_rcp_f32_e32 v53, v0
.LBB0_789:
	v_cvt_pk_bf16_f32 v54, v54, v55
	v_cvt_pk_bf16_f32 v55, v56, v57
	v_cvt_pk_bf16_f32 v56, v50, v51
	v_add_co_u32_e32 v50, vcc, 0x3cc000, v130
	v_cvt_pk_bf16_f32 v57, v52, v53
	s_nop 0
	v_addc_co_u32_e32 v51, vcc, 0, v131, vcc
	v_permlane16_swap_b32_e32 v54, v56
	v_permlane16_swap_b32_e32 v55, v57
	s_and_b64 vcc, exec, s[6:7]
	global_store_dwordx4 v[50:51], v[54:57], off sc1
	s_cbranch_vccnz .LBB0_791
	v_mul_f32_e32 v0, 0xbfb8aa3b, v46
	v_exp_f32_e32 v0, v0
	v_mul_f32_e32 v43, 0xbfb8aa3b, v43
	v_exp_f32_e32 v43, v43
	v_mul_f32_e32 v42, 0xbfb8aa3b, v42
	v_add_f32_e32 v0, 1.0, v0
	v_rcp_f32_e32 v46, v0
	v_mul_f32_e32 v0, 0xbfb8aa3b, v47
	v_exp_f32_e32 v0, v0
	v_exp_f32_e32 v42, v42
	v_add_f32_e32 v0, 1.0, v0
	v_rcp_f32_e32 v47, v0
	v_add_f32_e32 v0, 1.0, v43
	v_mul_f32_e32 v43, 0xbfb8aa3b, v48
	v_exp_f32_e32 v48, v43
	v_mul_f32_e32 v43, 0xbfb8aa3b, v44
	v_exp_f32_e32 v44, v43
	v_rcp_f32_e32 v43, v0
	v_add_f32_e32 v0, 1.0, v48
	v_rcp_f32_e32 v48, v0
	v_add_f32_e32 v0, 1.0, v44
	v_mul_f32_e32 v44, 0xbfb8aa3b, v49
	v_exp_f32_e32 v49, v44
	v_mul_f32_e32 v44, 0xbfb8aa3b, v45
	v_exp_f32_e32 v45, v44
	v_rcp_f32_e32 v44, v0
	v_add_f32_e32 v0, 1.0, v49
	v_add_f32_e32 v42, 1.0, v42
	v_rcp_f32_e32 v49, v0
	v_add_f32_e32 v0, 1.0, v45
	v_rcp_f32_e32 v42, v42
	v_rcp_f32_e32 v45, v0
.LBB0_791:
	v_cvt_pk_bf16_f32 v46, v46, v47
	v_cvt_pk_bf16_f32 v47, v48, v49
	v_cvt_pk_bf16_f32 v48, v42, v43
	v_add_co_u32_e32 v42, vcc, 0x438000, v130
	v_cvt_pk_bf16_f32 v49, v44, v45
	s_nop 0
	v_addc_co_u32_e32 v43, vcc, 0, v131, vcc
	v_permlane16_swap_b32_e32 v46, v48
	v_permlane16_swap_b32_e32 v47, v49
	s_and_b64 vcc, exec, s[6:7]
	global_store_dwordx4 v[42:43], v[46:49], off sc1
	s_cbranch_vccnz .LBB0_793
	v_mul_f32_e32 v0, 0xbfb8aa3b, v38
	v_exp_f32_e32 v0, v0
	v_mul_f32_e32 v35, 0xbfb8aa3b, v35
	v_exp_f32_e32 v35, v35
	v_mul_f32_e32 v34, 0xbfb8aa3b, v34
	v_add_f32_e32 v0, 1.0, v0
	v_rcp_f32_e32 v38, v0
	v_mul_f32_e32 v0, 0xbfb8aa3b, v39
	v_exp_f32_e32 v0, v0
	v_exp_f32_e32 v34, v34
	v_add_f32_e32 v0, 1.0, v0
	v_rcp_f32_e32 v39, v0
	v_add_f32_e32 v0, 1.0, v35
	v_mul_f32_e32 v35, 0xbfb8aa3b, v40
	v_exp_f32_e32 v40, v35
	v_mul_f32_e32 v35, 0xbfb8aa3b, v36
	v_exp_f32_e32 v36, v35
	v_rcp_f32_e32 v35, v0
	v_add_f32_e32 v0, 1.0, v40
	v_rcp_f32_e32 v40, v0
	v_add_f32_e32 v0, 1.0, v36
	v_mul_f32_e32 v36, 0xbfb8aa3b, v41
	v_exp_f32_e32 v41, v36
	v_mul_f32_e32 v36, 0xbfb8aa3b, v37
	v_exp_f32_e32 v37, v36
	v_rcp_f32_e32 v36, v0
	v_add_f32_e32 v0, 1.0, v41
	v_add_f32_e32 v34, 1.0, v34
	v_rcp_f32_e32 v41, v0
	v_add_f32_e32 v0, 1.0, v37
	v_rcp_f32_e32 v34, v34
	v_rcp_f32_e32 v37, v0
.LBB0_793:
	v_cvt_pk_bf16_f32 v38, v38, v39
	v_cvt_pk_bf16_f32 v39, v40, v41
	v_cvt_pk_bf16_f32 v40, v34, v35
	v_add_co_u32_e32 v34, vcc, 0x4a4000, v130
	v_cvt_pk_bf16_f32 v41, v36, v37
	s_nop 0
	v_addc_co_u32_e32 v35, vcc, 0, v131, vcc
	v_permlane16_swap_b32_e32 v38, v40
	v_permlane16_swap_b32_e32 v39, v41
	s_and_b64 vcc, exec, s[6:7]
	global_store_dwordx4 v[34:35], v[38:41], off sc1
	s_cbranch_vccnz .LBB0_795
	v_mul_f32_e32 v0, 0xbfb8aa3b, v30
	v_exp_f32_e32 v0, v0
	v_mul_f32_e32 v27, 0xbfb8aa3b, v27
	v_exp_f32_e32 v27, v27
	v_mul_f32_e32 v26, 0xbfb8aa3b, v26
	v_add_f32_e32 v0, 1.0, v0
	v_rcp_f32_e32 v30, v0
	v_mul_f32_e32 v0, 0xbfb8aa3b, v31
	v_exp_f32_e32 v0, v0
	v_exp_f32_e32 v26, v26
	v_add_f32_e32 v0, 1.0, v0
	v_rcp_f32_e32 v31, v0
	v_add_f32_e32 v0, 1.0, v27
	v_mul_f32_e32 v27, 0xbfb8aa3b, v32
	v_exp_f32_e32 v32, v27
	v_mul_f32_e32 v27, 0xbfb8aa3b, v28
	v_exp_f32_e32 v28, v27
	v_rcp_f32_e32 v27, v0
	v_add_f32_e32 v0, 1.0, v32
	v_rcp_f32_e32 v32, v0
	v_add_f32_e32 v0, 1.0, v28
	v_mul_f32_e32 v28, 0xbfb8aa3b, v33
	v_exp_f32_e32 v33, v28
	v_mul_f32_e32 v28, 0xbfb8aa3b, v29
	v_exp_f32_e32 v29, v28
	v_rcp_f32_e32 v28, v0
	v_add_f32_e32 v0, 1.0, v33
	v_add_f32_e32 v26, 1.0, v26
	v_rcp_f32_e32 v33, v0
	v_add_f32_e32 v0, 1.0, v29
	v_rcp_f32_e32 v26, v26
	v_rcp_f32_e32 v29, v0
.LBB0_795:
	v_cvt_pk_bf16_f32 v30, v30, v31
	v_cvt_pk_bf16_f32 v31, v32, v33
	v_cvt_pk_bf16_f32 v32, v26, v27
	v_add_co_u32_e32 v26, vcc, 0x360000, v130
	v_cvt_pk_bf16_f32 v33, v28, v29
	s_nop 0
	v_addc_co_u32_e32 v27, vcc, 0, v131, vcc
	v_permlane16_swap_b32_e32 v30, v32
	v_permlane16_swap_b32_e32 v31, v33
	s_and_b64 vcc, exec, s[6:7]
	global_store_dwordx4 v[26:27], v[30:33], off offset:256 sc1
	s_cbranch_vccnz .LBB0_797
	v_mul_f32_e32 v0, 0xbfb8aa3b, v22
	v_exp_f32_e32 v0, v0
	v_mul_f32_e32 v19, 0xbfb8aa3b, v19
	v_exp_f32_e32 v19, v19
	v_mul_f32_e32 v18, 0xbfb8aa3b, v18
	v_add_f32_e32 v0, 1.0, v0
	v_rcp_f32_e32 v22, v0
	v_mul_f32_e32 v0, 0xbfb8aa3b, v23
	v_exp_f32_e32 v0, v0
	v_exp_f32_e32 v18, v18
	v_add_f32_e32 v0, 1.0, v0
	v_rcp_f32_e32 v23, v0
	v_add_f32_e32 v0, 1.0, v19
	v_mul_f32_e32 v19, 0xbfb8aa3b, v24
	v_exp_f32_e32 v24, v19
	v_mul_f32_e32 v19, 0xbfb8aa3b, v20
	v_exp_f32_e32 v20, v19
	v_rcp_f32_e32 v19, v0
	v_add_f32_e32 v0, 1.0, v24
	v_rcp_f32_e32 v24, v0
	v_add_f32_e32 v0, 1.0, v20
	v_mul_f32_e32 v20, 0xbfb8aa3b, v25
	v_exp_f32_e32 v25, v20
	v_mul_f32_e32 v20, 0xbfb8aa3b, v21
	v_exp_f32_e32 v21, v20
	v_rcp_f32_e32 v20, v0
	v_add_f32_e32 v0, 1.0, v25
	v_add_f32_e32 v18, 1.0, v18
	v_rcp_f32_e32 v25, v0
	v_add_f32_e32 v0, 1.0, v21
	v_rcp_f32_e32 v18, v18
	v_rcp_f32_e32 v21, v0
.LBB0_797:
	v_cvt_pk_bf16_f32 v22, v22, v23
	v_cvt_pk_bf16_f32 v23, v24, v25
	v_cvt_pk_bf16_f32 v24, v18, v19
	v_add_co_u32_e32 v18, vcc, 0x3cc000, v130
	v_cvt_pk_bf16_f32 v25, v20, v21
	s_nop 0
	v_addc_co_u32_e32 v19, vcc, 0, v131, vcc
	v_permlane16_swap_b32_e32 v22, v24
	v_permlane16_swap_b32_e32 v23, v25
	s_and_b64 vcc, exec, s[6:7]
	global_store_dwordx4 v[18:19], v[22:25], off offset:256 sc1
	s_cbranch_vccnz .LBB0_799
	v_mul_f32_e32 v0, 0xbfb8aa3b, v14
	v_exp_f32_e32 v0, v0
	v_mul_f32_e32 v11, 0xbfb8aa3b, v11
	v_exp_f32_e32 v11, v11
	v_mul_f32_e32 v10, 0xbfb8aa3b, v10
	v_add_f32_e32 v0, 1.0, v0
	v_rcp_f32_e32 v14, v0
	v_mul_f32_e32 v0, 0xbfb8aa3b, v15
	v_exp_f32_e32 v0, v0
	v_exp_f32_e32 v10, v10
	v_add_f32_e32 v0, 1.0, v0
	v_rcp_f32_e32 v15, v0
	v_add_f32_e32 v0, 1.0, v11
	v_mul_f32_e32 v11, 0xbfb8aa3b, v16
	v_exp_f32_e32 v16, v11
	v_mul_f32_e32 v11, 0xbfb8aa3b, v12
	v_exp_f32_e32 v12, v11
	v_rcp_f32_e32 v11, v0
	v_add_f32_e32 v0, 1.0, v16
	v_rcp_f32_e32 v16, v0
	v_add_f32_e32 v0, 1.0, v12
	v_mul_f32_e32 v12, 0xbfb8aa3b, v17
	v_exp_f32_e32 v17, v12
	v_mul_f32_e32 v12, 0xbfb8aa3b, v13
	v_exp_f32_e32 v13, v12
	v_rcp_f32_e32 v12, v0
	v_add_f32_e32 v0, 1.0, v17
	v_add_f32_e32 v10, 1.0, v10
	v_rcp_f32_e32 v17, v0
	v_add_f32_e32 v0, 1.0, v13
	v_rcp_f32_e32 v10, v10
	v_rcp_f32_e32 v13, v0
.LBB0_799:
	v_cvt_pk_bf16_f32 v14, v14, v15
	v_cvt_pk_bf16_f32 v15, v16, v17
	v_cvt_pk_bf16_f32 v16, v10, v11
	v_add_co_u32_e32 v10, vcc, 0x438000, v130
	v_cvt_pk_bf16_f32 v17, v12, v13
	s_nop 0
	v_addc_co_u32_e32 v11, vcc, 0, v131, vcc
	v_permlane16_swap_b32_e32 v14, v16
	v_permlane16_swap_b32_e32 v15, v17
	s_and_b64 vcc, exec, s[6:7]
	global_store_dwordx4 v[10:11], v[14:17], off offset:256 sc1
	s_cbranch_vccnz .LBB0_246
	v_mul_f32_e32 v0, 0xbfb8aa3b, v6
	v_exp_f32_e32 v0, v0
	v_mul_f32_e32 v3, 0xbfb8aa3b, v3
	v_exp_f32_e32 v3, v3
	v_mul_f32_e32 v2, 0xbfb8aa3b, v2
	v_add_f32_e32 v0, 1.0, v0
	v_rcp_f32_e32 v6, v0
	v_mul_f32_e32 v0, 0xbfb8aa3b, v7
	v_exp_f32_e32 v0, v0
	v_exp_f32_e32 v2, v2
	v_add_f32_e32 v0, 1.0, v0
	v_rcp_f32_e32 v7, v0
	v_add_f32_e32 v0, 1.0, v3
	v_mul_f32_e32 v3, 0xbfb8aa3b, v8
	v_exp_f32_e32 v8, v3
	v_mul_f32_e32 v3, 0xbfb8aa3b, v4
	v_exp_f32_e32 v4, v3
	v_rcp_f32_e32 v3, v0
	v_add_f32_e32 v0, 1.0, v8
	v_rcp_f32_e32 v8, v0
	v_add_f32_e32 v0, 1.0, v4
	v_mul_f32_e32 v4, 0xbfb8aa3b, v9
	v_exp_f32_e32 v9, v4
	v_mul_f32_e32 v4, 0xbfb8aa3b, v5
	v_exp_f32_e32 v5, v4
	v_rcp_f32_e32 v4, v0
	v_add_f32_e32 v0, 1.0, v9
	v_add_f32_e32 v2, 1.0, v2
	v_rcp_f32_e32 v9, v0
	v_add_f32_e32 v0, 1.0, v5
	v_rcp_f32_e32 v2, v2
	v_rcp_f32_e32 v5, v0
	s_branch .LBB0_246

.LBB0_819:
	s_or_b64 exec, exec, s[30:31]
	v_lshlrev_b64 v[4:5], 13, v[4:5]
	v_lshl_add_u64 v[44:45], v[2:3], 0, v[4:5]
	v_lshl_add_u64 v[2:3], v[44:45], 0, v[0:1]
	v_mov_b32_e32 v15, v1
	global_load_dwordx4 v[6:9], v[2:3], off offset:16
	global_load_dwordx4 v[28:31], v[2:3], off
	global_load_dwordx4 v[32:35], v[2:3], off offset:2064
	global_load_dwordx4 v[36:39], v[2:3], off offset:2048
	v_lshl_add_u64 v[2:3], v[44:45], 0, v[14:15]
	global_load_dwordx4 v[40:43], v[2:3], off
	s_nop 0
	global_load_dwordx4 v[2:5], v[2:3], off offset:16
	v_mov_b32_e32 v17, v1
	v_lshl_add_u64 v[48:49], v[44:45], 0, v[16:17]
	global_load_dwordx4 v[44:47], v[48:49], off
	s_nop 0
	global_load_dwordx4 v[48:51], v[48:49], off offset:16
	v_cmp_gt_i32_e64 s[4:5], s1, v10
	v_lshlrev_b64 v[18:19], 12, v[18:19]
	v_lshl_add_u64 v[18:19], v[12:13], 0, v[18:19]
	s_movk_i32 s2, 0x1fff
	s_waitcnt vmcnt(7)
	v_pk_mul_f32 v[54:55], v[6:7], v[6:7]
	s_waitcnt vmcnt(6)
	v_pk_mul_f32 v[58:59], v[28:29], v[28:29]
	v_pk_mul_f32 v[52:53], v[8:9], v[8:9]
	v_pk_mul_f32 v[56:57], v[30:31], v[30:31]
	s_waitcnt vmcnt(4)
	v_pk_mul_f32 v[66:67], v[36:37], v[36:37]
	v_add_f32_e32 v15, v54, v55
	v_add_f32_e32 v17, v58, v59
	v_pk_mul_f32 v[62:63], v[32:33], v[32:33]
	v_pk_mul_f32 v[64:65], v[38:39], v[38:39]
	s_waitcnt vmcnt(3)
	v_mov_b32_e32 v74, v41
	s_waitcnt vmcnt(2)
	v_mov_b32_e32 v75, v3
	v_add_f32_e32 v27, v66, v67
	v_add_f32_e32 v15, v15, v52
	v_add_f32_e32 v17, v17, v56
	v_pk_mul_f32 v[60:61], v[34:35], v[34:35]
	v_mov_b32_e32 v72, v40
	v_mov_b32_e32 v73, v2
	v_pk_mul_f32 v[74:75], v[74:75], v[74:75]
	v_add_f32_e32 v62, v62, v63
	v_add_f32_e32 v27, v27, v64
	v_add_f32_e32 v15, v15, v53
	v_add_f32_e32 v17, v17, v57
	v_mov_b32_e32 v68, v42
	v_mov_b32_e32 v69, v4
	s_waitcnt vmcnt(1)
	v_mov_b32_e32 v82, v45
	s_waitcnt vmcnt(0)
	v_mov_b32_e32 v83, v49
	v_pk_fma_f32 v[54:55], v[72:73], v[72:73], v[74:75]
	v_add_f32_e32 v52, v62, v60
	v_add_f32_e32 v27, v27, v65
	v_add_f32_e32 v15, v17, v15
	v_mov_b32_e32 v70, v43
	v_mov_b32_e32 v71, v5
	v_mov_b32_e32 v80, v44
	v_mov_b32_e32 v81, v48
	v_pk_mul_f32 v[82:83], v[82:83], v[82:83]
	v_pk_fma_f32 v[54:55], v[68:69], v[68:69], v[54:55]
	v_add_f32_e32 v56, v52, v61
	v_add_f32_e32 v15, v15, v27
	v_mov_b32_e32 v76, v46
	v_mov_b32_e32 v77, v50
	v_pk_fma_f32 v[58:59], v[80:81], v[80:81], v[82:83]
	v_pk_fma_f32 v[52:53], v[70:71], v[70:71], v[54:55]
	v_add_f32_e32 v15, v15, v56
	v_mov_b32_e32 v78, v47
	v_mov_b32_e32 v79, v51
	v_pk_fma_f32 v[58:59], v[76:77], v[76:77], v[58:59]
	v_add_f32_e32 v15, v15, v52
	v_pk_fma_f32 v[54:55], v[78:79], v[78:79], v[58:59]
	v_add_f32_e32 v15, v15, v53
	v_add_f32_e32 v15, v15, v54
	v_add_f32_e32 v15, v15, v55
	ds_bpermute_b32 v17, v20, v15
	v_cndmask_b32_e64 v27, v220, v221, s[4:5]
	v_cmp_lt_i32_e64 s[4:5], s14, v10
	v_lshl_add_u64 v[10:11], v[10:11], 0, s[10:11]
	s_waitcnt lgkmcnt(0)
	v_add_f32_e32 v15, v15, v17
	ds_bpermute_b32 v17, v21, v15
	v_cndmask_b32_e64 v27, 0, v27, s[4:5]
	v_lshl_add_u32 v27, v27, 2, v26
	ds_read_b128 v[52:55], v27
	ds_read_b128 v[56:59], v27 offset:16
	ds_read_b128 v[60:63], v27 offset:24592
	ds_read_b128 v[64:67], v27 offset:24576
	ds_read_b128 v[68:71], v27 offset:2064
	ds_read_b128 v[72:75], v27 offset:2048
	ds_read_b128 v[76:79], v27 offset:26640
	ds_read_b128 v[80:83], v27 offset:26624
	s_waitcnt lgkmcnt(8)
	v_add_f32_e32 v15, v15, v17
	ds_bpermute_b32 v17, v22, v15
	ds_read_b128 v[84:87], v27 offset:4112
	ds_read_b128 v[88:91], v27 offset:4096
	ds_read_b128 v[92:95], v27 offset:28688
	ds_read_b128 v[96:99], v27 offset:28672
	ds_read_b128 v[100:103], v27 offset:6160
	ds_read_b128 v[104:107], v27 offset:6144
	ds_read_b128 v[108:111], v27 offset:30736
	ds_read_b128 v[112:115], v27 offset:30720
	s_waitcnt lgkmcnt(8)
	v_add_f32_e32 v15, v15, v17
	ds_bpermute_b32 v17, v23, v15
	s_waitcnt lgkmcnt(0)
	v_add_f32_e32 v15, v15, v17
	ds_bpermute_b32 v17, v24, v15
	s_waitcnt lgkmcnt(0)
	v_add_f32_e32 v15, v15, v17
	ds_bpermute_b32 v17, v25, v15
	s_waitcnt lgkmcnt(0)
	v_add_f32_e32 v15, v15, v17
	v_fmamk_f32 v15, v15, 0x3a000000, v191
	v_mul_f32_e32 v17, 0x4b800000, v15
	v_cmp_gt_f32_e64 s[4:5], s0, v15
	s_nop 1
	v_cndmask_b32_e64 v15, v15, v17, s[4:5]
	v_rsq_f32_e32 v15, v15
	s_nop 0
	v_mul_f32_e32 v17, 0x45800000, v15
	v_cndmask_b32_e64 v116, v15, v17, s[4:5]
	v_pk_mul_f32 v[30:31], v[30:31], v[116:117] op_sel_hi:[1,0]
	v_pk_mul_f32 v[34:35], v[34:35], v[116:117] op_sel_hi:[1,0]
	v_pk_mul_f32 v[2:3], v[2:3], v[116:117] op_sel_hi:[1,0]
	v_pk_mul_f32 v[28:29], v[28:29], v[116:117] op_sel_hi:[1,0]
	v_pk_mul_f32 v[6:7], v[6:7], v[116:117] op_sel_hi:[1,0]
	v_pk_fma_f32 v[30:31], v[54:55], v[30:31], v[66:67]
	v_pk_fma_f32 v[34:35], v[34:35], v[70:71], v[78:79]
	v_pk_fma_f32 v[2:3], v[2:3], v[84:85], v[92:93]
	v_pk_fma_f32 v[28:29], v[52:53], v[28:29], v[64:65]
	v_pk_fma_f32 v[52:53], v[56:57], v[6:7], v[60:61]
	v_cvt_pk_bf16_f32 v7, v30, v31
	v_cvt_pk_bf16_f32 v31, v34, v35
	v_cvt_pk_bf16_f32 v34, v2, v3
	v_pk_mul_f32 v[2:3], v[4:5], v[116:117] op_sel_hi:[1,0]
	v_pk_mul_f32 v[8:9], v[8:9], v[116:117] op_sel_hi:[1,0]
	v_pk_fma_f32 v[2:3], v[2:3], v[86:87], v[94:95]
	v_pk_mul_f32 v[36:37], v[36:37], v[116:117] op_sel_hi:[1,0]
	v_pk_mul_f32 v[38:39], v[38:39], v[116:117] op_sel_hi:[1,0]
	v_pk_mul_f32 v[32:33], v[32:33], v[116:117] op_sel_hi:[1,0]
	v_pk_fma_f32 v[54:55], v[58:59], v[8:9], v[62:63]
	v_cvt_pk_bf16_f32 v35, v2, v3
	v_pk_mul_f32 v[2:3], v[44:45], v[116:117] op_sel_hi:[1,0]
	v_pk_mul_f32 v[4:5], v[46:47], v[116:117] op_sel_hi:[1,0]
	v_pk_fma_f32 v[36:37], v[36:37], v[72:73], v[80:81]
	v_pk_fma_f32 v[38:39], v[38:39], v[74:75], v[82:83]
	v_pk_fma_f32 v[32:33], v[32:33], v[68:69], v[76:77]
	v_cvt_pk_bf16_f32 v6, v28, v29
	v_cvt_pk_bf16_f32 v8, v52, v53
	v_cvt_pk_bf16_f32 v9, v54, v55
	v_pk_fma_f32 v[2:3], v[2:3], v[104:105], v[112:113]
	v_pk_fma_f32 v[4:5], v[4:5], v[106:107], v[114:115]
	v_pk_mul_f32 v[40:41], v[40:41], v[116:117] op_sel_hi:[1,0]
	v_pk_mul_f32 v[42:43], v[42:43], v[116:117] op_sel_hi:[1,0]
	v_cvt_pk_bf16_f32 v28, v36, v37
	v_cvt_pk_bf16_f32 v29, v38, v39
	v_cvt_pk_bf16_f32 v30, v32, v33
	global_store_dwordx4 v[18:19], v[6:9], off sc1
	global_store_dwordx4 v[18:19], v[28:31], off offset:1024 sc1
	v_cvt_pk_bf16_f32 v2, v2, v3
	v_cvt_pk_bf16_f32 v3, v4, v5
	v_pk_mul_f32 v[4:5], v[48:49], v[116:117] op_sel_hi:[1,0]
	v_pk_mul_f32 v[6:7], v[50:51], v[116:117] op_sel_hi:[1,0]
	v_pk_fma_f32 v[40:41], v[40:41], v[88:89], v[96:97]
	v_pk_fma_f32 v[42:43], v[42:43], v[90:91], v[98:99]
	v_pk_fma_f32 v[4:5], v[4:5], v[100:101], v[108:109]
	v_pk_fma_f32 v[6:7], v[6:7], v[102:103], v[110:111]
	v_cmp_lt_i32_e64 s[4:5], s2, v10
	v_cvt_pk_bf16_f32 v32, v40, v41
	v_cvt_pk_bf16_f32 v33, v42, v43
	v_cvt_pk_bf16_f32 v4, v4, v5
	v_cvt_pk_bf16_f32 v5, v6, v7
	s_or_b64 s[28:29], s[4:5], s[28:29]
	global_store_dwordx4 v[18:19], v[32:35], off offset:2048 sc1
	global_store_dwordx4 v[18:19], v[2:5], off offset:3072 sc1
	s_andn2_b64 exec, exec, s[28:29]
	s_cbranch_execz .LBB0_825

.LBB0_881:
	v_lshl_add_u64 v[72:73], v[36:37], 0, v[34:35]
	v_lshl_add_u64 v[74:75], v[72:73], 0, s[8:9]
	v_add_co_u32_e64 v84, s[0:1], s11, v72
	v_lshl_add_u64 v[76:77], v[72:73], 0, s[12:13]
	v_lshl_add_u64 v[78:79], v[72:73], 0, s[14:15]
	v_lshl_add_u64 v[80:81], v[72:73], 0, s[16:17]
	v_add_co_u32_e32 v82, vcc, 0x25c00000, v72
	v_addc_co_u32_e64 v85, s[0:1], 0, v73, s[0:1]
	global_load_dwordx4 v[48:51], v[74:75], off offset:16
	global_load_dwordx4 v[52:55], v[76:77], off offset:16
	global_load_dwordx4 v[56:59], v[84:85], off
	global_load_dwordx4 v[60:63], v[78:79], off offset:16
	global_load_dwordx4 v[64:67], v[84:85], off offset:2048
	global_load_dwordx4 v[68:71], v[80:81], off offset:16
	v_addc_co_u32_e32 v83, vcc, 0, v73, vcc
	global_load_dwordx4 v[72:75], v[82:83], off
	global_load_dwordx4 v[76:79], v[82:83], off offset:2048
	v_lshl_add_u64 v[40:41], v[38:39], 0, v[34:35]
	v_add_co_u32_e64 v86, s[0:1], s19, v40
	v_add_u32_e32 v32, s10, v32
	s_nop 0
	v_addc_co_u32_e64 v87, s[0:1], 0, v41, s[0:1]
	v_cmp_lt_i32_e64 s[0:1], s20, v32
	v_lshl_add_u64 v[36:37], v[36:37], 0, s[4:5]
	v_lshl_add_u64 v[38:39], v[38:39], 0, s[4:5]
	s_or_b64 s[6:7], s[0:1], s[6:7]
	s_waitcnt vmcnt(7)
	v_pk_mul_f32 v[80:81], v[48:49], v[48:49]
	s_waitcnt vmcnt(6)
	v_pk_mul_f32 v[84:85], v[52:53], v[52:53]
	s_waitcnt vmcnt(5)
	v_mov_b32_e32 v92, v57
	s_waitcnt vmcnt(4)
	v_mov_b32_e32 v93, v61
	s_waitcnt vmcnt(3)
	v_mov_b32_e32 v100, v65
	s_waitcnt vmcnt(2)
	v_mov_b32_e32 v101, v69
	v_mov_b32_e32 v90, v56
	v_mov_b32_e32 v91, v60
	v_mov_b32_e32 v98, v64
	v_mov_b32_e32 v99, v68
	s_waitcnt vmcnt(1)
	v_pk_mul_f32 v[106:107], v[72:73], v[72:73]
	v_pk_mul_f32 v[92:93], v[92:93], v[92:93]
	v_pk_mul_f32 v[100:101], v[100:101], v[100:101]
	v_pk_mul_f32 v[82:83], v[50:51], v[50:51]
	v_mov_b32_e32 v102, v66
	v_mov_b32_e32 v103, v70
	v_pk_mul_f32 v[108:109], v[74:75], v[74:75]
	s_waitcnt vmcnt(0)
	v_pk_mul_f32 v[110:111], v[76:77], v[76:77]
	v_add_f32_e32 v114, v80, v81
	v_add_f32_e32 v115, v84, v85
	v_pk_fma_f32 v[80:81], v[90:91], v[90:91], v[92:93]
	v_pk_fma_f32 v[84:85], v[98:99], v[98:99], v[100:101]
	v_add_f32_e32 v91, v106, v107
	v_mov_b32_e32 v104, v67
	v_mov_b32_e32 v105, v71
	v_pk_mul_f32 v[112:113], v[78:79], v[78:79]
	v_add_f32_e32 v90, v110, v111
	v_add_f32_e32 v82, v114, v82
	v_pk_fma_f32 v[84:85], v[102:103], v[102:103], v[84:85]
	v_add_f32_e32 v91, v91, v108
	v_pk_mul_f32 v[88:89], v[54:55], v[54:55]
	v_add_f32_e32 v90, v90, v112
	v_add_f32_e32 v92, v82, v83
	v_pk_fma_f32 v[82:83], v[104:105], v[104:105], v[84:85]
	v_add_f32_e32 v85, v91, v109
	v_mov_b32_e32 v94, v58
	v_mov_b32_e32 v95, v62
	v_add_f32_e32 v88, v115, v88
	v_add_f32_e32 v84, v90, v113
	v_add_f32_e32 v85, v85, v92
	v_mov_b32_e32 v96, v59
	v_mov_b32_e32 v97, v63
	v_pk_fma_f32 v[80:81], v[94:95], v[94:95], v[80:81]
	v_add_f32_e32 v88, v88, v89
	v_add_f32_e32 v84, v85, v84
	v_pk_fma_f32 v[80:81], v[96:97], v[96:97], v[80:81]
	v_add_f32_e32 v84, v84, v88
	v_add_f32_e32 v80, v84, v80
	v_add_f32_e32 v80, v80, v81
	v_add_f32_e32 v80, v80, v82
	v_add_f32_e32 v80, v80, v83
	ds_bpermute_b32 v81, v42, v80
	s_waitcnt lgkmcnt(0)
	v_add_f32_e32 v80, v80, v81
	ds_bpermute_b32 v81, v43, v80
	s_waitcnt lgkmcnt(0)
	v_add_f32_e32 v80, v80, v81
	ds_bpermute_b32 v81, v44, v80
	s_waitcnt lgkmcnt(0)
	v_add_f32_e32 v80, v80, v81
	ds_bpermute_b32 v81, v45, v80
	s_waitcnt lgkmcnt(0)
	v_add_f32_e32 v80, v80, v81
	ds_bpermute_b32 v81, v46, v80
	s_waitcnt lgkmcnt(0)
	v_add_f32_e32 v80, v80, v81
	ds_bpermute_b32 v81, v47, v80
	s_waitcnt lgkmcnt(0)
	v_add_f32_e32 v80, v80, v81
	v_fmamk_f32 v80, v80, 0x3a000000, v33
	v_mul_f32_e32 v81, 0x4b800000, v80
	v_cmp_gt_f32_e32 vcc, s18, v80
	s_nop 1
	v_cndmask_b32_e32 v80, v80, v81, vcc
	v_rsq_f32_e32 v80, v80
	s_nop 0
	v_mul_f32_e32 v81, 0x45800000, v80
	v_cndmask_b32_e32 v80, v80, v81, vcc
	v_pk_mul_f32 v[72:73], v[72:73], v[80:81] op_sel_hi:[1,0]
	v_pk_mul_f32 v[74:75], v[74:75], v[80:81] op_sel_hi:[1,0]
	v_pk_mul_f32 v[82:83], v[48:49], v[80:81] op_sel_hi:[1,0]
	v_pk_mul_f32 v[84:85], v[50:51], v[80:81] op_sel_hi:[1,0]
	v_pk_mul_f32 v[76:77], v[76:77], v[80:81] op_sel_hi:[1,0]
	v_pk_mul_f32 v[78:79], v[78:79], v[80:81] op_sel_hi:[1,0]
	v_pk_mul_f32 v[88:89], v[52:53], v[80:81] op_sel_hi:[1,0]
	v_pk_mul_f32 v[90:91], v[54:55], v[80:81] op_sel_hi:[1,0]
	v_pk_mul_f32 v[92:93], v[56:57], v[80:81] op_sel_hi:[1,0]
	v_pk_mul_f32 v[94:95], v[58:59], v[80:81] op_sel_hi:[1,0]
	v_pk_mul_f32 v[96:97], v[60:61], v[80:81] op_sel_hi:[1,0]
	v_pk_mul_f32 v[98:99], v[62:63], v[80:81] op_sel_hi:[1,0]
	v_pk_mul_f32 v[100:101], v[64:65], v[80:81] op_sel_hi:[1,0]
	v_pk_mul_f32 v[102:103], v[66:67], v[80:81] op_sel_hi:[1,0]
	v_pk_mul_f32 v[104:105], v[68:69], v[80:81] op_sel_hi:[1,0]
	v_pk_mul_f32 v[80:81], v[70:71], v[80:81] op_sel_hi:[1,0]
	v_pk_mul_f32 v[48:49], v[0:1], v[72:73]
	v_pk_mul_f32 v[50:51], v[2:3], v[74:75]
	v_pk_mul_f32 v[52:53], v[4:5], v[82:83]
	v_pk_mul_f32 v[54:55], v[84:85], v[6:7]
	v_pk_mul_f32 v[56:57], v[76:77], v[8:9]
	v_pk_mul_f32 v[58:59], v[78:79], v[10:11]
	v_pk_mul_f32 v[60:61], v[88:89], v[12:13]
	v_pk_mul_f32 v[62:63], v[90:91], v[14:15]
	v_pk_mul_f32 v[64:65], v[92:93], v[16:17]
	v_pk_mul_f32 v[66:67], v[94:95], v[18:19]
	v_pk_mul_f32 v[68:69], v[96:97], v[20:21]
	v_pk_mul_f32 v[70:71], v[98:99], v[22:23]
	v_pk_mul_f32 v[72:73], v[100:101], v[24:25]
	v_pk_mul_f32 v[74:75], v[102:103], v[26:27]
	v_pk_mul_f32 v[76:77], v[104:105], v[28:29]
	v_pk_mul_f32 v[78:79], v[80:81], v[30:31]
	global_store_dwordx4 v[40:41], v[48:51], off sc1
	global_store_dwordx4 v[40:41], v[52:55], off offset:16 sc1
	global_store_dwordx4 v[40:41], v[56:59], off offset:2048 sc1
	global_store_dwordx4 v[40:41], v[60:63], off offset:2064 sc1
	global_store_dwordx4 v[86:87], v[64:67], off sc1
	global_store_dwordx4 v[86:87], v[68:71], off offset:16 sc1
	global_store_dwordx4 v[86:87], v[72:75], off offset:2048 sc1
	global_store_dwordx4 v[86:87], v[76:79], off offset:2064 sc1
	s_andn2_b64 exec, exec, s[6:7]
	s_cbranch_execnz .LBB0_881
